# GEMM phases: m0 set-up placed before the address add so the s_nop in front of the second LDS-DMA load of a phase is dropped (40 sites)
# baseline (speedup 1.0000x reference)
; #define G_LDA(dst, b, h)                                                                                                  \
;   _Pragma("unroll") for (int m = 0; m < 4; ++m) _Pragma("unroll") for (int k = 0; k < 2; ++k)                             \
;       dst[m][k] = *(const bf16x8*)((const char*)G_SA(b, h) + ((wr * 4 + m) * 2 + k) * 1024 + rdo)
; #define G_LDB(dst, b, h)                                                                                                  \
;   _Pragma("unroll") for (int n = 0; n < 2; ++n) _Pragma("unroll") for (int k = 0; k < 2; ++k)                             \
;       dst[n][k] = *(const bf16x8*)((const char*)G_SB(b, h) + ((wc * 2 + n) * 2 + k) * 1024 + rdo)
; #define G_WAIT_V(n) asm volatile("s_waitcnt vmcnt(" #n ")" ::: "memory")
; #define G_WAIT_L(n) asm volatile("s_waitcnt lgkmcnt(" #n ")" ::: "memory")
; #define G_BAR __builtin_amdgcn_s_barrier()
; #define G_SCHED __builtin_amdgcn_sched_barrier(0)
;     ...
;   for (int tt = 0; tt < nt - 2; tt += 2) {
;     G_LDB(B0, 0, 0); G_SCHED; G_LDA(At, 0, 0); G_STAGE(G_SA(1, 1), A, oa0, oa1, LDA, 128, KA(tt + 1));
;     G_WAIT_L(8); G_BAR; G_WAIT_L(0); G_MMA(0, 0, At, B0); G_BAR; G_SCHED;
;     G_LDB(B1, 0, 1); G_STAGE(G_SB(0, 0), B, ob0, ob1, LDB, 0, KB(tt + 2));
;     G_BAR; G_WAIT_L(0); G_MMA(0, 1, At, B1); G_BAR;
;     G_LDA(At, 0, 1); G_STAGE(G_SA(0, 0), A, oa0, oa1, LDA, 0, KA(tt + 2));
;     G_BAR; G_WAIT_L(0); G_MMA(1, 0, At, B0); G_BAR; G_SCHED;
;     G_STAGE(G_SB(0, 1), B, ob0, ob1, LDB, 128, KB(tt + 2));
;     G_WAIT_V(6); G_BAR; G_MMA(1, 1, At, B1); G_BAR;
;     G_LDB(B0, 1, 0); G_SCHED; G_LDA(At, 1, 0); G_STAGE(G_SA(0, 1), A, oa0, oa1, LDA, 128, KA(tt + 2));
.LBB0_40:
	ds_read_b128 v[164:167], v162
	ds_read_b128 v[182:185], v162 offset:1024
	ds_read_b128 v[186:189], v162 offset:2048
	ds_read_b128 v[190:193], v162 offset:3072
	v_lshl_add_u64 v[242:243], v[136:137], 0, s[20:21]
	v_readfirstlane_b32 s0, v161
	v_lshl_add_u64 v[226:227], v[242:243], 0, s[78:79]
	s_mov_b32 m0, s0
	v_lshl_add_u64 v[244:245], v[134:135], 0, s[20:21]
	v_readfirstlane_b32 s0, v160
	ds_read_b128 v[194:197], v142
	ds_read_b128 v[198:201], v142 offset:1024
	ds_read_b128 v[202:205], v142 offset:2048
	ds_read_b128 v[206:209], v142 offset:3072
	ds_read_b128 v[210:213], v142 offset:4096
	ds_read_b128 v[214:217], v142 offset:5120
	ds_read_b128 v[218:221], v142 offset:6144
	ds_read_b128 v[222:225], v142 offset:7168
	global_load_lds_dwordx4 v[226:227], off
	s_mov_b32 m0, s0
	v_lshl_add_u64 v[226:227], v[244:245], 0, s[78:79]
	global_load_lds_dwordx4 v[226:227], off
	s_waitcnt lgkmcnt(8)
	s_barrier
	s_waitcnt lgkmcnt(0)
	v_mfma_f32_16x16x32_bf16 v[126:129], v[194:197], v[164:167], v[126:129]
	v_mfma_f32_16x16x32_bf16 v[122:125], v[194:197], v[186:189], v[122:125]
	v_mfma_f32_16x16x32_bf16 v[118:121], v[202:205], v[164:167], v[118:121]
	v_mfma_f32_16x16x32_bf16 v[114:117], v[202:205], v[186:189], v[114:117]
	v_mfma_f32_16x16x32_bf16 v[110:113], v[210:213], v[164:167], v[110:113]
	v_mfma_f32_16x16x32_bf16 v[106:109], v[210:213], v[186:189], v[106:109]
	v_mfma_f32_16x16x32_bf16 v[102:105], v[218:221], v[164:167], v[102:105]
	v_mfma_f32_16x16x32_bf16 v[98:101], v[218:221], v[186:189], v[98:101]
	v_mfma_f32_16x16x32_bf16 v[126:129], v[198:201], v[182:185], v[126:129]
	v_mfma_f32_16x16x32_bf16 v[122:125], v[198:201], v[190:193], v[122:125]
	v_mfma_f32_16x16x32_bf16 v[118:121], v[206:209], v[182:185], v[118:121]
	v_mfma_f32_16x16x32_bf16 v[114:117], v[206:209], v[190:193], v[114:117]
	v_mfma_f32_16x16x32_bf16 v[110:113], v[214:217], v[182:185], v[110:113]
	v_mfma_f32_16x16x32_bf16 v[106:109], v[214:217], v[190:193], v[106:109]
	v_mfma_f32_16x16x32_bf16 v[102:105], v[222:225], v[182:185], v[102:105]
	v_mfma_f32_16x16x32_bf16 v[98:101], v[222:225], v[190:193], v[98:101]
	s_barrier
	v_lshl_add_u64 v[246:247], v[140:141], 0, s[20:21]
	v_readfirstlane_b32 s0, v146
	v_lshl_add_u64 v[248:249], v[246:247], 0, s[42:43]
	s_mov_b32 m0, s0
	ds_read_b128 v[226:229], v159
	ds_read_b128 v[230:233], v159 offset:1024
	ds_read_b128 v[234:237], v159 offset:2048
	ds_read_b128 v[238:241], v159 offset:3072
	global_load_lds_dwordx4 v[248:249], off
	v_lshl_add_u64 v[248:249], v[138:139], 0, s[20:21]
	v_readfirstlane_b32 s0, v147
	s_mov_b32 m0, s0
	v_lshl_add_u64 v[250:251], v[248:249], 0, s[42:43]
	global_load_lds_dwordx4 v[250:251], off
	s_barrier
	s_waitcnt lgkmcnt(0)
	v_mfma_f32_16x16x32_bf16 v[94:97], v[194:197], v[226:229], v[94:97]
	v_mfma_f32_16x16x32_bf16 v[78:81], v[194:197], v[234:237], v[78:81]
	v_mfma_f32_16x16x32_bf16 v[62:65], v[202:205], v[226:229], v[62:65]
	v_mfma_f32_16x16x32_bf16 v[54:57], v[202:205], v[234:237], v[54:57]
	v_mfma_f32_16x16x32_bf16 v[50:53], v[210:213], v[226:229], v[50:53]
	v_mfma_f32_16x16x32_bf16 v[46:49], v[210:213], v[234:237], v[46:49]
	v_mfma_f32_16x16x32_bf16 v[42:45], v[218:221], v[226:229], v[42:45]
	v_mfma_f32_16x16x32_bf16 v[38:41], v[218:221], v[234:237], v[38:41]
	v_mfma_f32_16x16x32_bf16 v[94:97], v[198:201], v[230:233], v[94:97]
	v_mfma_f32_16x16x32_bf16 v[78:81], v[198:201], v[238:241], v[78:81]
	v_mfma_f32_16x16x32_bf16 v[62:65], v[206:209], v[230:233], v[62:65]
	v_mfma_f32_16x16x32_bf16 v[54:57], v[206:209], v[238:241], v[54:57]
	v_mfma_f32_16x16x32_bf16 v[50:53], v[214:217], v[230:233], v[50:53]
	v_mfma_f32_16x16x32_bf16 v[46:49], v[214:217], v[238:241], v[46:49]
	v_mfma_f32_16x16x32_bf16 v[42:45], v[222:225], v[230:233], v[42:45]
	v_mfma_f32_16x16x32_bf16 v[38:41], v[222:225], v[238:241], v[38:41]
	v_readfirstlane_b32 s0, v143
	v_lshl_add_u64 v[250:251], v[242:243], 0, s[82:83]
	s_mov_b32 m0, s0
	v_readfirstlane_b32 s0, v144
	s_barrier
	ds_read_b128 v[194:197], v142 offset:16384
	ds_read_b128 v[198:201], v142 offset:17408
	ds_read_b128 v[202:205], v142 offset:18432
	ds_read_b128 v[206:209], v142 offset:19456
	ds_read_b128 v[210:213], v142 offset:20480
	ds_read_b128 v[214:217], v142 offset:21504
	ds_read_b128 v[218:221], v142 offset:22528
	ds_read_b128 v[222:225], v142 offset:23552
	global_load_lds_dwordx4 v[250:251], off
	s_mov_b32 m0, s0
	v_lshl_add_u64 v[250:251], v[244:245], 0, s[82:83]
	global_load_lds_dwordx4 v[250:251], off
	s_barrier
	s_waitcnt lgkmcnt(0)
	v_mfma_f32_16x16x32_bf16 v[34:37], v[194:197], v[164:167], v[34:37]
	v_mfma_f32_16x16x32_bf16 v[30:33], v[194:197], v[186:189], v[30:33]
	v_mfma_f32_16x16x32_bf16 v[26:29], v[202:205], v[164:167], v[26:29]
	v_mfma_f32_16x16x32_bf16 v[22:25], v[202:205], v[186:189], v[22:25]
	v_mfma_f32_16x16x32_bf16 v[18:21], v[210:213], v[164:167], v[18:21]
	v_mfma_f32_16x16x32_bf16 v[14:17], v[210:213], v[186:189], v[14:17]
	v_mfma_f32_16x16x32_bf16 v[10:13], v[218:221], v[164:167], v[10:13]
	v_mfma_f32_16x16x32_bf16 v[6:9], v[218:221], v[186:189], v[6:9]
	v_mfma_f32_16x16x32_bf16 v[34:37], v[198:201], v[182:185], v[34:37]
	v_mfma_f32_16x16x32_bf16 v[30:33], v[198:201], v[190:193], v[30:33]
	v_mfma_f32_16x16x32_bf16 v[26:29], v[206:209], v[182:185], v[26:29]
	v_mfma_f32_16x16x32_bf16 v[22:25], v[206:209], v[190:193], v[22:25]
	v_mfma_f32_16x16x32_bf16 v[18:21], v[214:217], v[182:185], v[18:21]
	v_mfma_f32_16x16x32_bf16 v[14:17], v[214:217], v[190:193], v[14:17]
	v_mfma_f32_16x16x32_bf16 v[10:13], v[222:225], v[182:185], v[10:13]
	v_mfma_f32_16x16x32_bf16 v[6:9], v[222:225], v[190:193], v[6:9]
	s_barrier
; #define G_LDA(dst, b, h)                                                                                                  \
;   _Pragma("unroll") for (int m = 0; m < 4; ++m) _Pragma("unroll") for (int k = 0; k < 2; ++k)                             \
;       dst[m][k] = *(const bf16x8*)((const char*)G_SA(b, h) + ((wr * 4 + m) * 2 + k) * 1024 + rdo)
; #define G_LDB(dst, b, h)                                                                                                  \
;   _Pragma("unroll") for (int n = 0; n < 2; ++n) _Pragma("unroll") for (int k = 0; k < 2; ++k)                             \
;       dst[n][k] = *(const bf16x8*)((const char*)G_SB(b, h) + ((wc * 2 + n) * 2 + k) * 1024 + rdo)
; #define G_WAIT_L(n) asm volatile("s_waitcnt lgkmcnt(" #n ")" ::: "memory")
; #define G_BAR __builtin_amdgcn_s_barrier()
; #define G_SCHED __builtin_amdgcn_sched_barrier(0)
;     ...
;     G_LDB(B0, 1, 0); G_SCHED; G_LDA(At, 1, 0); G_STAGE(G_SA(0, 1), A, oa0, oa1, LDA, 128, KA(tt + 2));
;     G_WAIT_L(8); G_BAR; G_WAIT_L(0); G_MMA(0, 0, At, B0); G_BAR; G_SCHED;
;     G_LDB(B1, 1, 1); G_STAGE(G_SB(1, 0), B, ob0, ob1, LDB, 0, KB(tt + 3));
;     G_BAR; G_WAIT_L(0); G_MMA(0, 1, At, B1); G_BAR;
;     G_LDA(At, 1, 1); G_STAGE(G_SA(1, 0), A, oa0, oa1, LDA, 0, KA(tt + 3));
;     G_BAR; G_WAIT_L(0); G_MMA(1, 0, At, B0); G_BAR; G_SCHED;
;     G_STAGE(G_SB(1, 1), B, ob0, ob1, LDB, 128, KB(tt + 3));
	v_readfirstlane_b32 s0, v148
	v_lshl_add_u64 v[164:165], v[246:247], 0, s[24:25]
	s_mov_b32 m0, s0
	v_readfirstlane_b32 s0, v149
	global_load_lds_dwordx4 v[164:165], off
	s_mov_b32 m0, s0
	v_lshl_add_u64 v[164:165], v[248:249], 0, s[24:25]
	global_load_lds_dwordx4 v[164:165], off
	s_waitcnt vmcnt(6)
	s_barrier
	v_mfma_f32_16x16x32_bf16 v[2:5], v[194:197], v[226:229], v[2:5]
	v_mfma_f32_16x16x32_bf16 v[58:61], v[194:197], v[234:237], v[58:61]
	v_mfma_f32_16x16x32_bf16 v[66:69], v[202:205], v[226:229], v[66:69]
	v_mfma_f32_16x16x32_bf16 v[70:73], v[202:205], v[234:237], v[70:73]
	v_mfma_f32_16x16x32_bf16 v[74:77], v[210:213], v[226:229], v[74:77]
	v_mfma_f32_16x16x32_bf16 v[82:85], v[210:213], v[234:237], v[82:85]
	v_mfma_f32_16x16x32_bf16 v[86:89], v[218:221], v[226:229], v[86:89]
	v_mfma_f32_16x16x32_bf16 v[90:93], v[218:221], v[234:237], v[90:93]
	v_mfma_f32_16x16x32_bf16 v[2:5], v[198:201], v[230:233], v[2:5]
	v_mfma_f32_16x16x32_bf16 v[58:61], v[198:201], v[238:241], v[58:61]
	v_mfma_f32_16x16x32_bf16 v[66:69], v[206:209], v[230:233], v[66:69]
	v_mfma_f32_16x16x32_bf16 v[70:73], v[206:209], v[238:241], v[70:73]
	v_mfma_f32_16x16x32_bf16 v[74:77], v[214:217], v[230:233], v[74:77]
	v_mfma_f32_16x16x32_bf16 v[82:85], v[214:217], v[238:241], v[82:85]
	v_mfma_f32_16x16x32_bf16 v[86:89], v[222:225], v[230:233], v[86:89]
	v_mfma_f32_16x16x32_bf16 v[90:93], v[222:225], v[238:241], v[90:93]
	s_barrier
	ds_read_b128 v[164:167], v150
	ds_read_b128 v[182:185], v150 offset:1024
	ds_read_b128 v[186:189], v150 offset:2048
	ds_read_b128 v[190:193], v150 offset:3072
	v_readfirstlane_b32 s0, v151
	v_lshl_add_u64 v[226:227], v[242:243], 0, s[86:87]
	s_mov_b32 m0, s0
	v_readfirstlane_b32 s0, v152
	ds_read_b128 v[194:197], v142 offset:32768
	ds_read_b128 v[198:201], v142 offset:33792
	ds_read_b128 v[202:205], v142 offset:34816
	ds_read_b128 v[206:209], v142 offset:35840
	ds_read_b128 v[210:213], v142 offset:36864
	ds_read_b128 v[214:217], v142 offset:37888
	ds_read_b128 v[218:221], v142 offset:38912
	ds_read_b128 v[222:225], v142 offset:39936
	global_load_lds_dwordx4 v[226:227], off
	s_mov_b32 m0, s0
	v_lshl_add_u64 v[226:227], v[244:245], 0, s[86:87]
	global_load_lds_dwordx4 v[226:227], off
	s_waitcnt lgkmcnt(8)
	s_barrier
	s_waitcnt lgkmcnt(0)
	v_mfma_f32_16x16x32_bf16 v[126:129], v[194:197], v[164:167], v[126:129]
	v_mfma_f32_16x16x32_bf16 v[122:125], v[194:197], v[186:189], v[122:125]
	v_mfma_f32_16x16x32_bf16 v[118:121], v[202:205], v[164:167], v[118:121]
	v_mfma_f32_16x16x32_bf16 v[114:117], v[202:205], v[186:189], v[114:117]
	v_mfma_f32_16x16x32_bf16 v[110:113], v[210:213], v[164:167], v[110:113]
	v_mfma_f32_16x16x32_bf16 v[106:109], v[210:213], v[186:189], v[106:109]
	v_mfma_f32_16x16x32_bf16 v[102:105], v[218:221], v[164:167], v[102:105]
	v_mfma_f32_16x16x32_bf16 v[98:101], v[218:221], v[186:189], v[98:101]
	v_mfma_f32_16x16x32_bf16 v[126:129], v[198:201], v[182:185], v[126:129]
	v_mfma_f32_16x16x32_bf16 v[122:125], v[198:201], v[190:193], v[122:125]
	v_mfma_f32_16x16x32_bf16 v[118:121], v[206:209], v[182:185], v[118:121]
	v_mfma_f32_16x16x32_bf16 v[114:117], v[206:209], v[190:193], v[114:117]
	v_mfma_f32_16x16x32_bf16 v[110:113], v[214:217], v[182:185], v[110:113]
	v_mfma_f32_16x16x32_bf16 v[106:109], v[214:217], v[190:193], v[106:109]
	v_mfma_f32_16x16x32_bf16 v[102:105], v[222:225], v[182:185], v[102:105]
	v_mfma_f32_16x16x32_bf16 v[98:101], v[222:225], v[190:193], v[98:101]
	s_barrier
	v_readfirstlane_b32 s0, v153
	v_lshl_add_u64 v[250:251], v[246:247], 0, s[36:37]
	s_mov_b32 m0, s0
	v_readfirstlane_b32 s0, v154
	ds_read_b128 v[226:229], v145
	ds_read_b128 v[230:233], v145 offset:1024
	ds_read_b128 v[234:237], v145 offset:2048
	ds_read_b128 v[238:241], v145 offset:3072
	global_load_lds_dwordx4 v[250:251], off
	s_mov_b32 m0, s0
	v_lshl_add_u64 v[250:251], v[248:249], 0, s[36:37]
	global_load_lds_dwordx4 v[250:251], off
	s_barrier
	s_waitcnt lgkmcnt(0)
	v_mfma_f32_16x16x32_bf16 v[94:97], v[194:197], v[226:229], v[94:97]
	v_mfma_f32_16x16x32_bf16 v[78:81], v[194:197], v[234:237], v[78:81]
	v_mfma_f32_16x16x32_bf16 v[62:65], v[202:205], v[226:229], v[62:65]
	v_mfma_f32_16x16x32_bf16 v[54:57], v[202:205], v[234:237], v[54:57]
	v_mfma_f32_16x16x32_bf16 v[50:53], v[210:213], v[226:229], v[50:53]
	v_mfma_f32_16x16x32_bf16 v[46:49], v[210:213], v[234:237], v[46:49]
	v_mfma_f32_16x16x32_bf16 v[42:45], v[218:221], v[226:229], v[42:45]
	v_mfma_f32_16x16x32_bf16 v[38:41], v[218:221], v[234:237], v[38:41]
	v_mfma_f32_16x16x32_bf16 v[94:97], v[198:201], v[230:233], v[94:97]
	v_mfma_f32_16x16x32_bf16 v[78:81], v[198:201], v[238:241], v[78:81]
	v_mfma_f32_16x16x32_bf16 v[62:65], v[206:209], v[230:233], v[62:65]
	v_mfma_f32_16x16x32_bf16 v[54:57], v[206:209], v[238:241], v[54:57]
	v_mfma_f32_16x16x32_bf16 v[50:53], v[214:217], v[230:233], v[50:53]
	v_mfma_f32_16x16x32_bf16 v[46:49], v[214:217], v[238:241], v[46:49]
	v_mfma_f32_16x16x32_bf16 v[42:45], v[222:225], v[230:233], v[42:45]
	v_mfma_f32_16x16x32_bf16 v[38:41], v[222:225], v[238:241], v[38:41]
	v_readfirstlane_b32 s0, v155
	v_lshl_add_u64 v[242:243], v[242:243], 0, s[90:91]
	s_mov_b32 m0, s0
	v_readfirstlane_b32 s0, v156
	s_barrier
	ds_read_b128 v[194:197], v142 offset:49152
	ds_read_b128 v[198:201], v142 offset:50176
	ds_read_b128 v[202:205], v142 offset:51200
	ds_read_b128 v[206:209], v142 offset:52224
	ds_read_b128 v[210:213], v142 offset:53248
	ds_read_b128 v[214:217], v142 offset:54272
	ds_read_b128 v[218:221], v142 offset:55296
	ds_read_b128 v[222:225], v142 offset:56320
	global_load_lds_dwordx4 v[242:243], off
	s_mov_b32 m0, s0
	v_lshl_add_u64 v[242:243], v[244:245], 0, s[90:91]
	global_load_lds_dwordx4 v[242:243], off
	s_barrier
; #define G_LDA(dst, b, h)                                                                                                  \
;   _Pragma("unroll") for (int m = 0; m < 4; ++m) _Pragma("unroll") for (int k = 0; k < 2; ++k)                             \
;       dst[m][k] = *(const bf16x8*)((const char*)G_SA(b, h) + ((wr * 4 + m) * 2 + k) * 1024 + rdo)
; #define G_LDB(dst, b, h)                                                                                                  \
;   _Pragma("unroll") for (int n = 0; n < 2; ++n) _Pragma("unroll") for (int k = 0; k < 2; ++k)                             \
;       dst[n][k] = *(const bf16x8*)((const char*)G_SB(b, h) + ((wc * 2 + n) * 2 + k) * 1024 + rdo)
; #define G_WAIT_V(n) asm volatile("s_waitcnt vmcnt(" #n ")" ::: "memory")
; #define G_WAIT_L(n) asm volatile("s_waitcnt lgkmcnt(" #n ")" ::: "memory")
; #define G_BAR __builtin_amdgcn_s_barrier()
; DI void br_flush(PREF p, f32x4 (&acc)[2][2][4][2], int slot) { br_store(p, acc, slot); zero_acc256(acc); }
;     ...
;     G_WAIT_V(6); G_BAR; G_MMA(1, 1, At, B1); G_BAR;
;     if (MODE && ((tt + 1) & 3) == 3) br_flush(p, acc, (tt + 1) >> 2);
;   }
;   {
;     G_LDB(B0, 0, 0); G_LDA(At, 0, 0); G_STAGE(G_SA(1, 1), A, oa0, oa1, LDA, 128, KA(nt - 1));
;     G_BAR; G_WAIT_L(0); G_MMA(0, 0, At, B0); G_BAR;
;     G_LDB(B1, 0, 1); G_BAR; G_WAIT_L(0); G_MMA(0, 1, At, B1); G_BAR;
;     G_LDA(At, 0, 1); G_WAIT_V(4); G_BAR; G_WAIT_L(0); G_MMA(1, 0, At, B0); G_MMA(1, 1, At, B1); G_BAR;
	s_waitcnt lgkmcnt(0)
	v_mfma_f32_16x16x32_bf16 v[34:37], v[194:197], v[164:167], v[34:37]
	v_mfma_f32_16x16x32_bf16 v[30:33], v[194:197], v[186:189], v[30:33]
	v_mfma_f32_16x16x32_bf16 v[26:29], v[202:205], v[164:167], v[26:29]
	v_mfma_f32_16x16x32_bf16 v[22:25], v[202:205], v[186:189], v[22:25]
	v_mfma_f32_16x16x32_bf16 v[18:21], v[210:213], v[164:167], v[18:21]
	v_mfma_f32_16x16x32_bf16 v[14:17], v[210:213], v[186:189], v[14:17]
	v_mfma_f32_16x16x32_bf16 v[10:13], v[218:221], v[164:167], v[10:13]
	v_mfma_f32_16x16x32_bf16 v[6:9], v[218:221], v[186:189], v[6:9]
	v_mfma_f32_16x16x32_bf16 v[34:37], v[198:201], v[182:185], v[34:37]
	v_mfma_f32_16x16x32_bf16 v[30:33], v[198:201], v[190:193], v[30:33]
	v_mfma_f32_16x16x32_bf16 v[26:29], v[206:209], v[182:185], v[26:29]
	v_mfma_f32_16x16x32_bf16 v[22:25], v[206:209], v[190:193], v[22:25]
	v_mfma_f32_16x16x32_bf16 v[18:21], v[214:217], v[182:185], v[18:21]
	v_mfma_f32_16x16x32_bf16 v[14:17], v[214:217], v[190:193], v[14:17]
	v_mfma_f32_16x16x32_bf16 v[10:13], v[222:225], v[182:185], v[10:13]
	v_mfma_f32_16x16x32_bf16 v[6:9], v[222:225], v[190:193], v[6:9]
	s_barrier
	v_readfirstlane_b32 s0, v157
	v_lshl_add_u64 v[164:165], v[246:247], 0, s[40:41]
	s_mov_b32 m0, s0
	v_readfirstlane_b32 s0, v158
	global_load_lds_dwordx4 v[164:165], off
	s_mov_b32 m0, s0
	v_lshl_add_u64 v[164:165], v[248:249], 0, s[40:41]
	global_load_lds_dwordx4 v[164:165], off
	s_waitcnt vmcnt(6)
	s_barrier
	v_mfma_f32_16x16x32_bf16 v[2:5], v[194:197], v[226:229], v[2:5]
	v_mfma_f32_16x16x32_bf16 v[58:61], v[194:197], v[234:237], v[58:61]
	v_mfma_f32_16x16x32_bf16 v[66:69], v[202:205], v[226:229], v[66:69]
	v_mfma_f32_16x16x32_bf16 v[70:73], v[202:205], v[234:237], v[70:73]
	v_mfma_f32_16x16x32_bf16 v[74:77], v[210:213], v[226:229], v[74:77]
	v_mfma_f32_16x16x32_bf16 v[82:85], v[210:213], v[234:237], v[82:85]
	v_mfma_f32_16x16x32_bf16 v[86:89], v[218:221], v[226:229], v[86:89]
	v_mfma_f32_16x16x32_bf16 v[90:93], v[218:221], v[234:237], v[90:93]
	v_mfma_f32_16x16x32_bf16 v[2:5], v[198:201], v[230:233], v[2:5]
	v_mfma_f32_16x16x32_bf16 v[58:61], v[198:201], v[238:241], v[58:61]
	v_mfma_f32_16x16x32_bf16 v[66:69], v[206:209], v[230:233], v[66:69]
	v_mfma_f32_16x16x32_bf16 v[70:73], v[206:209], v[238:241], v[70:73]
	v_mfma_f32_16x16x32_bf16 v[74:77], v[214:217], v[230:233], v[74:77]
	v_mfma_f32_16x16x32_bf16 v[82:85], v[214:217], v[238:241], v[82:85]
	v_mfma_f32_16x16x32_bf16 v[86:89], v[222:225], v[230:233], v[86:89]
	v_mfma_f32_16x16x32_bf16 v[90:93], v[222:225], v[238:241], v[90:93]
	s_add_i32 s22, s22, 2
	s_add_u32 s20, s20, 0x100
	s_addc_u32 s21, s21, 0
	s_cmp_lt_u32 s22, 12
	s_barrier
	s_cbranch_scc1 .LBB0_40
	s_add_u32 s0, s16, 0x40780
	s_addc_u32 s1, s17, 0
	v_readfirstlane_b32 s16, v161
	v_lshl_add_u64 v[132:133], v[132:133], 1, s[0:1]
	s_mov_b32 m0, s16
	v_lshl_add_u64 v[130:131], v[130:131], 1, s[0:1]
	v_readfirstlane_b32 s0, v160
	ds_read_b128 v[134:137], v162
	ds_read_b128 v[138:141], v162 offset:1024
	ds_read_b128 v[146:149], v162 offset:2048
	ds_read_b128 v[152:155], v162 offset:3072
	ds_read_b128 v[164:167], v142
	ds_read_b128 v[182:185], v142 offset:1024
	ds_read_b128 v[186:189], v142 offset:2048
	ds_read_b128 v[190:193], v142 offset:3072
	ds_read_b128 v[194:197], v142 offset:4096
	ds_read_b128 v[198:201], v142 offset:5120
	ds_read_b128 v[202:205], v142 offset:6144
	ds_read_b128 v[206:209], v142 offset:7168
	global_load_lds_dwordx4 v[132:133], off
	s_mov_b32 m0, s0
	s_nop 0
	global_load_lds_dwordx4 v[130:131], off
	s_barrier
	s_waitcnt lgkmcnt(0)
	v_mfma_f32_16x16x32_bf16 v[126:129], v[164:167], v[134:137], v[126:129]
	v_mfma_f32_16x16x32_bf16 v[122:125], v[164:167], v[146:149], v[122:125]
	v_mfma_f32_16x16x32_bf16 v[110:113], v[194:197], v[134:137], v[110:113]
	v_mfma_f32_16x16x32_bf16 v[102:105], v[202:205], v[134:137], v[102:105]
	v_mfma_f32_16x16x32_bf16 v[126:129], v[182:185], v[138:141], v[126:129]
	v_mfma_f32_16x16x32_bf16 v[122:125], v[182:185], v[152:155], v[122:125]
	v_mfma_f32_16x16x32_bf16 v[118:121], v[186:189], v[134:137], v[118:121]
	v_mfma_f32_16x16x32_bf16 v[114:117], v[186:189], v[146:149], v[114:117]
	v_mfma_f32_16x16x32_bf16 v[110:113], v[198:201], v[138:141], v[110:113]
	v_mfma_f32_16x16x32_bf16 v[106:109], v[194:197], v[146:149], v[106:109]
	v_mfma_f32_16x16x32_bf16 v[102:105], v[206:209], v[138:141], v[102:105]
	v_mfma_f32_16x16x32_bf16 v[98:101], v[202:205], v[146:149], v[98:101]
	v_mfma_f32_16x16x32_bf16 v[130:133], v[190:193], v[138:141], v[118:121]
	v_mfma_f32_16x16x32_bf16 v[210:213], v[190:193], v[152:155], v[114:117]
	v_mfma_f32_16x16x32_bf16 v[214:217], v[198:201], v[152:155], v[106:109]
	v_mfma_f32_16x16x32_bf16 v[218:221], v[206:209], v[152:155], v[98:101]
	s_barrier
	s_nop 1
	s_nop 0
	ds_read_b128 v[98:101], v159
	ds_read_b128 v[106:109], v159 offset:1024
	ds_read_b128 v[114:117], v159 offset:2048
	ds_read_b128 v[118:121], v159 offset:3072
	s_barrier
	s_waitcnt lgkmcnt(0)
	v_mfma_f32_16x16x32_bf16 v[94:97], v[164:167], v[98:101], v[94:97]
	v_mfma_f32_16x16x32_bf16 v[78:81], v[164:167], v[114:117], v[78:81]
	v_mfma_f32_16x16x32_bf16 v[62:65], v[186:189], v[98:101], v[62:65]
	v_mfma_f32_16x16x32_bf16 v[54:57], v[186:189], v[114:117], v[54:57]
	v_mfma_f32_16x16x32_bf16 v[50:53], v[194:197], v[98:101], v[50:53]
	v_mfma_f32_16x16x32_bf16 v[46:49], v[194:197], v[114:117], v[46:49]
	v_mfma_f32_16x16x32_bf16 v[42:45], v[202:205], v[98:101], v[42:45]
	v_mfma_f32_16x16x32_bf16 v[38:41], v[202:205], v[114:117], v[38:41]
	v_mfma_f32_16x16x32_bf16 v[94:97], v[182:185], v[106:109], v[94:97]
	v_mfma_f32_16x16x32_bf16 v[78:81], v[182:185], v[118:121], v[78:81]
	v_mfma_f32_16x16x32_bf16 v[62:65], v[190:193], v[106:109], v[62:65]
	v_mfma_f32_16x16x32_bf16 v[54:57], v[190:193], v[118:121], v[54:57]
	v_mfma_f32_16x16x32_bf16 v[50:53], v[198:201], v[106:109], v[50:53]
	v_mfma_f32_16x16x32_bf16 v[46:49], v[198:201], v[118:121], v[46:49]
	v_mfma_f32_16x16x32_bf16 v[42:45], v[206:209], v[106:109], v[42:45]
	v_mfma_f32_16x16x32_bf16 v[38:41], v[206:209], v[118:121], v[38:41]
	s_barrier
; #define G_LDA(dst, b, h)                                                                                                  \
;   _Pragma("unroll") for (int m = 0; m < 4; ++m) _Pragma("unroll") for (int k = 0; k < 2; ++k)                             \
;       dst[m][k] = *(const bf16x8*)((const char*)G_SA(b, h) + ((wr * 4 + m) * 2 + k) * 1024 + rdo)
; #define G_LDB(dst, b, h)                                                                                                  \
;   _Pragma("unroll") for (int n = 0; n < 2; ++n) _Pragma("unroll") for (int k = 0; k < 2; ++k)                             \
;       dst[n][k] = *(const bf16x8*)((const char*)G_SB(b, h) + ((wc * 2 + n) * 2 + k) * 1024 + rdo)
; #define G_WAIT_V(n) asm volatile("s_waitcnt vmcnt(" #n ")" ::: "memory")
; #define G_WAIT_L(n) asm volatile("s_waitcnt lgkmcnt(" #n ")" ::: "memory")
; #define G_BAR __builtin_amdgcn_s_barrier()
;     ...
;     G_LDA(At, 0, 1); G_WAIT_V(4); G_BAR; G_WAIT_L(0); G_MMA(1, 0, At, B0); G_MMA(1, 1, At, B1); G_BAR;
;   }
;   {
;     G_LDB(B0, 1, 0); G_LDA(At, 1, 0); G_WAIT_V(2); G_BAR; G_WAIT_L(0); G_MMA(0, 0, At, B0); G_BAR;
	ds_read_b128 v[156:159], v142 offset:16384
	ds_read_b128 v[164:167], v142 offset:17408
	ds_read_b128 v[182:185], v142 offset:18432
	ds_read_b128 v[186:189], v142 offset:19456
	ds_read_b128 v[190:193], v142 offset:20480
	ds_read_b128 v[194:197], v142 offset:21504
	ds_read_b128 v[198:201], v142 offset:22528
	ds_read_b128 v[202:205], v142 offset:23552
	s_waitcnt vmcnt(4)
	s_barrier
	s_waitcnt lgkmcnt(0)
	v_mfma_f32_16x16x32_bf16 v[34:37], v[156:159], v[134:137], v[34:37]
	v_mfma_f32_16x16x32_bf16 v[30:33], v[156:159], v[146:149], v[30:33]
	v_mfma_f32_16x16x32_bf16 v[26:29], v[182:185], v[134:137], v[26:29]
	v_mfma_f32_16x16x32_bf16 v[22:25], v[182:185], v[146:149], v[22:25]
	v_mfma_f32_16x16x32_bf16 v[18:21], v[190:193], v[134:137], v[18:21]
	v_mfma_f32_16x16x32_bf16 v[14:17], v[190:193], v[146:149], v[14:17]
	v_mfma_f32_16x16x32_bf16 v[10:13], v[198:201], v[134:137], v[10:13]
	v_mfma_f32_16x16x32_bf16 v[6:9], v[198:201], v[146:149], v[6:9]
	v_mfma_f32_16x16x32_bf16 v[34:37], v[164:167], v[138:141], v[34:37]
	v_mfma_f32_16x16x32_bf16 v[30:33], v[164:167], v[152:155], v[30:33]
	v_mfma_f32_16x16x32_bf16 v[26:29], v[186:189], v[138:141], v[26:29]
	v_mfma_f32_16x16x32_bf16 v[22:25], v[186:189], v[152:155], v[22:25]
	v_mfma_f32_16x16x32_bf16 v[18:21], v[194:197], v[138:141], v[18:21]
	v_mfma_f32_16x16x32_bf16 v[14:17], v[194:197], v[152:155], v[14:17]
	v_mfma_f32_16x16x32_bf16 v[10:13], v[202:205], v[138:141], v[10:13]
	v_mfma_f32_16x16x32_bf16 v[6:9], v[202:205], v[152:155], v[6:9]
	v_mfma_f32_16x16x32_bf16 v[58:61], v[156:159], v[114:117], v[58:61]
	v_mfma_f32_16x16x32_bf16 v[134:137], v[164:167], v[118:121], v[58:61]
	v_mfma_f32_16x16x32_bf16 v[58:61], v[182:185], v[98:101], v[66:69]
	v_mfma_f32_16x16x32_bf16 v[138:141], v[186:189], v[106:109], v[58:61]
	v_mfma_f32_16x16x32_bf16 v[58:61], v[182:185], v[114:117], v[70:73]
	v_mfma_f32_16x16x32_bf16 v[146:149], v[186:189], v[118:121], v[58:61]
	v_mfma_f32_16x16x32_bf16 v[58:61], v[190:193], v[98:101], v[74:77]
	v_mfma_f32_16x16x32_bf16 v[152:155], v[194:197], v[106:109], v[58:61]
	v_mfma_f32_16x16x32_bf16 v[58:61], v[190:193], v[114:117], v[82:85]
	v_mfma_f32_16x16x32_bf16 v[2:5], v[156:159], v[98:101], v[2:5]
	v_mfma_f32_16x16x32_bf16 v[156:159], v[194:197], v[118:121], v[58:61]
	v_mfma_f32_16x16x32_bf16 v[58:61], v[198:201], v[98:101], v[86:89]
	v_mfma_f32_16x16x32_bf16 v[2:5], v[164:167], v[106:109], v[2:5]
	v_mfma_f32_16x16x32_bf16 v[164:167], v[202:205], v[106:109], v[58:61]
	v_mfma_f32_16x16x32_bf16 v[58:61], v[198:201], v[114:117], v[90:93]
	v_mfma_f32_16x16x32_bf16 v[182:185], v[202:205], v[118:121], v[58:61]
	s_barrier
	ds_read_b128 v[186:189], v150
	ds_read_b128 v[190:193], v150 offset:1024
	ds_read_b128 v[194:197], v150 offset:2048
	ds_read_b128 v[198:201], v150 offset:3072
	s_nop 0
	s_nop 0
	ds_read_b128 v[58:61], v142 offset:32768
	ds_read_b128 v[66:69], v142 offset:33792
	ds_read_b128 v[70:73], v142 offset:34816
	ds_read_b128 v[74:77], v142 offset:35840
	ds_read_b128 v[202:205], v142 offset:36864
	ds_read_b128 v[206:209], v142 offset:37888
	ds_read_b128 v[222:225], v142 offset:38912
	ds_read_b128 v[226:229], v142 offset:39936
	s_waitcnt vmcnt(2)
	s_barrier
	s_waitcnt lgkmcnt(0)
	v_mfma_f32_16x16x32_bf16 v[82:85], v[58:61], v[186:189], v[126:129]
	v_mfma_f32_16x16x32_bf16 v[118:121], v[66:69], v[190:193], v[82:85]
	v_mfma_f32_16x16x32_bf16 v[82:85], v[58:61], v[194:197], v[122:125]
	v_mfma_f32_16x16x32_bf16 v[126:129], v[66:69], v[198:201], v[82:85]
	v_mfma_f32_16x16x32_bf16 v[82:85], v[70:73], v[186:189], v[130:133]
	v_mfma_f32_16x16x32_bf16 v[114:117], v[74:77], v[190:193], v[82:85]
	v_mfma_f32_16x16x32_bf16 v[82:85], v[70:73], v[194:197], v[210:213]
	v_mfma_f32_16x16x32_bf16 v[122:125], v[74:77], v[198:201], v[82:85]
	v_mfma_f32_16x16x32_bf16 v[82:85], v[202:205], v[186:189], v[110:113]
	v_mfma_f32_16x16x32_bf16 v[106:109], v[206:209], v[190:193], v[82:85]
	v_mfma_f32_16x16x32_bf16 v[82:85], v[202:205], v[194:197], v[214:217]
	v_mfma_f32_16x16x32_bf16 v[110:113], v[206:209], v[198:201], v[82:85]
	v_mfma_f32_16x16x32_bf16 v[82:85], v[222:225], v[186:189], v[102:105]
	v_mfma_f32_16x16x32_bf16 v[98:101], v[226:229], v[190:193], v[82:85]
	v_mfma_f32_16x16x32_bf16 v[82:85], v[222:225], v[194:197], v[218:221]
	v_mfma_f32_16x16x32_bf16 v[102:105], v[226:229], v[198:201], v[82:85]
	s_barrier
; #define G_LDA(dst, b, h)                                                                                                  \
;   _Pragma("unroll") for (int m = 0; m < 4; ++m) _Pragma("unroll") for (int k = 0; k < 2; ++k)                             \
;       dst[m][k] = *(const bf16x8*)((const char*)G_SA(b, h) + ((wr * 4 + m) * 2 + k) * 1024 + rdo)
; #define G_LDB(dst, b, h)                                                                                                  \
;   _Pragma("unroll") for (int n = 0; n < 2; ++n) _Pragma("unroll") for (int k = 0; k < 2; ++k)                             \
;       dst[n][k] = *(const bf16x8*)((const char*)G_SB(b, h) + ((wc * 2 + n) * 2 + k) * 1024 + rdo)
; #define G_WAIT_V(n) asm volatile("s_waitcnt vmcnt(" #n ")" ::: "memory")
; #define G_WAIT_L(n) asm volatile("s_waitcnt lgkmcnt(" #n ")" ::: "memory")
; #define G_BAR __builtin_amdgcn_s_barrier()
;     ...
;     G_LDB(B0, 1, 0); G_LDA(At, 1, 0); G_WAIT_V(2); G_BAR; G_WAIT_L(0); G_MMA(0, 0, At, B0); G_BAR;
;     G_LDB(B1, 1, 1); G_WAIT_V(0); G_BAR; G_WAIT_L(0); G_MMA(0, 1, At, B1); G_BAR;
;     G_LDA(At, 1, 1); G_BAR; G_WAIT_L(0); G_MMA(1, 0, At, B0); G_MMA(1, 1, At, B1); G_BAR;
;   }
;   if (wr == 0) G_BAR;
	ds_read_b128 v[130:133], v145
	ds_read_b128 v[210:213], v145 offset:1024
	ds_read_b128 v[214:217], v145 offset:2048
	ds_read_b128 v[218:221], v145 offset:3072
	s_waitcnt vmcnt(0)
	s_barrier
	s_waitcnt lgkmcnt(0)
	v_mfma_f32_16x16x32_bf16 v[82:85], v[58:61], v[130:133], v[94:97]
	v_mfma_f32_16x16x32_bf16 v[58:61], v[58:61], v[214:217], v[78:81]
	v_mfma_f32_16x16x32_bf16 v[94:97], v[66:69], v[218:221], v[58:61]
	v_mfma_f32_16x16x32_bf16 v[58:61], v[70:73], v[130:133], v[62:65]
	v_mfma_f32_16x16x32_bf16 v[54:57], v[70:73], v[214:217], v[54:57]
	v_mfma_f32_16x16x32_bf16 v[50:53], v[202:205], v[130:133], v[50:53]
	v_mfma_f32_16x16x32_bf16 v[46:49], v[202:205], v[214:217], v[46:49]
	v_mfma_f32_16x16x32_bf16 v[42:45], v[222:225], v[130:133], v[42:45]
	v_mfma_f32_16x16x32_bf16 v[38:41], v[222:225], v[214:217], v[38:41]
	v_mfma_f32_16x16x32_bf16 v[86:89], v[66:69], v[210:213], v[82:85]
	v_mfma_f32_16x16x32_bf16 v[82:85], v[74:77], v[210:213], v[58:61]
	v_mfma_f32_16x16x32_bf16 v[90:93], v[74:77], v[218:221], v[54:57]
	v_mfma_f32_16x16x32_bf16 v[74:77], v[206:209], v[210:213], v[50:53]
	v_mfma_f32_16x16x32_bf16 v[78:81], v[206:209], v[218:221], v[46:49]
	v_mfma_f32_16x16x32_bf16 v[66:69], v[226:229], v[210:213], v[42:45]
	v_mfma_f32_16x16x32_bf16 v[70:73], v[226:229], v[218:221], v[38:41]
	s_barrier
	ds_read_b128 v[202:205], v142 offset:49152
	ds_read_b128 v[206:209], v142 offset:50176
	ds_read_b128 v[222:225], v142 offset:51200
	ds_read_b128 v[226:229], v142 offset:52224
	ds_read_b128 v[230:233], v142 offset:53248
	ds_read_b128 v[234:237], v142 offset:54272
	ds_read_b128 v[238:241], v142 offset:55296
	ds_read_b128 v[142:145], v142 offset:56320
	s_barrier
	s_waitcnt lgkmcnt(0)
	v_mfma_f32_16x16x32_bf16 v[34:37], v[202:205], v[186:189], v[34:37]
	v_mfma_f32_16x16x32_bf16 v[30:33], v[202:205], v[194:197], v[30:33]
	v_mfma_f32_16x16x32_bf16 v[26:29], v[222:225], v[186:189], v[26:29]
	v_mfma_f32_16x16x32_bf16 v[22:25], v[222:225], v[194:197], v[22:25]
	v_mfma_f32_16x16x32_bf16 v[18:21], v[230:233], v[186:189], v[18:21]
	v_mfma_f32_16x16x32_bf16 v[14:17], v[230:233], v[194:197], v[14:17]
	v_mfma_f32_16x16x32_bf16 v[10:13], v[238:241], v[186:189], v[10:13]
	v_mfma_f32_16x16x32_bf16 v[6:9], v[238:241], v[194:197], v[6:9]
	v_mfma_f32_16x16x32_bf16 v[54:57], v[206:209], v[190:193], v[34:37]
	v_mfma_f32_16x16x32_bf16 v[62:65], v[206:209], v[198:201], v[30:33]
	v_mfma_f32_16x16x32_bf16 v[50:53], v[226:229], v[190:193], v[26:29]
	v_mfma_f32_16x16x32_bf16 v[58:61], v[226:229], v[198:201], v[22:25]
	v_mfma_f32_16x16x32_bf16 v[42:45], v[234:237], v[190:193], v[18:21]
	v_mfma_f32_16x16x32_bf16 v[46:49], v[234:237], v[198:201], v[14:17]
	v_mfma_f32_16x16x32_bf16 v[34:37], v[142:145], v[190:193], v[10:13]
	v_mfma_f32_16x16x32_bf16 v[38:41], v[142:145], v[198:201], v[6:9]
	v_mfma_f32_16x16x32_bf16 v[2:5], v[202:205], v[130:133], v[2:5]
	v_mfma_f32_16x16x32_bf16 v[22:25], v[206:209], v[210:213], v[2:5]
	v_mfma_f32_16x16x32_bf16 v[2:5], v[202:205], v[214:217], v[134:137]
	v_mfma_f32_16x16x32_bf16 v[30:33], v[206:209], v[218:221], v[2:5]
	v_mfma_f32_16x16x32_bf16 v[2:5], v[222:225], v[130:133], v[138:141]
	v_mfma_f32_16x16x32_bf16 v[18:21], v[226:229], v[210:213], v[2:5]
	v_mfma_f32_16x16x32_bf16 v[2:5], v[222:225], v[214:217], v[146:149]
	v_mfma_f32_16x16x32_bf16 v[26:29], v[226:229], v[218:221], v[2:5]
	v_mfma_f32_16x16x32_bf16 v[2:5], v[230:233], v[130:133], v[152:155]
	v_mfma_f32_16x16x32_bf16 v[10:13], v[234:237], v[210:213], v[2:5]
	v_mfma_f32_16x16x32_bf16 v[2:5], v[230:233], v[214:217], v[156:159]
	v_mfma_f32_16x16x32_bf16 v[14:17], v[234:237], v[218:221], v[2:5]
	v_mfma_f32_16x16x32_bf16 v[2:5], v[238:241], v[130:133], v[164:167]
	v_mfma_f32_16x16x32_bf16 v[6:9], v[238:241], v[214:217], v[182:185]
	v_mfma_f32_16x16x32_bf16 v[2:5], v[142:145], v[210:213], v[2:5]
	v_mfma_f32_16x16x32_bf16 v[6:9], v[142:145], v[218:221], v[6:9]
	v_cmp_gt_u32_e32 vcc, s67, v0
	s_barrier
	s_and_saveexec_b64 s[16:17], vcc
	s_cbranch_execz .LBB0_43
	s_barrier

; #define G_LDA(dst, b, h)                                                                                                  \
;   _Pragma("unroll") for (int m = 0; m < 4; ++m) _Pragma("unroll") for (int k = 0; k < 2; ++k)                             \
;       dst[m][k] = *(const bf16x8*)((const char*)G_SA(b, h) + ((wr * 4 + m) * 2 + k) * 1024 + rdo)
; #define G_LDB(dst, b, h)                                                                                                  \
;   _Pragma("unroll") for (int n = 0; n < 2; ++n) _Pragma("unroll") for (int k = 0; k < 2; ++k)                             \
;       dst[n][k] = *(const bf16x8*)((const char*)G_SB(b, h) + ((wc * 2 + n) * 2 + k) * 1024 + rdo)
; #define G_WAIT_V(n) asm volatile("s_waitcnt vmcnt(" #n ")" ::: "memory")
; #define G_WAIT_L(n) asm volatile("s_waitcnt lgkmcnt(" #n ")" ::: "memory")
; #define G_BAR __builtin_amdgcn_s_barrier()
; #define G_SCHED __builtin_amdgcn_sched_barrier(0)
;     ...
;   if (wr == 1) G_BAR;
;   G_WAIT_V(4); G_BAR;
;   G_STAGE(G_SB(1, 0), B, ob0, ob1, LDB, 0, KB(1)); G_STAGE(G_SA(1, 0), A, oa0, oa1, LDA, 0, KA(1)); G_STAGE(G_SB(1, 1), B, ob0, ob1, LDB, 128, KB(1));
;   G_WAIT_V(6); G_BAR;
;   for (int tt = 0; tt < nt - 2; tt += 2) {
;     G_LDB(B0, 0, 0); G_SCHED; G_LDA(At, 0, 0); G_STAGE(G_SA(1, 1), A, oa0, oa1, LDA, 128, KA(tt + 1));
;     G_WAIT_L(8); G_BAR; G_WAIT_L(0); G_MMA(0, 0, At, B0); G_BAR; G_SCHED;
;     G_LDB(B1, 0, 1); G_STAGE(G_SB(0, 0), B, ob0, ob1, LDB, 0, KB(tt + 2));
;     G_BAR; G_WAIT_L(0); G_MMA(0, 1, At, B1); G_BAR;
.LBB0_45:
	s_or_b64 exec, exec, s[22:23]
	v_add_u32_e32 v13, 0x18000, v18
	v_lshl_add_u64 v[24:25], v[6:7], 0, s[76:77]
	v_readfirstlane_b32 s37, v13
	v_add_u32_e32 v13, 0x1a000, v18
	s_mov_b32 m0, s37
	v_readfirstlane_b32 s40, v13
	v_add_u32_e32 v13, 0x8000, v18
	s_waitcnt vmcnt(4)
	s_barrier
	global_load_lds_dwordx4 v[24:25], off
	v_lshl_add_u64 v[24:25], v[8:9], 0, s[76:77]
	s_mov_b32 m0, s40
	v_readfirstlane_b32 s35, v13
	v_add_u32_e32 v13, 0xa000, v18
	global_load_lds_dwordx4 v[24:25], off
	v_lshl_add_u64 v[24:25], v[10:11], 0, s[76:77]
	s_mov_b32 m0, s35
	v_readfirstlane_b32 s36, v13
	s_add_u32 s0, s18, 0x10080
	v_add_u32_e32 v13, 0x1c000, v18
	global_load_lds_dwordx4 v[24:25], off
	v_lshl_add_u64 v[24:25], v[14:15], 0, s[76:77]
	s_mov_b32 m0, s36
	s_addc_u32 s1, s19, 0
	v_readfirstlane_b32 s22, v13
	v_add_u32_e32 v13, 0x1e000, v18
	global_load_lds_dwordx4 v[24:25], off
	v_lshl_add_u64 v[24:25], s[0:1], 0, v[2:3]
	s_mov_b32 m0, s22
	v_readfirstlane_b32 s23, v13
	global_load_lds_dwordx4 v[24:25], off
	v_lshl_add_u64 v[24:25], s[0:1], 0, v[4:5]
	s_mov_b32 m0, s23
	v_lshlrev_b32_e32 v26, 2, v0
	global_load_lds_dwordx4 v[24:25], off
	v_lshlrev_b32_e32 v24, 6, v0
	v_and_b32_e32 v13, 48, v0
	v_and_b32_e32 v25, 0x3c0, v24
	v_and_b32_e32 v41, 32, v26
	v_or_b32_e32 v40, v25, v13
	v_bitop3_b32 v13, v25, v41, v13 bitop3:0x36
	s_movk_i32 s0, 0x3000
	v_and_or_b32 v162, v24, s0, v13
	s_add_u32 s0, s20, 0x10080
	s_addc_u32 s1, s21, 0
	v_lshl_add_u64 v[72:73], s[0:1], 0, v[2:3]
	v_lshl_add_u64 v[74:75], s[0:1], 0, v[4:5]
	s_add_u32 s0, s18, 0x10100
	s_addc_u32 s1, s19, 0
	v_or_b32_e32 v230, 0x10000, v162
	v_or_b32_e32 v232, 0x10800, v162
	s_waitcnt vmcnt(6)
	s_barrier
	v_lshl_add_u64 v[160:161], s[0:1], 0, v[2:3]
	v_lshl_add_u64 v[194:195], s[0:1], 0, v[4:5]
	s_add_u32 s0, s20, 0x10100
	v_or_b32_e32 v231, 0x10400, v162
	ds_read_b128 v[24:27], v230
	ds_read_b128 v[28:31], v231
	v_or_b32_e32 v233, 0x10c00, v162
	ds_read_b128 v[32:35], v232
	ds_read_b128 v[36:39], v233
	s_addc_u32 s1, s21, 0
	v_lshl_add_u64 v[214:215], s[0:1], 0, v[2:3]
	v_lshl_add_u64 v[216:217], s[0:1], 0, v[4:5]
	s_add_u32 s0, s18, 0x10180
	s_addc_u32 s1, s19, 0
	v_lshlrev_b32_e32 v42, 13, v12
	v_lshl_add_u64 v[120:121], v[6:7], 0, s[82:83]
	v_lshl_add_u64 v[122:123], v[8:9], 0, s[82:83]
	v_lshl_add_u64 v[152:153], v[10:11], 0, s[82:83]
	v_lshl_add_u64 v[226:227], v[6:7], 0, s[90:91]
	v_lshl_add_u64 v[228:229], v[8:9], 0, s[90:91]
	v_lshl_add_u64 v[12:13], v[10:11], 0, s[90:91]
	v_lshl_add_u64 v[10:11], v[14:15], 0, s[90:91]
	v_lshl_add_u64 v[8:9], s[0:1], 0, v[2:3]
	v_lshl_add_u64 v[6:7], s[0:1], 0, v[4:5]
	v_lshl_add_u64 v[154:155], v[14:15], 0, s[82:83]
	v_add_u32_e32 v14, 0xc000, v18
	v_bitop3_b32 v242, v40, v42, v41 bitop3:0xde
	v_readfirstlane_b32 s19, v14
	v_add_u32_e32 v14, 0xe000, v18
	s_mov_b32 m0, s19
	v_readfirstlane_b32 s18, v14
	ds_read_b128 v[40:43], v242
	ds_read_b128 v[44:47], v242 offset:1024
	ds_read_b128 v[48:51], v242 offset:2048
	ds_read_b128 v[52:55], v242 offset:3072
	ds_read_b128 v[56:59], v242 offset:4096
	ds_read_b128 v[60:63], v242 offset:5120
	ds_read_b128 v[64:67], v242 offset:6144
	ds_read_b128 v[68:71], v242 offset:7168
	global_load_lds_dwordx4 v[72:73], off
	s_mov_b32 m0, s18
	s_nop 0
	global_load_lds_dwordx4 v[74:75], off
	s_waitcnt lgkmcnt(8)
	s_barrier
	s_waitcnt lgkmcnt(0)
	v_mfma_f32_16x16x32_bf16 v[72:75], v[40:43], v[24:27], 0
	v_mfma_f32_16x16x32_bf16 v[76:79], v[40:43], v[32:35], 0
	v_mfma_f32_16x16x32_bf16 v[80:83], v[48:51], v[24:27], 0
	v_mfma_f32_16x16x32_bf16 v[84:87], v[48:51], v[32:35], 0
	v_mfma_f32_16x16x32_bf16 v[88:91], v[56:59], v[24:27], 0
	v_mfma_f32_16x16x32_bf16 v[92:95], v[56:59], v[32:35], 0
	v_mfma_f32_16x16x32_bf16 v[96:99], v[64:67], v[24:27], 0
	v_mfma_f32_16x16x32_bf16 v[100:103], v[64:67], v[32:35], 0
	v_mfma_f32_16x16x32_bf16 v[72:75], v[44:47], v[28:31], v[72:75]
	v_mfma_f32_16x16x32_bf16 v[76:79], v[44:47], v[36:39], v[76:79]
	v_mfma_f32_16x16x32_bf16 v[80:83], v[52:55], v[28:31], v[80:83]
	v_mfma_f32_16x16x32_bf16 v[84:87], v[52:55], v[36:39], v[84:87]
	v_mfma_f32_16x16x32_bf16 v[88:91], v[60:63], v[28:31], v[88:91]
	v_mfma_f32_16x16x32_bf16 v[92:95], v[60:63], v[36:39], v[92:95]
	v_mfma_f32_16x16x32_bf16 v[96:99], v[68:71], v[28:31], v[96:99]
	v_mfma_f32_16x16x32_bf16 v[100:103], v[68:71], v[36:39], v[100:103]
	s_barrier
	v_readfirstlane_b32 s0, v22
	v_or_b32_e32 v234, 0x14000, v162
	v_or_b32_e32 v236, 0x14800, v162
	s_mov_b32 m0, s0
	v_readfirstlane_b32 s0, v23
	v_or_b32_e32 v235, 0x14400, v162
	ds_read_b128 v[104:107], v234
	ds_read_b128 v[108:111], v235
	v_or_b32_e32 v237, 0x14c00, v162
	ds_read_b128 v[112:115], v236
	ds_read_b128 v[116:119], v237
	global_load_lds_dwordx4 v[120:121], off
	s_mov_b32 m0, s0
	s_nop 0
	global_load_lds_dwordx4 v[122:123], off
	s_barrier
	s_waitcnt lgkmcnt(0)
	v_mfma_f32_16x16x32_bf16 v[120:123], v[40:43], v[104:107], 0
	v_mfma_f32_16x16x32_bf16 v[40:43], v[40:43], v[112:115], 0
	v_mfma_f32_16x16x32_bf16 v[120:123], v[44:47], v[108:111], v[120:123]
	v_mfma_f32_16x16x32_bf16 v[40:43], v[44:47], v[116:119], v[40:43]
	v_mfma_f32_16x16x32_bf16 v[44:47], v[48:51], v[104:107], 0
	v_mfma_f32_16x16x32_bf16 v[48:51], v[48:51], v[112:115], 0
	v_mfma_f32_16x16x32_bf16 v[44:47], v[52:55], v[108:111], v[44:47]
	v_mfma_f32_16x16x32_bf16 v[48:51], v[52:55], v[116:119], v[48:51]
	v_mfma_f32_16x16x32_bf16 v[52:55], v[56:59], v[104:107], 0
	v_mfma_f32_16x16x32_bf16 v[56:59], v[56:59], v[112:115], 0
	v_mfma_f32_16x16x32_bf16 v[52:55], v[60:63], v[108:111], v[52:55]
	v_mfma_f32_16x16x32_bf16 v[56:59], v[60:63], v[116:119], v[56:59]
	v_mfma_f32_16x16x32_bf16 v[60:63], v[64:67], v[104:107], 0
	v_mfma_f32_16x16x32_bf16 v[64:67], v[64:67], v[112:115], 0
	v_mfma_f32_16x16x32_bf16 v[60:63], v[68:71], v[108:111], v[60:63]
	v_mfma_f32_16x16x32_bf16 v[64:67], v[68:71], v[116:119], v[64:67]
	v_readfirstlane_b32 s0, v18
	s_mov_b32 m0, s0
	v_readfirstlane_b32 s0, v19
	s_barrier
; #define G_LDA(dst, b, h)                                                                                                  \
;   _Pragma("unroll") for (int m = 0; m < 4; ++m) _Pragma("unroll") for (int k = 0; k < 2; ++k)                             \
;       dst[m][k] = *(const bf16x8*)((const char*)G_SA(b, h) + ((wr * 4 + m) * 2 + k) * 1024 + rdo)
; #define G_LDB(dst, b, h)                                                                                                  \
;   _Pragma("unroll") for (int n = 0; n < 2; ++n) _Pragma("unroll") for (int k = 0; k < 2; ++k)                             \
;       dst[n][k] = *(const bf16x8*)((const char*)G_SB(b, h) + ((wc * 2 + n) * 2 + k) * 1024 + rdo)
; #define G_WAIT_V(n) asm volatile("s_waitcnt vmcnt(" #n ")" ::: "memory")
; #define G_WAIT_L(n) asm volatile("s_waitcnt lgkmcnt(" #n ")" ::: "memory")
; #define G_BAR __builtin_amdgcn_s_barrier()
; #define G_SCHED __builtin_amdgcn_sched_barrier(0)
;     ...
;     G_BAR; G_WAIT_L(0); G_MMA(0, 1, At, B1); G_BAR;
;     G_LDA(At, 0, 1); G_STAGE(G_SA(0, 0), A, oa0, oa1, LDA, 0, KA(tt + 2));
;     G_BAR; G_WAIT_L(0); G_MMA(1, 0, At, B0); G_BAR; G_SCHED;
;     G_STAGE(G_SB(0, 1), B, ob0, ob1, LDB, 128, KB(tt + 2));
;     G_WAIT_V(6); G_BAR; G_MMA(1, 1, At, B1); G_BAR;
;     G_LDB(B0, 1, 0); G_SCHED; G_LDA(At, 1, 0); G_STAGE(G_SA(0, 1), A, oa0, oa1, LDA, 128, KA(tt + 2));
;     G_WAIT_L(8); G_BAR; G_WAIT_L(0); G_MMA(0, 0, At, B0); G_BAR; G_SCHED;
;     G_LDB(B1, 1, 1); G_STAGE(G_SB(1, 0), B, ob0, ob1, LDB, 0, KB(tt + 3));
;     G_BAR; G_WAIT_L(0); G_MMA(0, 1, At, B1); G_BAR;
;     G_LDA(At, 1, 1); G_STAGE(G_SA(1, 0), A, oa0, oa1, LDA, 0, KA(tt + 3));
;     G_BAR; G_WAIT_L(0); G_MMA(1, 0, At, B0); G_BAR; G_SCHED;
	ds_read_b128 v[68:71], v242 offset:16384
	ds_read_b128 v[124:127], v242 offset:17408
	ds_read_b128 v[128:131], v242 offset:18432
	ds_read_b128 v[132:135], v242 offset:19456
	ds_read_b128 v[136:139], v242 offset:20480
	ds_read_b128 v[140:143], v242 offset:21504
	ds_read_b128 v[144:147], v242 offset:22528
	ds_read_b128 v[148:151], v242 offset:23552
	global_load_lds_dwordx4 v[152:153], off
	s_mov_b32 m0, s0
	s_nop 0
	global_load_lds_dwordx4 v[154:155], off
	s_barrier
	s_waitcnt lgkmcnt(0)
	v_mfma_f32_16x16x32_bf16 v[152:155], v[68:71], v[24:27], 0
	v_mfma_f32_16x16x32_bf16 v[164:167], v[128:131], v[24:27], 0
	v_mfma_f32_16x16x32_bf16 v[186:189], v[136:139], v[24:27], 0
	v_mfma_f32_16x16x32_bf16 v[22:25], v[144:147], v[24:27], 0
	v_mfma_f32_16x16x32_bf16 v[152:155], v[124:127], v[28:31], v[152:155]
	v_mfma_f32_16x16x32_bf16 v[164:167], v[132:135], v[28:31], v[164:167]
	v_mfma_f32_16x16x32_bf16 v[186:189], v[140:143], v[28:31], v[186:189]
	v_mfma_f32_16x16x32_bf16 v[22:25], v[148:151], v[28:31], v[22:25]
	v_mfma_f32_16x16x32_bf16 v[26:29], v[144:147], v[32:35], 0
	v_mfma_f32_16x16x32_bf16 v[156:159], v[68:71], v[32:35], 0
	v_mfma_f32_16x16x32_bf16 v[182:185], v[128:131], v[32:35], 0
	v_mfma_f32_16x16x32_bf16 v[190:193], v[136:139], v[32:35], 0
	v_mfma_f32_16x16x32_bf16 v[26:29], v[148:151], v[36:39], v[26:29]
	v_mfma_f32_16x16x32_bf16 v[156:159], v[124:127], v[36:39], v[156:159]
	v_mfma_f32_16x16x32_bf16 v[182:185], v[132:135], v[36:39], v[182:185]
	v_mfma_f32_16x16x32_bf16 v[190:193], v[140:143], v[36:39], v[190:193]
	s_barrier
	v_readfirstlane_b32 s0, v20
	s_mov_b32 m0, s0
	v_readfirstlane_b32 s0, v21
	global_load_lds_dwordx4 v[160:161], off
	s_mov_b32 m0, s0
	s_nop 0
	global_load_lds_dwordx4 v[194:195], off
	s_waitcnt vmcnt(6)
	s_barrier
	v_mfma_f32_16x16x32_bf16 v[18:21], v[68:71], v[104:107], 0
	v_mfma_f32_16x16x32_bf16 v[30:33], v[68:71], v[112:115], 0
	v_mfma_f32_16x16x32_bf16 v[18:21], v[124:127], v[108:111], v[18:21]
	v_mfma_f32_16x16x32_bf16 v[30:33], v[124:127], v[116:119], v[30:33]
	v_mfma_f32_16x16x32_bf16 v[34:37], v[128:131], v[104:107], 0
	v_mfma_f32_16x16x32_bf16 v[124:127], v[136:139], v[104:107], 0
	v_mfma_f32_16x16x32_bf16 v[104:107], v[144:147], v[104:107], 0
	v_mfma_f32_16x16x32_bf16 v[34:37], v[132:135], v[108:111], v[34:37]
	v_mfma_f32_16x16x32_bf16 v[68:71], v[128:131], v[112:115], 0
	v_mfma_f32_16x16x32_bf16 v[124:127], v[140:143], v[108:111], v[124:127]
	v_mfma_f32_16x16x32_bf16 v[128:131], v[136:139], v[112:115], 0
	v_mfma_f32_16x16x32_bf16 v[104:107], v[148:151], v[108:111], v[104:107]
	v_mfma_f32_16x16x32_bf16 v[108:111], v[144:147], v[112:115], 0
	v_mfma_f32_16x16x32_bf16 v[68:71], v[132:135], v[116:119], v[68:71]
	v_mfma_f32_16x16x32_bf16 v[128:131], v[140:143], v[116:119], v[128:131]
	v_mfma_f32_16x16x32_bf16 v[108:111], v[148:151], v[116:119], v[108:111]
	v_or_b32_e32 v160, 0x18000, v162
	v_or_b32_e32 v238, 0x18800, v162
	s_barrier
	v_or_b32_e32 v161, 0x18400, v162
	ds_read_b128 v[112:115], v160
	ds_read_b128 v[116:119], v161
	v_or_b32_e32 v239, 0x18c00, v162
	ds_read_b128 v[132:135], v238
	ds_read_b128 v[136:139], v239
	v_readfirstlane_b32 s0, v16
	s_mov_b32 m0, s0
	v_readfirstlane_b32 s0, v17
	ds_read_b128 v[140:143], v242 offset:32768
	ds_read_b128 v[144:147], v242 offset:33792
	ds_read_b128 v[148:151], v242 offset:34816
	ds_read_b128 v[194:197], v242 offset:35840
	ds_read_b128 v[198:201], v242 offset:36864
	ds_read_b128 v[202:205], v242 offset:37888
	ds_read_b128 v[206:209], v242 offset:38912
	ds_read_b128 v[210:213], v242 offset:39936
	global_load_lds_dwordx4 v[214:215], off
	s_mov_b32 m0, s0
	s_nop 0
	global_load_lds_dwordx4 v[216:217], off
	s_waitcnt lgkmcnt(8)
	s_barrier
	s_waitcnt lgkmcnt(0)
	v_mfma_f32_16x16x32_bf16 v[14:17], v[140:143], v[112:115], v[72:75]
	v_mfma_f32_16x16x32_bf16 v[72:75], v[140:143], v[132:135], v[76:79]
	v_mfma_f32_16x16x32_bf16 v[76:79], v[148:151], v[112:115], v[80:83]
	v_mfma_f32_16x16x32_bf16 v[80:83], v[148:151], v[132:135], v[84:87]
	v_mfma_f32_16x16x32_bf16 v[84:87], v[198:201], v[112:115], v[88:91]
	v_mfma_f32_16x16x32_bf16 v[88:91], v[198:201], v[132:135], v[92:95]
	v_mfma_f32_16x16x32_bf16 v[92:95], v[206:209], v[112:115], v[96:99]
	v_mfma_f32_16x16x32_bf16 v[96:99], v[206:209], v[132:135], v[100:103]
	v_mfma_f32_16x16x32_bf16 v[14:17], v[144:147], v[116:119], v[14:17]
	v_mfma_f32_16x16x32_bf16 v[72:75], v[144:147], v[136:139], v[72:75]
	v_mfma_f32_16x16x32_bf16 v[76:79], v[194:197], v[116:119], v[76:79]
	v_mfma_f32_16x16x32_bf16 v[80:83], v[194:197], v[136:139], v[80:83]
	v_mfma_f32_16x16x32_bf16 v[84:87], v[202:205], v[116:119], v[84:87]
	v_mfma_f32_16x16x32_bf16 v[88:91], v[202:205], v[136:139], v[88:91]
	v_mfma_f32_16x16x32_bf16 v[92:95], v[210:213], v[116:119], v[92:95]
	v_mfma_f32_16x16x32_bf16 v[96:99], v[210:213], v[136:139], v[96:99]
	s_barrier
	v_or_b32_e32 v240, 0x1c000, v162
	v_or_b32_e32 v243, 0x1c800, v162
	s_mov_b32 m0, s37
	v_or_b32_e32 v241, 0x1c400, v162
	ds_read_b128 v[100:103], v240
	ds_read_b128 v[214:217], v241
	v_or_b32_e32 v162, 0x1cc00, v162
	ds_read_b128 v[218:221], v243
	ds_read_b128 v[222:225], v162
	global_load_lds_dwordx4 v[226:227], off
	s_mov_b32 m0, s40
	s_nop 0
	global_load_lds_dwordx4 v[228:229], off
	s_barrier
; #define G_LDA(dst, b, h)                                                                                                  \
;   _Pragma("unroll") for (int m = 0; m < 4; ++m) _Pragma("unroll") for (int k = 0; k < 2; ++k)                             \
;       dst[m][k] = *(const bf16x8*)((const char*)G_SA(b, h) + ((wr * 4 + m) * 2 + k) * 1024 + rdo)
; #define G_LDB(dst, b, h)                                                                                                  \
;   _Pragma("unroll") for (int n = 0; n < 2; ++n) _Pragma("unroll") for (int k = 0; k < 2; ++k)                             \
;       dst[n][k] = *(const bf16x8*)((const char*)G_SB(b, h) + ((wc * 2 + n) * 2 + k) * 1024 + rdo)
; #define G_WAIT_V(n) asm volatile("s_waitcnt vmcnt(" #n ")" ::: "memory")
; #define G_WAIT_L(n) asm volatile("s_waitcnt lgkmcnt(" #n ")" ::: "memory")
; #define G_BAR __builtin_amdgcn_s_barrier()
; #define G_SCHED __builtin_amdgcn_sched_barrier(0)
; DI void br_flush(PREF p, f32x4 (&acc)[2][2][4][2], int slot) { br_store(p, acc, slot); zero_acc256(acc); }
;     ...
;     G_LDA(At, 1, 1); G_STAGE(G_SA(1, 0), A, oa0, oa1, LDA, 0, KA(tt + 3));
;     G_BAR; G_WAIT_L(0); G_MMA(1, 0, At, B0); G_BAR; G_SCHED;
;     G_STAGE(G_SB(1, 1), B, ob0, ob1, LDB, 128, KB(tt + 3));
;     G_WAIT_V(6); G_BAR; G_MMA(1, 1, At, B1); G_BAR;
;     if (MODE && ((tt + 1) & 3) == 3) br_flush(p, acc, (tt + 1) >> 2);
;   }
;   {
;     G_LDB(B0, 0, 0); G_LDA(At, 0, 0); G_STAGE(G_SA(1, 1), A, oa0, oa1, LDA, 128, KA(nt - 1));
;     G_BAR; G_WAIT_L(0); G_MMA(0, 0, At, B0); G_BAR;
	s_waitcnt lgkmcnt(0)
	v_mfma_f32_16x16x32_bf16 v[120:123], v[140:143], v[100:103], v[120:123]
	v_mfma_f32_16x16x32_bf16 v[38:41], v[140:143], v[218:221], v[40:43]
	v_mfma_f32_16x16x32_bf16 v[42:45], v[148:151], v[100:103], v[44:47]
	v_mfma_f32_16x16x32_bf16 v[46:49], v[148:151], v[218:221], v[48:51]
	v_mfma_f32_16x16x32_bf16 v[50:53], v[198:201], v[100:103], v[52:55]
	v_mfma_f32_16x16x32_bf16 v[54:57], v[198:201], v[218:221], v[56:59]
	v_mfma_f32_16x16x32_bf16 v[58:61], v[206:209], v[100:103], v[60:63]
	v_mfma_f32_16x16x32_bf16 v[62:65], v[206:209], v[218:221], v[64:67]
	v_mfma_f32_16x16x32_bf16 v[120:123], v[144:147], v[214:217], v[120:123]
	v_mfma_f32_16x16x32_bf16 v[38:41], v[144:147], v[222:225], v[38:41]
	v_mfma_f32_16x16x32_bf16 v[42:45], v[194:197], v[214:217], v[42:45]
	v_mfma_f32_16x16x32_bf16 v[46:49], v[194:197], v[222:225], v[46:49]
	v_mfma_f32_16x16x32_bf16 v[50:53], v[202:205], v[214:217], v[50:53]
	v_mfma_f32_16x16x32_bf16 v[54:57], v[202:205], v[222:225], v[54:57]
	v_mfma_f32_16x16x32_bf16 v[58:61], v[210:213], v[214:217], v[58:61]
	v_mfma_f32_16x16x32_bf16 v[62:65], v[210:213], v[222:225], v[62:65]
	s_mov_b32 m0, s35
	s_barrier
	ds_read_b128 v[140:143], v242 offset:49152
	ds_read_b128 v[144:147], v242 offset:50176
	ds_read_b128 v[148:151], v242 offset:51200
	ds_read_b128 v[194:197], v242 offset:52224
	ds_read_b128 v[198:201], v242 offset:53248
	ds_read_b128 v[202:205], v242 offset:54272
	ds_read_b128 v[206:209], v242 offset:55296
	ds_read_b128 v[210:213], v242 offset:56320
	global_load_lds_dwordx4 v[12:13], off
	s_mov_b32 m0, s36
	s_nop 0
	global_load_lds_dwordx4 v[10:11], off
	s_barrier
	s_waitcnt lgkmcnt(0)
	v_mfma_f32_16x16x32_bf16 v[10:13], v[140:143], v[112:115], v[152:155]
	v_mfma_f32_16x16x32_bf16 v[22:25], v[206:209], v[112:115], v[22:25]
	v_mfma_f32_16x16x32_bf16 v[26:29], v[206:209], v[132:135], v[26:29]
	v_mfma_f32_16x16x32_bf16 v[10:13], v[144:147], v[116:119], v[10:13]
	v_mfma_f32_16x16x32_bf16 v[152:155], v[140:143], v[132:135], v[156:159]
	v_mfma_f32_16x16x32_bf16 v[156:159], v[148:151], v[112:115], v[164:167]
	v_mfma_f32_16x16x32_bf16 v[164:167], v[148:151], v[132:135], v[182:185]
	v_mfma_f32_16x16x32_bf16 v[182:185], v[198:201], v[112:115], v[186:189]
	v_mfma_f32_16x16x32_bf16 v[186:189], v[198:201], v[132:135], v[190:193]
	v_mfma_f32_16x16x32_bf16 v[22:25], v[210:213], v[116:119], v[22:25]
	v_mfma_f32_16x16x32_bf16 v[26:29], v[210:213], v[136:139], v[26:29]
	v_mfma_f32_16x16x32_bf16 v[152:155], v[144:147], v[136:139], v[152:155]
	v_mfma_f32_16x16x32_bf16 v[156:159], v[194:197], v[116:119], v[156:159]
	v_mfma_f32_16x16x32_bf16 v[164:167], v[194:197], v[136:139], v[164:167]
	v_mfma_f32_16x16x32_bf16 v[182:185], v[202:205], v[116:119], v[182:185]
	v_mfma_f32_16x16x32_bf16 v[186:189], v[202:205], v[136:139], v[186:189]
	s_barrier
	s_mov_b32 m0, s22
	s_nop 0
	global_load_lds_dwordx4 v[8:9], off
	s_mov_b32 m0, s23
	s_nop 0
	global_load_lds_dwordx4 v[6:7], off
	s_waitcnt vmcnt(6)
	s_barrier
	v_mfma_f32_16x16x32_bf16 v[6:9], v[140:143], v[100:103], v[18:21]
	v_mfma_f32_16x16x32_bf16 v[18:21], v[140:143], v[218:221], v[30:33]
	v_mfma_f32_16x16x32_bf16 v[30:33], v[148:151], v[100:103], v[34:37]
	v_mfma_f32_16x16x32_bf16 v[34:37], v[148:151], v[218:221], v[68:71]
	v_mfma_f32_16x16x32_bf16 v[66:69], v[198:201], v[100:103], v[124:127]
	v_mfma_f32_16x16x32_bf16 v[100:103], v[206:209], v[100:103], v[104:107]
	v_mfma_f32_16x16x32_bf16 v[104:107], v[206:209], v[218:221], v[108:111]
	v_mfma_f32_16x16x32_bf16 v[6:9], v[144:147], v[214:217], v[6:9]
	v_mfma_f32_16x16x32_bf16 v[18:21], v[144:147], v[222:225], v[18:21]
	v_mfma_f32_16x16x32_bf16 v[30:33], v[194:197], v[214:217], v[30:33]
	v_mfma_f32_16x16x32_bf16 v[34:37], v[194:197], v[222:225], v[34:37]
	v_mfma_f32_16x16x32_bf16 v[66:69], v[202:205], v[214:217], v[66:69]
	v_mfma_f32_16x16x32_bf16 v[112:115], v[198:201], v[218:221], v[128:131]
	v_mfma_f32_16x16x32_bf16 v[100:103], v[210:213], v[214:217], v[100:103]
	v_mfma_f32_16x16x32_bf16 v[104:107], v[210:213], v[222:225], v[104:107]
	v_mfma_f32_16x16x32_bf16 v[112:115], v[202:205], v[222:225], v[112:115]
	s_add_u32 s0, s20, 0x10180
	s_addc_u32 s1, s21, 0
	s_mov_b32 m0, s19
	v_lshl_add_u64 v[2:3], s[0:1], 0, v[2:3]
	s_barrier
	ds_read_b128 v[108:111], v230
	ds_read_b128 v[116:119], v231
	ds_read_b128 v[124:127], v232
	ds_read_b128 v[128:131], v233
	ds_read_b128 v[132:135], v242
	ds_read_b128 v[136:139], v242 offset:1024
	ds_read_b128 v[140:143], v242 offset:2048
	ds_read_b128 v[144:147], v242 offset:3072
	ds_read_b128 v[148:151], v242 offset:4096
	ds_read_b128 v[190:193], v242 offset:5120
	ds_read_b128 v[194:197], v242 offset:6144
	ds_read_b128 v[198:201], v242 offset:7168
	global_load_lds_dwordx4 v[2:3], off
	s_mov_b32 m0, s18
	v_lshl_add_u64 v[2:3], s[0:1], 0, v[4:5]
	global_load_lds_dwordx4 v[2:3], off
	s_barrier
	s_waitcnt lgkmcnt(0)
	v_mfma_f32_16x16x32_bf16 v[2:5], v[132:135], v[108:111], v[14:17]
	v_mfma_f32_16x16x32_bf16 v[14:17], v[132:135], v[124:127], v[72:75]
	v_mfma_f32_16x16x32_bf16 v[70:73], v[140:143], v[108:111], v[76:79]
	v_mfma_f32_16x16x32_bf16 v[74:77], v[140:143], v[124:127], v[80:83]
	v_mfma_f32_16x16x32_bf16 v[78:81], v[148:151], v[108:111], v[84:87]
	v_mfma_f32_16x16x32_bf16 v[82:85], v[148:151], v[124:127], v[88:91]
	v_mfma_f32_16x16x32_bf16 v[86:89], v[194:197], v[108:111], v[92:95]
	v_mfma_f32_16x16x32_bf16 v[90:93], v[194:197], v[124:127], v[96:99]
	v_mfma_f32_16x16x32_bf16 v[2:5], v[136:139], v[116:119], v[2:5]
	v_mfma_f32_16x16x32_bf16 v[14:17], v[136:139], v[128:131], v[14:17]
	v_mfma_f32_16x16x32_bf16 v[70:73], v[144:147], v[116:119], v[70:73]
	v_mfma_f32_16x16x32_bf16 v[74:77], v[144:147], v[128:131], v[74:77]
	v_mfma_f32_16x16x32_bf16 v[78:81], v[190:193], v[116:119], v[78:81]
	v_mfma_f32_16x16x32_bf16 v[82:85], v[190:193], v[128:131], v[82:85]
	v_mfma_f32_16x16x32_bf16 v[86:89], v[198:201], v[116:119], v[86:89]
	v_mfma_f32_16x16x32_bf16 v[90:93], v[198:201], v[128:131], v[90:93]
	s_barrier
; #define G_LDA(dst, b, h)                                                                                                  \
;   _Pragma("unroll") for (int m = 0; m < 4; ++m) _Pragma("unroll") for (int k = 0; k < 2; ++k)                             \
;       dst[m][k] = *(const bf16x8*)((const char*)G_SA(b, h) + ((wr * 4 + m) * 2 + k) * 1024 + rdo)
; #define G_LDB(dst, b, h)                                                                                                  \
;   _Pragma("unroll") for (int n = 0; n < 2; ++n) _Pragma("unroll") for (int k = 0; k < 2; ++k)                             \
;       dst[n][k] = *(const bf16x8*)((const char*)G_SB(b, h) + ((wc * 2 + n) * 2 + k) * 1024 + rdo)
; #define G_WAIT_V(n) asm volatile("s_waitcnt vmcnt(" #n ")" ::: "memory")
; #define G_WAIT_L(n) asm volatile("s_waitcnt lgkmcnt(" #n ")" ::: "memory")
; #define G_BAR __builtin_amdgcn_s_barrier()
;     ...
;     G_LDB(B1, 0, 1); G_BAR; G_WAIT_L(0); G_MMA(0, 1, At, B1); G_BAR;
;     G_LDA(At, 0, 1); G_WAIT_V(4); G_BAR; G_WAIT_L(0); G_MMA(1, 0, At, B0); G_MMA(1, 1, At, B1); G_BAR;
;   }
;   {
;     G_LDB(B0, 1, 0); G_LDA(At, 1, 0); G_WAIT_V(2); G_BAR; G_WAIT_L(0); G_MMA(0, 0, At, B0); G_BAR;
	ds_read_b128 v[94:97], v234
	ds_read_b128 v[202:205], v235
	ds_read_b128 v[206:209], v236
	ds_read_b128 v[210:213], v237
	s_barrier
	s_waitcnt lgkmcnt(0)
	v_mfma_f32_16x16x32_bf16 v[38:41], v[132:135], v[206:209], v[38:41]
	v_mfma_f32_16x16x32_bf16 v[42:45], v[140:143], v[94:97], v[42:45]
	v_mfma_f32_16x16x32_bf16 v[46:49], v[140:143], v[206:209], v[46:49]
	v_mfma_f32_16x16x32_bf16 v[50:53], v[148:151], v[94:97], v[50:53]
	v_mfma_f32_16x16x32_bf16 v[54:57], v[148:151], v[206:209], v[54:57]
	v_mfma_f32_16x16x32_bf16 v[58:61], v[194:197], v[94:97], v[58:61]
	v_mfma_f32_16x16x32_bf16 v[62:65], v[194:197], v[206:209], v[62:65]
	v_mfma_f32_16x16x32_bf16 v[120:123], v[132:135], v[94:97], v[120:123]
	v_mfma_f32_16x16x32_bf16 v[38:41], v[136:139], v[210:213], v[38:41]
	v_mfma_f32_16x16x32_bf16 v[42:45], v[144:147], v[202:205], v[42:45]
	v_mfma_f32_16x16x32_bf16 v[46:49], v[144:147], v[210:213], v[46:49]
	v_mfma_f32_16x16x32_bf16 v[50:53], v[190:193], v[202:205], v[50:53]
	v_mfma_f32_16x16x32_bf16 v[54:57], v[190:193], v[210:213], v[54:57]
	v_mfma_f32_16x16x32_bf16 v[58:61], v[198:201], v[202:205], v[58:61]
	v_mfma_f32_16x16x32_bf16 v[62:65], v[198:201], v[210:213], v[62:65]
	v_mfma_f32_16x16x32_bf16 v[214:217], v[136:139], v[202:205], v[120:123]
	s_barrier
	s_nop 0
	ds_read_b128 v[120:123], v242 offset:16384
	ds_read_b128 v[132:135], v242 offset:17408
	ds_read_b128 v[136:139], v242 offset:18432
	ds_read_b128 v[140:143], v242 offset:19456
	ds_read_b128 v[144:147], v242 offset:20480
	ds_read_b128 v[148:151], v242 offset:21504
	ds_read_b128 v[190:193], v242 offset:22528
	ds_read_b128 v[194:197], v242 offset:23552
	s_waitcnt vmcnt(4)
	s_barrier
	s_waitcnt lgkmcnt(0)
	v_mfma_f32_16x16x32_bf16 v[10:13], v[120:123], v[108:111], v[10:13]
	v_mfma_f32_16x16x32_bf16 v[22:25], v[190:193], v[108:111], v[22:25]
	v_mfma_f32_16x16x32_bf16 v[26:29], v[190:193], v[124:127], v[26:29]
	v_mfma_f32_16x16x32_bf16 v[10:13], v[132:135], v[116:119], v[10:13]
	v_mfma_f32_16x16x32_bf16 v[152:155], v[120:123], v[124:127], v[152:155]
	v_mfma_f32_16x16x32_bf16 v[156:159], v[136:139], v[108:111], v[156:159]
	v_mfma_f32_16x16x32_bf16 v[164:167], v[136:139], v[124:127], v[164:167]
	v_mfma_f32_16x16x32_bf16 v[182:185], v[144:147], v[108:111], v[182:185]
	v_mfma_f32_16x16x32_bf16 v[186:189], v[144:147], v[124:127], v[186:189]
	v_mfma_f32_16x16x32_bf16 v[22:25], v[194:197], v[116:119], v[22:25]
	v_mfma_f32_16x16x32_bf16 v[26:29], v[194:197], v[128:131], v[26:29]
	v_mfma_f32_16x16x32_bf16 v[152:155], v[132:135], v[128:131], v[152:155]
	v_mfma_f32_16x16x32_bf16 v[156:159], v[140:143], v[116:119], v[156:159]
	v_mfma_f32_16x16x32_bf16 v[164:167], v[140:143], v[128:131], v[164:167]
	v_mfma_f32_16x16x32_bf16 v[182:185], v[148:151], v[116:119], v[182:185]
	v_mfma_f32_16x16x32_bf16 v[186:189], v[148:151], v[128:131], v[186:189]
	v_mfma_f32_16x16x32_bf16 v[30:33], v[136:139], v[94:97], v[30:33]
	v_mfma_f32_16x16x32_bf16 v[126:129], v[140:143], v[202:205], v[30:33]
	v_mfma_f32_16x16x32_bf16 v[30:33], v[136:139], v[206:209], v[34:37]
	v_mfma_f32_16x16x32_bf16 v[198:201], v[140:143], v[210:213], v[30:33]
	v_mfma_f32_16x16x32_bf16 v[30:33], v[144:147], v[94:97], v[66:69]
	v_mfma_f32_16x16x32_bf16 v[218:221], v[148:151], v[202:205], v[30:33]
	v_mfma_f32_16x16x32_bf16 v[30:33], v[144:147], v[206:209], v[112:115]
	v_mfma_f32_16x16x32_bf16 v[6:9], v[120:123], v[94:97], v[6:9]
	v_mfma_f32_16x16x32_bf16 v[18:21], v[120:123], v[206:209], v[18:21]
	v_mfma_f32_16x16x32_bf16 v[110:113], v[148:151], v[210:213], v[30:33]
	v_mfma_f32_16x16x32_bf16 v[30:33], v[190:193], v[94:97], v[100:103]
	v_mfma_f32_16x16x32_bf16 v[6:9], v[132:135], v[202:205], v[6:9]
	v_mfma_f32_16x16x32_bf16 v[18:21], v[132:135], v[210:213], v[18:21]
	v_mfma_f32_16x16x32_bf16 v[114:117], v[194:197], v[202:205], v[30:33]
	v_mfma_f32_16x16x32_bf16 v[30:33], v[190:193], v[206:209], v[104:107]
	v_mfma_f32_16x16x32_bf16 v[102:105], v[194:197], v[210:213], v[30:33]
	s_barrier
	s_nop 4
	s_nop 0
	ds_read_b128 v[30:33], v160
	ds_read_b128 v[34:37], v161
	ds_read_b128 v[146:149], v238
	ds_read_b128 v[190:193], v239
	ds_read_b128 v[66:69], v242 offset:32768
	ds_read_b128 v[94:97], v242 offset:33792
	ds_read_b128 v[194:197], v242 offset:34816
	ds_read_b128 v[202:205], v242 offset:35840
	ds_read_b128 v[206:209], v242 offset:36864
	ds_read_b128 v[210:213], v242 offset:37888
	ds_read_b128 v[222:225], v242 offset:38912
	ds_read_b128 v[226:229], v242 offset:39936
	s_waitcnt vmcnt(2)
	s_barrier
; #define G_LDA(dst, b, h)                                                                                                  \
;   _Pragma("unroll") for (int m = 0; m < 4; ++m) _Pragma("unroll") for (int k = 0; k < 2; ++k)                             \
;       dst[m][k] = *(const bf16x8*)((const char*)G_SA(b, h) + ((wr * 4 + m) * 2 + k) * 1024 + rdo)
; #define G_LDB(dst, b, h)                                                                                                  \
;   _Pragma("unroll") for (int n = 0; n < 2; ++n) _Pragma("unroll") for (int k = 0; k < 2; ++k)                             \
;       dst[n][k] = *(const bf16x8*)((const char*)G_SB(b, h) + ((wc * 2 + n) * 2 + k) * 1024 + rdo)
; #define G_WAIT_V(n) asm volatile("s_waitcnt vmcnt(" #n ")" ::: "memory")
; #define G_WAIT_L(n) asm volatile("s_waitcnt lgkmcnt(" #n ")" ::: "memory")
; #define G_BAR __builtin_amdgcn_s_barrier()
;     ...
;     G_LDB(B0, 1, 0); G_LDA(At, 1, 0); G_WAIT_V(2); G_BAR; G_WAIT_L(0); G_MMA(0, 0, At, B0); G_BAR;
;     G_LDB(B1, 1, 1); G_WAIT_V(0); G_BAR; G_WAIT_L(0); G_MMA(0, 1, At, B1); G_BAR;
;     G_LDA(At, 1, 1); G_BAR; G_WAIT_L(0); G_MMA(1, 0, At, B0); G_MMA(1, 1, At, B1); G_BAR;
;   }
;   if (wr == 0) G_BAR;
	s_waitcnt lgkmcnt(0)
	v_mfma_f32_16x16x32_bf16 v[2:5], v[66:69], v[30:33], v[2:5]
	v_mfma_f32_16x16x32_bf16 v[134:137], v[94:97], v[34:37], v[2:5]
	v_mfma_f32_16x16x32_bf16 v[2:5], v[66:69], v[146:149], v[14:17]
	v_mfma_f32_16x16x32_bf16 v[142:145], v[94:97], v[190:193], v[2:5]
	v_mfma_f32_16x16x32_bf16 v[2:5], v[194:197], v[30:33], v[70:73]
	v_mfma_f32_16x16x32_bf16 v[130:133], v[202:205], v[34:37], v[2:5]
	v_mfma_f32_16x16x32_bf16 v[2:5], v[194:197], v[146:149], v[74:77]
	v_mfma_f32_16x16x32_bf16 v[138:141], v[202:205], v[190:193], v[2:5]
	v_mfma_f32_16x16x32_bf16 v[2:5], v[206:209], v[30:33], v[78:81]
	v_mfma_f32_16x16x32_bf16 v[118:121], v[210:213], v[34:37], v[2:5]
	v_mfma_f32_16x16x32_bf16 v[2:5], v[206:209], v[146:149], v[82:85]
	v_mfma_f32_16x16x32_bf16 v[122:125], v[210:213], v[190:193], v[2:5]
	v_mfma_f32_16x16x32_bf16 v[2:5], v[222:225], v[30:33], v[86:89]
	v_mfma_f32_16x16x32_bf16 v[98:101], v[226:229], v[34:37], v[2:5]
	v_mfma_f32_16x16x32_bf16 v[2:5], v[222:225], v[146:149], v[90:93]
	v_mfma_f32_16x16x32_bf16 v[106:109], v[226:229], v[190:193], v[2:5]
	s_barrier
	s_nop 4
	s_nop 0
	ds_read_b128 v[2:5], v240
	ds_read_b128 v[230:233], v241
	ds_read_b128 v[234:237], v243
	ds_read_b128 v[238:241], v162
	s_waitcnt vmcnt(0)
	s_barrier
	s_waitcnt lgkmcnt(0)
	v_mfma_f32_16x16x32_bf16 v[14:17], v[66:69], v[2:5], v[214:217]
	v_mfma_f32_16x16x32_bf16 v[86:89], v[94:97], v[230:233], v[14:17]
	v_mfma_f32_16x16x32_bf16 v[14:17], v[66:69], v[234:237], v[38:41]
	v_mfma_f32_16x16x32_bf16 v[94:97], v[94:97], v[238:241], v[14:17]
	v_mfma_f32_16x16x32_bf16 v[14:17], v[194:197], v[2:5], v[42:45]
	v_mfma_f32_16x16x32_bf16 v[82:85], v[202:205], v[230:233], v[14:17]
	v_mfma_f32_16x16x32_bf16 v[14:17], v[194:197], v[234:237], v[46:49]
	v_mfma_f32_16x16x32_bf16 v[90:93], v[202:205], v[238:241], v[14:17]
	v_mfma_f32_16x16x32_bf16 v[14:17], v[206:209], v[2:5], v[50:53]
	v_mfma_f32_16x16x32_bf16 v[74:77], v[210:213], v[230:233], v[14:17]
	v_mfma_f32_16x16x32_bf16 v[14:17], v[206:209], v[234:237], v[54:57]
	v_mfma_f32_16x16x32_bf16 v[78:81], v[210:213], v[238:241], v[14:17]
	v_mfma_f32_16x16x32_bf16 v[14:17], v[222:225], v[2:5], v[58:61]
	v_mfma_f32_16x16x32_bf16 v[66:69], v[226:229], v[230:233], v[14:17]
	v_mfma_f32_16x16x32_bf16 v[14:17], v[222:225], v[234:237], v[62:65]
	v_mfma_f32_16x16x32_bf16 v[70:73], v[226:229], v[238:241], v[14:17]
	s_barrier
	s_nop 4
	s_nop 0
	ds_read_b128 v[14:17], v242 offset:49152
	ds_read_b128 v[194:197], v242 offset:50176
	ds_read_b128 v[202:205], v242 offset:51200
	ds_read_b128 v[206:209], v242 offset:52224
	ds_read_b128 v[210:213], v242 offset:53248
	ds_read_b128 v[214:217], v242 offset:54272
	ds_read_b128 v[222:225], v242 offset:55296
	ds_read_b128 v[226:229], v242 offset:56320
	s_barrier
	s_waitcnt lgkmcnt(0)
	v_mfma_f32_16x16x32_bf16 v[10:13], v[14:17], v[30:33], v[10:13]
	v_mfma_f32_16x16x32_bf16 v[54:57], v[194:197], v[34:37], v[10:13]
	v_mfma_f32_16x16x32_bf16 v[10:13], v[14:17], v[146:149], v[152:155]
	v_mfma_f32_16x16x32_bf16 v[62:65], v[194:197], v[190:193], v[10:13]
	v_mfma_f32_16x16x32_bf16 v[10:13], v[202:205], v[30:33], v[156:159]
	v_mfma_f32_16x16x32_bf16 v[50:53], v[206:209], v[34:37], v[10:13]
	v_mfma_f32_16x16x32_bf16 v[10:13], v[202:205], v[146:149], v[164:167]
	v_mfma_f32_16x16x32_bf16 v[58:61], v[206:209], v[190:193], v[10:13]
	v_mfma_f32_16x16x32_bf16 v[10:13], v[210:213], v[30:33], v[182:185]
	v_mfma_f32_16x16x32_bf16 v[42:45], v[214:217], v[34:37], v[10:13]
	v_mfma_f32_16x16x32_bf16 v[10:13], v[210:213], v[146:149], v[186:189]
	v_mfma_f32_16x16x32_bf16 v[46:49], v[214:217], v[190:193], v[10:13]
	v_mfma_f32_16x16x32_bf16 v[10:13], v[222:225], v[30:33], v[22:25]
	v_mfma_f32_16x16x32_bf16 v[34:37], v[226:229], v[34:37], v[10:13]
	v_mfma_f32_16x16x32_bf16 v[10:13], v[222:225], v[146:149], v[26:29]
	v_mfma_f32_16x16x32_bf16 v[38:41], v[226:229], v[190:193], v[10:13]
	v_mfma_f32_16x16x32_bf16 v[6:9], v[14:17], v[2:5], v[6:9]
	v_mfma_f32_16x16x32_bf16 v[22:25], v[194:197], v[230:233], v[6:9]
	v_mfma_f32_16x16x32_bf16 v[6:9], v[14:17], v[234:237], v[18:21]
	v_mfma_f32_16x16x32_bf16 v[30:33], v[194:197], v[238:241], v[6:9]
	v_mfma_f32_16x16x32_bf16 v[6:9], v[202:205], v[2:5], v[126:129]
	v_mfma_f32_16x16x32_bf16 v[18:21], v[206:209], v[230:233], v[6:9]
	v_mfma_f32_16x16x32_bf16 v[6:9], v[202:205], v[234:237], v[198:201]
	v_mfma_f32_16x16x32_bf16 v[26:29], v[206:209], v[238:241], v[6:9]
	v_mfma_f32_16x16x32_bf16 v[6:9], v[210:213], v[2:5], v[218:221]
	v_mfma_f32_16x16x32_bf16 v[10:13], v[214:217], v[230:233], v[6:9]
	v_mfma_f32_16x16x32_bf16 v[6:9], v[210:213], v[234:237], v[110:113]
	v_mfma_f32_16x16x32_bf16 v[14:17], v[214:217], v[238:241], v[6:9]
	v_mfma_f32_16x16x32_bf16 v[2:5], v[222:225], v[2:5], v[114:117]
	v_mfma_f32_16x16x32_bf16 v[6:9], v[222:225], v[234:237], v[102:105]
	v_mfma_f32_16x16x32_bf16 v[2:5], v[226:229], v[230:233], v[2:5]
	v_mfma_f32_16x16x32_bf16 v[6:9], v[226:229], v[238:241], v[6:9]
	v_cmp_gt_u32_e32 vcc, s67, v0
	s_barrier
	s_and_saveexec_b64 s[18:19], vcc
	s_cbranch_execz .LBB0_36
	s_barrier
	s_branch .LBB0_36

; #define G_LDA(dst, b, h)                                                                                                  \
;   _Pragma("unroll") for (int m = 0; m < 4; ++m) _Pragma("unroll") for (int k = 0; k < 2; ++k)                             \
;       dst[m][k] = *(const bf16x8*)((const char*)G_SA(b, h) + ((wr * 4 + m) * 2 + k) * 1024 + rdo)
; #define G_LDB(dst, b, h)                                                                                                  \
;   _Pragma("unroll") for (int n = 0; n < 2; ++n) _Pragma("unroll") for (int k = 0; k < 2; ++k)                             \
;       dst[n][k] = *(const bf16x8*)((const char*)G_SB(b, h) + ((wc * 2 + n) * 2 + k) * 1024 + rdo)
; #define G_WAIT_L(n) asm volatile("s_waitcnt lgkmcnt(" #n ")" ::: "memory")
; #define G_BAR __builtin_amdgcn_s_barrier()
; #define G_SCHED __builtin_amdgcn_sched_barrier(0)
;     ...
;     G_LDB(B0, 0, 0); G_SCHED; G_LDA(At, 0, 0); G_STAGE(G_SA(1, 1), A, oa0, oa1, LDA, 128, KA(tt + 1));
;     G_WAIT_L(8); G_BAR; G_WAIT_L(0); G_MMA(0, 0, At, B0); G_BAR; G_SCHED;
;     G_LDB(B1, 0, 1); G_STAGE(G_SB(0, 0), B, ob0, ob1, LDB, 0, KB(tt + 2));
;     G_BAR; G_WAIT_L(0); G_MMA(0, 1, At, B1); G_BAR;
;     G_LDA(At, 0, 1); G_STAGE(G_SA(0, 0), A, oa0, oa1, LDA, 0, KA(tt + 2));
;     G_BAR; G_WAIT_L(0); G_MMA(1, 0, At, B0); G_BAR; G_SCHED;
.LBB0_66:
	ds_read_b128 v[164:167], v160
	ds_read_b128 v[182:185], v160 offset:1024
	ds_read_b128 v[186:189], v160 offset:2048
	ds_read_b128 v[190:193], v160 offset:3072
	v_add_u32_e32 v161, 0xc000, v143
	v_lshl_add_u64 v[242:243], v[136:137], 0, s[22:23]
	v_readfirstlane_b32 s0, v161
	v_add_u32_e32 v162, 0xe000, v143
	v_lshl_add_u64 v[226:227], v[242:243], 0, s[78:79]
	s_mov_b32 m0, s0
	v_lshl_add_u64 v[244:245], v[134:135], 0, s[22:23]
	v_readfirstlane_b32 s0, v162
	ds_read_b128 v[194:197], v142
	ds_read_b128 v[198:201], v142 offset:1024
	ds_read_b128 v[202:205], v142 offset:2048
	ds_read_b128 v[206:209], v142 offset:3072
	ds_read_b128 v[210:213], v142 offset:4096
	ds_read_b128 v[214:217], v142 offset:5120
	ds_read_b128 v[218:221], v142 offset:6144
	ds_read_b128 v[222:225], v142 offset:7168
	global_load_lds_dwordx4 v[226:227], off
	s_mov_b32 m0, s0
	v_lshl_add_u64 v[226:227], v[244:245], 0, s[78:79]
	global_load_lds_dwordx4 v[226:227], off
	s_waitcnt lgkmcnt(8)
	s_barrier
	s_waitcnt lgkmcnt(0)
	v_mfma_f32_16x16x32_bf16 v[126:129], v[194:197], v[164:167], v[126:129]
	v_mfma_f32_16x16x32_bf16 v[122:125], v[194:197], v[186:189], v[122:125]
	v_mfma_f32_16x16x32_bf16 v[118:121], v[202:205], v[164:167], v[118:121]
	v_mfma_f32_16x16x32_bf16 v[114:117], v[202:205], v[186:189], v[114:117]
	v_mfma_f32_16x16x32_bf16 v[110:113], v[210:213], v[164:167], v[110:113]
	v_mfma_f32_16x16x32_bf16 v[106:109], v[210:213], v[186:189], v[106:109]
	v_mfma_f32_16x16x32_bf16 v[102:105], v[218:221], v[164:167], v[102:105]
	v_mfma_f32_16x16x32_bf16 v[98:101], v[218:221], v[186:189], v[98:101]
	v_mfma_f32_16x16x32_bf16 v[126:129], v[198:201], v[182:185], v[126:129]
	v_mfma_f32_16x16x32_bf16 v[122:125], v[198:201], v[190:193], v[122:125]
	v_mfma_f32_16x16x32_bf16 v[118:121], v[206:209], v[182:185], v[118:121]
	v_mfma_f32_16x16x32_bf16 v[114:117], v[206:209], v[190:193], v[114:117]
	v_mfma_f32_16x16x32_bf16 v[110:113], v[214:217], v[182:185], v[110:113]
	v_mfma_f32_16x16x32_bf16 v[106:109], v[214:217], v[190:193], v[106:109]
	v_mfma_f32_16x16x32_bf16 v[102:105], v[222:225], v[182:185], v[102:105]
	v_mfma_f32_16x16x32_bf16 v[98:101], v[222:225], v[190:193], v[98:101]
	s_barrier
	v_lshl_add_u64 v[246:247], v[140:141], 0, s[22:23]
	v_readfirstlane_b32 s0, v146
	v_lshl_add_u64 v[248:249], v[246:247], 0, s[48:49]
	s_mov_b32 m0, s0
	ds_read_b128 v[226:229], v158
	ds_read_b128 v[230:233], v158 offset:1024
	ds_read_b128 v[234:237], v158 offset:2048
	ds_read_b128 v[238:241], v158 offset:3072
	global_load_lds_dwordx4 v[248:249], off
	v_lshl_add_u64 v[248:249], v[138:139], 0, s[22:23]
	v_readfirstlane_b32 s0, v147
	s_mov_b32 m0, s0
	v_lshl_add_u64 v[250:251], v[248:249], 0, s[48:49]
	global_load_lds_dwordx4 v[250:251], off
	s_barrier
	s_waitcnt lgkmcnt(0)
	v_mfma_f32_16x16x32_bf16 v[94:97], v[194:197], v[226:229], v[94:97]
	v_mfma_f32_16x16x32_bf16 v[90:93], v[194:197], v[234:237], v[90:93]
	v_mfma_f32_16x16x32_bf16 v[86:89], v[202:205], v[226:229], v[86:89]
	v_mfma_f32_16x16x32_bf16 v[82:85], v[202:205], v[234:237], v[82:85]
	v_mfma_f32_16x16x32_bf16 v[78:81], v[210:213], v[226:229], v[78:81]
	v_mfma_f32_16x16x32_bf16 v[74:77], v[210:213], v[234:237], v[74:77]
	v_mfma_f32_16x16x32_bf16 v[70:73], v[218:221], v[226:229], v[70:73]
	v_mfma_f32_16x16x32_bf16 v[66:69], v[218:221], v[234:237], v[66:69]
	v_mfma_f32_16x16x32_bf16 v[94:97], v[198:201], v[230:233], v[94:97]
	v_mfma_f32_16x16x32_bf16 v[90:93], v[198:201], v[238:241], v[90:93]
	v_mfma_f32_16x16x32_bf16 v[86:89], v[206:209], v[230:233], v[86:89]
	v_mfma_f32_16x16x32_bf16 v[82:85], v[206:209], v[238:241], v[82:85]
	v_mfma_f32_16x16x32_bf16 v[78:81], v[214:217], v[230:233], v[78:81]
	v_mfma_f32_16x16x32_bf16 v[74:77], v[214:217], v[238:241], v[74:77]
	v_mfma_f32_16x16x32_bf16 v[70:73], v[222:225], v[230:233], v[70:73]
	v_mfma_f32_16x16x32_bf16 v[66:69], v[222:225], v[238:241], v[66:69]
	v_readfirstlane_b32 s0, v143
	v_lshl_add_u64 v[250:251], v[242:243], 0, s[82:83]
	s_mov_b32 m0, s0
	v_readfirstlane_b32 s0, v144
	s_barrier
	ds_read_b128 v[194:197], v142 offset:16384
	ds_read_b128 v[198:201], v142 offset:17408
	ds_read_b128 v[202:205], v142 offset:18432
	ds_read_b128 v[206:209], v142 offset:19456
	ds_read_b128 v[210:213], v142 offset:20480
	ds_read_b128 v[214:217], v142 offset:21504
	ds_read_b128 v[218:221], v142 offset:22528
	ds_read_b128 v[222:225], v142 offset:23552
	global_load_lds_dwordx4 v[250:251], off
	s_mov_b32 m0, s0
	v_lshl_add_u64 v[250:251], v[244:245], 0, s[82:83]
	global_load_lds_dwordx4 v[250:251], off
	s_barrier
	s_waitcnt lgkmcnt(0)
	v_mfma_f32_16x16x32_bf16 v[62:65], v[194:197], v[164:167], v[62:65]
	v_mfma_f32_16x16x32_bf16 v[58:61], v[194:197], v[186:189], v[58:61]
	v_mfma_f32_16x16x32_bf16 v[54:57], v[202:205], v[164:167], v[54:57]
	v_mfma_f32_16x16x32_bf16 v[50:53], v[202:205], v[186:189], v[50:53]
	v_mfma_f32_16x16x32_bf16 v[46:49], v[210:213], v[164:167], v[46:49]
	v_mfma_f32_16x16x32_bf16 v[42:45], v[210:213], v[186:189], v[42:45]
	v_mfma_f32_16x16x32_bf16 v[38:41], v[218:221], v[164:167], v[38:41]
	v_mfma_f32_16x16x32_bf16 v[34:37], v[218:221], v[186:189], v[34:37]
	v_mfma_f32_16x16x32_bf16 v[62:65], v[198:201], v[182:185], v[62:65]
	v_mfma_f32_16x16x32_bf16 v[58:61], v[198:201], v[190:193], v[58:61]
	v_mfma_f32_16x16x32_bf16 v[54:57], v[206:209], v[182:185], v[54:57]
	v_mfma_f32_16x16x32_bf16 v[50:53], v[206:209], v[190:193], v[50:53]
	v_mfma_f32_16x16x32_bf16 v[46:49], v[214:217], v[182:185], v[46:49]
	v_mfma_f32_16x16x32_bf16 v[42:45], v[214:217], v[190:193], v[42:45]
	v_mfma_f32_16x16x32_bf16 v[38:41], v[222:225], v[182:185], v[38:41]
	v_mfma_f32_16x16x32_bf16 v[34:37], v[222:225], v[190:193], v[34:37]
	s_barrier
; #define G_LDA(dst, b, h)                                                                                                  \
;   _Pragma("unroll") for (int m = 0; m < 4; ++m) _Pragma("unroll") for (int k = 0; k < 2; ++k)                             \
;       dst[m][k] = *(const bf16x8*)((const char*)G_SA(b, h) + ((wr * 4 + m) * 2 + k) * 1024 + rdo)
; #define G_LDB(dst, b, h)                                                                                                  \
;   _Pragma("unroll") for (int n = 0; n < 2; ++n) _Pragma("unroll") for (int k = 0; k < 2; ++k)                             \
;       dst[n][k] = *(const bf16x8*)((const char*)G_SB(b, h) + ((wc * 2 + n) * 2 + k) * 1024 + rdo)
; #define G_WAIT_V(n) asm volatile("s_waitcnt vmcnt(" #n ")" ::: "memory")
; #define G_WAIT_L(n) asm volatile("s_waitcnt lgkmcnt(" #n ")" ::: "memory")
; #define G_BAR __builtin_amdgcn_s_barrier()
; #define G_SCHED __builtin_amdgcn_sched_barrier(0)
;     ...
;     G_STAGE(G_SB(0, 1), B, ob0, ob1, LDB, 128, KB(tt + 2));
;     G_WAIT_V(6); G_BAR; G_MMA(1, 1, At, B1); G_BAR;
;     G_LDB(B0, 1, 0); G_SCHED; G_LDA(At, 1, 0); G_STAGE(G_SA(0, 1), A, oa0, oa1, LDA, 128, KA(tt + 2));
;     G_WAIT_L(8); G_BAR; G_WAIT_L(0); G_MMA(0, 0, At, B0); G_BAR; G_SCHED;
;     G_LDB(B1, 1, 1); G_STAGE(G_SB(1, 0), B, ob0, ob1, LDB, 0, KB(tt + 3));
;     G_BAR; G_WAIT_L(0); G_MMA(0, 1, At, B1); G_BAR;
;     G_LDA(At, 1, 1); G_STAGE(G_SA(1, 0), A, oa0, oa1, LDA, 0, KA(tt + 3));
	v_readfirstlane_b32 s0, v148
	v_lshl_add_u64 v[164:165], v[246:247], 0, s[24:25]
	s_mov_b32 m0, s0
	v_readfirstlane_b32 s0, v150
	global_load_lds_dwordx4 v[164:165], off
	s_mov_b32 m0, s0
	v_lshl_add_u64 v[164:165], v[248:249], 0, s[24:25]
	global_load_lds_dwordx4 v[164:165], off
	s_waitcnt vmcnt(6)
	s_barrier
	v_mfma_f32_16x16x32_bf16 v[30:33], v[194:197], v[226:229], v[30:33]
	v_mfma_f32_16x16x32_bf16 v[26:29], v[194:197], v[234:237], v[26:29]
	v_mfma_f32_16x16x32_bf16 v[22:25], v[202:205], v[226:229], v[22:25]
	v_mfma_f32_16x16x32_bf16 v[18:21], v[202:205], v[234:237], v[18:21]
	v_mfma_f32_16x16x32_bf16 v[14:17], v[210:213], v[226:229], v[14:17]
	v_mfma_f32_16x16x32_bf16 v[10:13], v[210:213], v[234:237], v[10:13]
	v_mfma_f32_16x16x32_bf16 v[6:9], v[218:221], v[226:229], v[6:9]
	v_mfma_f32_16x16x32_bf16 v[2:5], v[218:221], v[234:237], v[2:5]
	v_mfma_f32_16x16x32_bf16 v[30:33], v[198:201], v[230:233], v[30:33]
	v_mfma_f32_16x16x32_bf16 v[26:29], v[198:201], v[238:241], v[26:29]
	v_mfma_f32_16x16x32_bf16 v[22:25], v[206:209], v[230:233], v[22:25]
	v_mfma_f32_16x16x32_bf16 v[18:21], v[206:209], v[238:241], v[18:21]
	v_mfma_f32_16x16x32_bf16 v[14:17], v[214:217], v[230:233], v[14:17]
	v_mfma_f32_16x16x32_bf16 v[10:13], v[214:217], v[238:241], v[10:13]
	v_mfma_f32_16x16x32_bf16 v[6:9], v[222:225], v[230:233], v[6:9]
	v_mfma_f32_16x16x32_bf16 v[2:5], v[222:225], v[238:241], v[2:5]
	s_barrier
	ds_read_b128 v[164:167], v149
	ds_read_b128 v[182:185], v149 offset:1024
	ds_read_b128 v[186:189], v149 offset:2048
	ds_read_b128 v[190:193], v149 offset:3072
	v_readfirstlane_b32 s0, v151
	v_lshl_add_u64 v[226:227], v[242:243], 0, s[86:87]
	s_mov_b32 m0, s0
	v_readfirstlane_b32 s0, v152
	ds_read_b128 v[194:197], v142 offset:32768
	ds_read_b128 v[198:201], v142 offset:33792
	ds_read_b128 v[202:205], v142 offset:34816
	ds_read_b128 v[206:209], v142 offset:35840
	ds_read_b128 v[210:213], v142 offset:36864
	ds_read_b128 v[214:217], v142 offset:37888
	ds_read_b128 v[218:221], v142 offset:38912
	ds_read_b128 v[222:225], v142 offset:39936
	global_load_lds_dwordx4 v[226:227], off
	s_mov_b32 m0, s0
	v_lshl_add_u64 v[226:227], v[244:245], 0, s[86:87]
	global_load_lds_dwordx4 v[226:227], off
	s_waitcnt lgkmcnt(8)
	s_barrier
	s_waitcnt lgkmcnt(0)
	v_mfma_f32_16x16x32_bf16 v[126:129], v[194:197], v[164:167], v[126:129]
	v_mfma_f32_16x16x32_bf16 v[122:125], v[194:197], v[186:189], v[122:125]
	v_mfma_f32_16x16x32_bf16 v[118:121], v[202:205], v[164:167], v[118:121]
	v_mfma_f32_16x16x32_bf16 v[114:117], v[202:205], v[186:189], v[114:117]
	v_mfma_f32_16x16x32_bf16 v[110:113], v[210:213], v[164:167], v[110:113]
	v_mfma_f32_16x16x32_bf16 v[106:109], v[210:213], v[186:189], v[106:109]
	v_mfma_f32_16x16x32_bf16 v[102:105], v[218:221], v[164:167], v[102:105]
	v_mfma_f32_16x16x32_bf16 v[98:101], v[218:221], v[186:189], v[98:101]
	v_mfma_f32_16x16x32_bf16 v[126:129], v[198:201], v[182:185], v[126:129]
	v_mfma_f32_16x16x32_bf16 v[122:125], v[198:201], v[190:193], v[122:125]
	v_mfma_f32_16x16x32_bf16 v[118:121], v[206:209], v[182:185], v[118:121]
	v_mfma_f32_16x16x32_bf16 v[114:117], v[206:209], v[190:193], v[114:117]
	v_mfma_f32_16x16x32_bf16 v[110:113], v[214:217], v[182:185], v[110:113]
	v_mfma_f32_16x16x32_bf16 v[106:109], v[214:217], v[190:193], v[106:109]
	v_mfma_f32_16x16x32_bf16 v[102:105], v[222:225], v[182:185], v[102:105]
	v_mfma_f32_16x16x32_bf16 v[98:101], v[222:225], v[190:193], v[98:101]
	s_barrier
	v_readfirstlane_b32 s0, v153
	v_lshl_add_u64 v[250:251], v[246:247], 0, s[26:27]
	s_mov_b32 m0, s0
	v_readfirstlane_b32 s0, v154
	ds_read_b128 v[226:229], v145
	ds_read_b128 v[230:233], v145 offset:1024
	ds_read_b128 v[234:237], v145 offset:2048
	ds_read_b128 v[238:241], v145 offset:3072
	global_load_lds_dwordx4 v[250:251], off
	s_mov_b32 m0, s0
	v_lshl_add_u64 v[250:251], v[248:249], 0, s[26:27]
	global_load_lds_dwordx4 v[250:251], off
	s_barrier
	s_waitcnt lgkmcnt(0)
	v_mfma_f32_16x16x32_bf16 v[94:97], v[194:197], v[226:229], v[94:97]
	v_mfma_f32_16x16x32_bf16 v[90:93], v[194:197], v[234:237], v[90:93]
	v_mfma_f32_16x16x32_bf16 v[86:89], v[202:205], v[226:229], v[86:89]
	v_mfma_f32_16x16x32_bf16 v[82:85], v[202:205], v[234:237], v[82:85]
	v_mfma_f32_16x16x32_bf16 v[78:81], v[210:213], v[226:229], v[78:81]
	v_mfma_f32_16x16x32_bf16 v[74:77], v[210:213], v[234:237], v[74:77]
	v_mfma_f32_16x16x32_bf16 v[70:73], v[218:221], v[226:229], v[70:73]
	v_mfma_f32_16x16x32_bf16 v[66:69], v[218:221], v[234:237], v[66:69]
	v_mfma_f32_16x16x32_bf16 v[94:97], v[198:201], v[230:233], v[94:97]
	v_mfma_f32_16x16x32_bf16 v[90:93], v[198:201], v[238:241], v[90:93]
	v_mfma_f32_16x16x32_bf16 v[86:89], v[206:209], v[230:233], v[86:89]
	v_mfma_f32_16x16x32_bf16 v[82:85], v[206:209], v[238:241], v[82:85]
	v_mfma_f32_16x16x32_bf16 v[78:81], v[214:217], v[230:233], v[78:81]
	v_mfma_f32_16x16x32_bf16 v[74:77], v[214:217], v[238:241], v[74:77]
	v_mfma_f32_16x16x32_bf16 v[70:73], v[222:225], v[230:233], v[70:73]
	v_mfma_f32_16x16x32_bf16 v[66:69], v[222:225], v[238:241], v[66:69]
	v_readfirstlane_b32 s0, v155
	v_lshl_add_u64 v[242:243], v[242:243], 0, s[90:91]
	s_mov_b32 m0, s0
	v_readfirstlane_b32 s0, v156
	s_barrier
	ds_read_b128 v[194:197], v142 offset:49152
	ds_read_b128 v[198:201], v142 offset:50176
	ds_read_b128 v[202:205], v142 offset:51200
	ds_read_b128 v[206:209], v142 offset:52224
	ds_read_b128 v[210:213], v142 offset:53248
	ds_read_b128 v[214:217], v142 offset:54272
	ds_read_b128 v[218:221], v142 offset:55296
	ds_read_b128 v[222:225], v142 offset:56320
	global_load_lds_dwordx4 v[242:243], off
	s_mov_b32 m0, s0
	v_lshl_add_u64 v[242:243], v[244:245], 0, s[90:91]
	global_load_lds_dwordx4 v[242:243], off
	s_barrier
; #define G_LDA(dst, b, h)                                                                                                  \
;   _Pragma("unroll") for (int m = 0; m < 4; ++m) _Pragma("unroll") for (int k = 0; k < 2; ++k)                             \
;       dst[m][k] = *(const bf16x8*)((const char*)G_SA(b, h) + ((wr * 4 + m) * 2 + k) * 1024 + rdo)
; #define G_LDB(dst, b, h)                                                                                                  \
;   _Pragma("unroll") for (int n = 0; n < 2; ++n) _Pragma("unroll") for (int k = 0; k < 2; ++k)                             \
;       dst[n][k] = *(const bf16x8*)((const char*)G_SB(b, h) + ((wc * 2 + n) * 2 + k) * 1024 + rdo)
; #define G_WAIT_V(n) asm volatile("s_waitcnt vmcnt(" #n ")" ::: "memory")
; #define G_WAIT_L(n) asm volatile("s_waitcnt lgkmcnt(" #n ")" ::: "memory")
; #define G_BAR __builtin_amdgcn_s_barrier()
; #define G_SCHED __builtin_amdgcn_sched_barrier(0)
; DI void br_flush(PREF p, f32x4 (&acc)[2][2][4][2], int slot) { br_store(p, acc, slot); zero_acc256(acc); }
;     ...
;     G_BAR; G_WAIT_L(0); G_MMA(1, 0, At, B0); G_BAR; G_SCHED;
;     G_STAGE(G_SB(1, 1), B, ob0, ob1, LDB, 128, KB(tt + 3));
;     G_WAIT_V(6); G_BAR; G_MMA(1, 1, At, B1); G_BAR;
;     if (MODE && ((tt + 1) & 3) == 3) br_flush(p, acc, (tt + 1) >> 2);
;   }
;   {
;     G_LDB(B0, 0, 0); G_LDA(At, 0, 0); G_STAGE(G_SA(1, 1), A, oa0, oa1, LDA, 128, KA(nt - 1));
;     G_BAR; G_WAIT_L(0); G_MMA(0, 0, At, B0); G_BAR;
	s_waitcnt lgkmcnt(0)
	v_mfma_f32_16x16x32_bf16 v[62:65], v[194:197], v[164:167], v[62:65]
	v_mfma_f32_16x16x32_bf16 v[58:61], v[194:197], v[186:189], v[58:61]
	v_mfma_f32_16x16x32_bf16 v[54:57], v[202:205], v[164:167], v[54:57]
	v_mfma_f32_16x16x32_bf16 v[50:53], v[202:205], v[186:189], v[50:53]
	v_mfma_f32_16x16x32_bf16 v[46:49], v[210:213], v[164:167], v[46:49]
	v_mfma_f32_16x16x32_bf16 v[42:45], v[210:213], v[186:189], v[42:45]
	v_mfma_f32_16x16x32_bf16 v[38:41], v[218:221], v[164:167], v[38:41]
	v_mfma_f32_16x16x32_bf16 v[34:37], v[218:221], v[186:189], v[34:37]
	v_mfma_f32_16x16x32_bf16 v[62:65], v[198:201], v[182:185], v[62:65]
	v_mfma_f32_16x16x32_bf16 v[58:61], v[198:201], v[190:193], v[58:61]
	v_mfma_f32_16x16x32_bf16 v[54:57], v[206:209], v[182:185], v[54:57]
	v_mfma_f32_16x16x32_bf16 v[50:53], v[206:209], v[190:193], v[50:53]
	v_mfma_f32_16x16x32_bf16 v[46:49], v[214:217], v[182:185], v[46:49]
	v_mfma_f32_16x16x32_bf16 v[42:45], v[214:217], v[190:193], v[42:45]
	v_mfma_f32_16x16x32_bf16 v[38:41], v[222:225], v[182:185], v[38:41]
	v_mfma_f32_16x16x32_bf16 v[34:37], v[222:225], v[190:193], v[34:37]
	s_barrier
	v_readfirstlane_b32 s0, v157
	v_lshl_add_u64 v[164:165], v[246:247], 0, s[36:37]
	s_mov_b32 m0, s0
	v_readfirstlane_b32 s0, v159
	global_load_lds_dwordx4 v[164:165], off
	s_mov_b32 m0, s0
	v_lshl_add_u64 v[164:165], v[248:249], 0, s[36:37]
	global_load_lds_dwordx4 v[164:165], off
	s_waitcnt vmcnt(6)
	s_barrier
	v_mfma_f32_16x16x32_bf16 v[30:33], v[194:197], v[226:229], v[30:33]
	v_mfma_f32_16x16x32_bf16 v[26:29], v[194:197], v[234:237], v[26:29]
	v_mfma_f32_16x16x32_bf16 v[22:25], v[202:205], v[226:229], v[22:25]
	v_mfma_f32_16x16x32_bf16 v[18:21], v[202:205], v[234:237], v[18:21]
	v_mfma_f32_16x16x32_bf16 v[14:17], v[210:213], v[226:229], v[14:17]
	v_mfma_f32_16x16x32_bf16 v[10:13], v[210:213], v[234:237], v[10:13]
	v_mfma_f32_16x16x32_bf16 v[6:9], v[218:221], v[226:229], v[6:9]
	v_mfma_f32_16x16x32_bf16 v[2:5], v[218:221], v[234:237], v[2:5]
	v_mfma_f32_16x16x32_bf16 v[30:33], v[198:201], v[230:233], v[30:33]
	v_mfma_f32_16x16x32_bf16 v[26:29], v[198:201], v[238:241], v[26:29]
	v_mfma_f32_16x16x32_bf16 v[22:25], v[206:209], v[230:233], v[22:25]
	v_mfma_f32_16x16x32_bf16 v[18:21], v[206:209], v[238:241], v[18:21]
	v_mfma_f32_16x16x32_bf16 v[14:17], v[214:217], v[230:233], v[14:17]
	v_mfma_f32_16x16x32_bf16 v[10:13], v[214:217], v[238:241], v[10:13]
	v_mfma_f32_16x16x32_bf16 v[6:9], v[222:225], v[230:233], v[6:9]
	v_mfma_f32_16x16x32_bf16 v[2:5], v[222:225], v[238:241], v[2:5]
	s_add_i32 s9, s9, 2
	s_add_u32 s22, s22, 0x100
	s_addc_u32 s23, s23, 0
	s_cmp_lt_u32 s9, 12
	s_barrier
	s_cbranch_scc1 .LBB0_66
	s_add_u32 s0, s20, 0x40780
	s_addc_u32 s1, s21, 0
	v_readfirstlane_b32 s9, v161
	v_lshl_add_u64 v[132:133], v[132:133], 1, s[0:1]
	s_mov_b32 m0, s9
	v_lshl_add_u64 v[130:131], v[130:131], 1, s[0:1]
	v_readfirstlane_b32 s0, v162
	ds_read_b128 v[134:137], v160
	ds_read_b128 v[138:141], v160 offset:1024
	ds_read_b128 v[150:153], v160 offset:2048
	ds_read_b128 v[154:157], v160 offset:3072
	ds_read_b128 v[164:167], v142
	ds_read_b128 v[182:185], v142 offset:1024
	ds_read_b128 v[186:189], v142 offset:2048
	ds_read_b128 v[190:193], v142 offset:3072
	ds_read_b128 v[194:197], v142 offset:4096
	ds_read_b128 v[198:201], v142 offset:5120
	ds_read_b128 v[202:205], v142 offset:6144
	ds_read_b128 v[206:209], v142 offset:7168
	global_load_lds_dwordx4 v[132:133], off
	s_mov_b32 m0, s0
	s_nop 0
	global_load_lds_dwordx4 v[130:131], off
	s_barrier
	s_waitcnt lgkmcnt(0)
	v_mfma_f32_16x16x32_bf16 v[126:129], v[164:167], v[134:137], v[126:129]
	v_mfma_f32_16x16x32_bf16 v[122:125], v[164:167], v[150:153], v[122:125]
	v_mfma_f32_16x16x32_bf16 v[110:113], v[194:197], v[134:137], v[110:113]
	v_mfma_f32_16x16x32_bf16 v[102:105], v[202:205], v[134:137], v[102:105]
	v_mfma_f32_16x16x32_bf16 v[126:129], v[182:185], v[138:141], v[126:129]
	v_mfma_f32_16x16x32_bf16 v[122:125], v[182:185], v[154:157], v[122:125]
	v_mfma_f32_16x16x32_bf16 v[118:121], v[186:189], v[134:137], v[118:121]
	v_mfma_f32_16x16x32_bf16 v[114:117], v[186:189], v[150:153], v[114:117]
	v_mfma_f32_16x16x32_bf16 v[110:113], v[198:201], v[138:141], v[110:113]
	v_mfma_f32_16x16x32_bf16 v[106:109], v[194:197], v[150:153], v[106:109]
	v_mfma_f32_16x16x32_bf16 v[102:105], v[206:209], v[138:141], v[102:105]
	v_mfma_f32_16x16x32_bf16 v[98:101], v[202:205], v[150:153], v[98:101]
	v_mfma_f32_16x16x32_bf16 v[130:133], v[190:193], v[138:141], v[118:121]
	v_mfma_f32_16x16x32_bf16 v[210:213], v[190:193], v[154:157], v[114:117]
	v_mfma_f32_16x16x32_bf16 v[214:217], v[198:201], v[154:157], v[106:109]
	v_mfma_f32_16x16x32_bf16 v[218:221], v[206:209], v[154:157], v[98:101]
	s_barrier
	s_nop 1
	s_nop 0
	ds_read_b128 v[98:101], v158
	ds_read_b128 v[106:109], v158 offset:1024
	ds_read_b128 v[114:117], v158 offset:2048
	ds_read_b128 v[118:121], v158 offset:3072
	s_barrier
	s_waitcnt lgkmcnt(0)
	v_mfma_f32_16x16x32_bf16 v[94:97], v[164:167], v[98:101], v[94:97]
	v_mfma_f32_16x16x32_bf16 v[90:93], v[164:167], v[114:117], v[90:93]
	v_mfma_f32_16x16x32_bf16 v[78:81], v[194:197], v[98:101], v[78:81]
	v_mfma_f32_16x16x32_bf16 v[70:73], v[202:205], v[98:101], v[70:73]
	v_mfma_f32_16x16x32_bf16 v[94:97], v[182:185], v[106:109], v[94:97]
	v_mfma_f32_16x16x32_bf16 v[90:93], v[182:185], v[118:121], v[90:93]
	v_mfma_f32_16x16x32_bf16 v[86:89], v[186:189], v[98:101], v[86:89]
	v_mfma_f32_16x16x32_bf16 v[82:85], v[186:189], v[114:117], v[82:85]
	v_mfma_f32_16x16x32_bf16 v[78:81], v[198:201], v[106:109], v[78:81]
	v_mfma_f32_16x16x32_bf16 v[74:77], v[194:197], v[114:117], v[74:77]
	v_mfma_f32_16x16x32_bf16 v[70:73], v[206:209], v[106:109], v[70:73]
	v_mfma_f32_16x16x32_bf16 v[66:69], v[202:205], v[114:117], v[66:69]
	v_mfma_f32_16x16x32_bf16 v[158:161], v[190:193], v[106:109], v[86:89]
	v_mfma_f32_16x16x32_bf16 v[164:167], v[190:193], v[118:121], v[82:85]
	v_mfma_f32_16x16x32_bf16 v[182:185], v[198:201], v[118:121], v[74:77]
	v_mfma_f32_16x16x32_bf16 v[186:189], v[206:209], v[118:121], v[66:69]
	s_barrier
; #define G_LDA(dst, b, h)                                                                                                  \
;   _Pragma("unroll") for (int m = 0; m < 4; ++m) _Pragma("unroll") for (int k = 0; k < 2; ++k)                             \
;       dst[m][k] = *(const bf16x8*)((const char*)G_SA(b, h) + ((wr * 4 + m) * 2 + k) * 1024 + rdo)
; #define G_LDB(dst, b, h)                                                                                                  \
;   _Pragma("unroll") for (int n = 0; n < 2; ++n) _Pragma("unroll") for (int k = 0; k < 2; ++k)                             \
;       dst[n][k] = *(const bf16x8*)((const char*)G_SB(b, h) + ((wc * 2 + n) * 2 + k) * 1024 + rdo)
; #define G_WAIT_V(n) asm volatile("s_waitcnt vmcnt(" #n ")" ::: "memory")
; #define G_WAIT_L(n) asm volatile("s_waitcnt lgkmcnt(" #n ")" ::: "memory")
; #define G_BAR __builtin_amdgcn_s_barrier()
;     ...
;     G_LDB(B1, 0, 1); G_BAR; G_WAIT_L(0); G_MMA(0, 1, At, B1); G_BAR;
;     G_LDA(At, 0, 1); G_WAIT_V(4); G_BAR; G_WAIT_L(0); G_MMA(1, 0, At, B0); G_MMA(1, 1, At, B1); G_BAR;
;   }
;   {
;     G_LDB(B0, 1, 0); G_LDA(At, 1, 0); G_WAIT_V(2); G_BAR; G_WAIT_L(0); G_MMA(0, 0, At, B0); G_BAR;
	s_nop 1
	s_nop 0
	ds_read_b128 v[66:69], v142 offset:16384
	ds_read_b128 v[74:77], v142 offset:17408
	ds_read_b128 v[82:85], v142 offset:18432
	ds_read_b128 v[86:89], v142 offset:19456
	ds_read_b128 v[190:193], v142 offset:20480
	ds_read_b128 v[194:197], v142 offset:21504
	ds_read_b128 v[198:201], v142 offset:22528
	ds_read_b128 v[202:205], v142 offset:23552
	s_waitcnt vmcnt(4)
	s_barrier
	s_waitcnt lgkmcnt(0)
	v_mfma_f32_16x16x32_bf16 v[62:65], v[66:69], v[134:137], v[62:65]
	v_mfma_f32_16x16x32_bf16 v[58:61], v[66:69], v[150:153], v[58:61]
	v_mfma_f32_16x16x32_bf16 v[46:49], v[190:193], v[134:137], v[46:49]
	v_mfma_f32_16x16x32_bf16 v[38:41], v[198:201], v[134:137], v[38:41]
	v_mfma_f32_16x16x32_bf16 v[62:65], v[74:77], v[138:141], v[62:65]
	v_mfma_f32_16x16x32_bf16 v[58:61], v[74:77], v[154:157], v[58:61]
	v_mfma_f32_16x16x32_bf16 v[54:57], v[82:85], v[134:137], v[54:57]
	v_mfma_f32_16x16x32_bf16 v[50:53], v[82:85], v[150:153], v[50:53]
	v_mfma_f32_16x16x32_bf16 v[46:49], v[194:197], v[138:141], v[46:49]
	v_mfma_f32_16x16x32_bf16 v[42:45], v[190:193], v[150:153], v[42:45]
	v_mfma_f32_16x16x32_bf16 v[38:41], v[202:205], v[138:141], v[38:41]
	v_mfma_f32_16x16x32_bf16 v[34:37], v[198:201], v[150:153], v[34:37]
	v_mfma_f32_16x16x32_bf16 v[206:209], v[86:89], v[138:141], v[54:57]
	v_mfma_f32_16x16x32_bf16 v[222:225], v[86:89], v[154:157], v[50:53]
	v_mfma_f32_16x16x32_bf16 v[226:229], v[194:197], v[154:157], v[42:45]
	v_mfma_f32_16x16x32_bf16 v[134:137], v[202:205], v[154:157], v[34:37]
	v_mfma_f32_16x16x32_bf16 v[30:33], v[66:69], v[98:101], v[30:33]
	v_mfma_f32_16x16x32_bf16 v[26:29], v[66:69], v[114:117], v[26:29]
	v_mfma_f32_16x16x32_bf16 v[14:17], v[190:193], v[98:101], v[14:17]
	v_mfma_f32_16x16x32_bf16 v[6:9], v[198:201], v[98:101], v[6:9]
	v_mfma_f32_16x16x32_bf16 v[30:33], v[74:77], v[106:109], v[30:33]
	v_mfma_f32_16x16x32_bf16 v[26:29], v[74:77], v[118:121], v[26:29]
	v_mfma_f32_16x16x32_bf16 v[22:25], v[82:85], v[98:101], v[22:25]
	v_mfma_f32_16x16x32_bf16 v[18:21], v[82:85], v[114:117], v[18:21]
	v_mfma_f32_16x16x32_bf16 v[14:17], v[194:197], v[106:109], v[14:17]
	v_mfma_f32_16x16x32_bf16 v[10:13], v[190:193], v[114:117], v[10:13]
	v_mfma_f32_16x16x32_bf16 v[6:9], v[202:205], v[106:109], v[6:9]
	v_mfma_f32_16x16x32_bf16 v[2:5], v[198:201], v[114:117], v[2:5]
	v_mfma_f32_16x16x32_bf16 v[138:141], v[86:89], v[106:109], v[22:25]
	v_mfma_f32_16x16x32_bf16 v[150:153], v[86:89], v[118:121], v[18:21]
	v_mfma_f32_16x16x32_bf16 v[154:157], v[194:197], v[118:121], v[10:13]
	v_mfma_f32_16x16x32_bf16 v[190:193], v[202:205], v[118:121], v[2:5]
	s_barrier
	s_nop 1
	s_nop 0
	ds_read_b128 v[2:5], v149
	ds_read_b128 v[10:13], v149 offset:1024
	ds_read_b128 v[18:21], v149 offset:2048
	ds_read_b128 v[22:25], v149 offset:3072
	ds_read_b128 v[34:37], v142 offset:32768
	ds_read_b128 v[42:45], v142 offset:33792
	ds_read_b128 v[50:53], v142 offset:34816
	ds_read_b128 v[54:57], v142 offset:35840
	ds_read_b128 v[66:69], v142 offset:36864
	ds_read_b128 v[146:149], v142 offset:37888
	ds_read_b128 v[194:197], v142 offset:38912
	ds_read_b128 v[198:201], v142 offset:39936
	s_waitcnt vmcnt(2)
	s_barrier
	s_waitcnt lgkmcnt(0)
	v_mfma_f32_16x16x32_bf16 v[74:77], v[34:37], v[2:5], v[126:129]
	v_mfma_f32_16x16x32_bf16 v[118:121], v[42:45], v[10:13], v[74:77]
	v_mfma_f32_16x16x32_bf16 v[74:77], v[34:37], v[18:21], v[122:125]
	v_mfma_f32_16x16x32_bf16 v[126:129], v[42:45], v[22:25], v[74:77]
	v_mfma_f32_16x16x32_bf16 v[74:77], v[50:53], v[2:5], v[130:133]
	v_mfma_f32_16x16x32_bf16 v[114:117], v[54:57], v[10:13], v[74:77]
	v_mfma_f32_16x16x32_bf16 v[74:77], v[50:53], v[18:21], v[210:213]
	v_mfma_f32_16x16x32_bf16 v[122:125], v[54:57], v[22:25], v[74:77]
	v_mfma_f32_16x16x32_bf16 v[74:77], v[66:69], v[2:5], v[110:113]
	v_mfma_f32_16x16x32_bf16 v[106:109], v[146:149], v[10:13], v[74:77]
	v_mfma_f32_16x16x32_bf16 v[74:77], v[66:69], v[18:21], v[214:217]
	v_mfma_f32_16x16x32_bf16 v[110:113], v[146:149], v[22:25], v[74:77]
	v_mfma_f32_16x16x32_bf16 v[74:77], v[194:197], v[2:5], v[102:105]
	v_mfma_f32_16x16x32_bf16 v[98:101], v[198:201], v[10:13], v[74:77]
	v_mfma_f32_16x16x32_bf16 v[74:77], v[194:197], v[18:21], v[218:221]
	v_mfma_f32_16x16x32_bf16 v[102:105], v[198:201], v[22:25], v[74:77]
	s_barrier
; #define G_LDA(dst, b, h)                                                                                                  \
;   _Pragma("unroll") for (int m = 0; m < 4; ++m) _Pragma("unroll") for (int k = 0; k < 2; ++k)                             \
;       dst[m][k] = *(const bf16x8*)((const char*)G_SA(b, h) + ((wr * 4 + m) * 2 + k) * 1024 + rdo)
; #define G_LDB(dst, b, h)                                                                                                  \
;   _Pragma("unroll") for (int n = 0; n < 2; ++n) _Pragma("unroll") for (int k = 0; k < 2; ++k)                             \
;       dst[n][k] = *(const bf16x8*)((const char*)G_SB(b, h) + ((wc * 2 + n) * 2 + k) * 1024 + rdo)
; #define G_WAIT_V(n) asm volatile("s_waitcnt vmcnt(" #n ")" ::: "memory")
; #define G_WAIT_L(n) asm volatile("s_waitcnt lgkmcnt(" #n ")" ::: "memory")
; #define G_BAR __builtin_amdgcn_s_barrier()
;     ...
;     G_LDB(B0, 1, 0); G_LDA(At, 1, 0); G_WAIT_V(2); G_BAR; G_WAIT_L(0); G_MMA(0, 0, At, B0); G_BAR;
;     G_LDB(B1, 1, 1); G_WAIT_V(0); G_BAR; G_WAIT_L(0); G_MMA(0, 1, At, B1); G_BAR;
;     G_LDA(At, 1, 1); G_BAR; G_WAIT_L(0); G_MMA(1, 0, At, B0); G_MMA(1, 1, At, B1); G_BAR;
;   }
;   if (wr == 0) G_BAR;
	ds_read_b128 v[130:133], v145
	ds_read_b128 v[202:205], v145 offset:1024
	ds_read_b128 v[210:213], v145 offset:2048
	ds_read_b128 v[214:217], v145 offset:3072
	s_waitcnt vmcnt(0)
	s_barrier
	s_waitcnt lgkmcnt(0)
	v_mfma_f32_16x16x32_bf16 v[74:77], v[34:37], v[130:133], v[94:97]
	v_mfma_f32_16x16x32_bf16 v[34:37], v[34:37], v[210:213], v[90:93]
	v_mfma_f32_16x16x32_bf16 v[94:97], v[42:45], v[214:217], v[34:37]
	v_mfma_f32_16x16x32_bf16 v[34:37], v[50:53], v[130:133], v[158:161]
	v_mfma_f32_16x16x32_bf16 v[82:85], v[54:57], v[202:205], v[34:37]
	v_mfma_f32_16x16x32_bf16 v[34:37], v[50:53], v[210:213], v[164:167]
	v_mfma_f32_16x16x32_bf16 v[90:93], v[54:57], v[214:217], v[34:37]
	v_mfma_f32_16x16x32_bf16 v[34:37], v[66:69], v[130:133], v[78:81]
	v_mfma_f32_16x16x32_bf16 v[86:89], v[42:45], v[202:205], v[74:77]
	v_mfma_f32_16x16x32_bf16 v[74:77], v[146:149], v[202:205], v[34:37]
	v_mfma_f32_16x16x32_bf16 v[34:37], v[66:69], v[210:213], v[182:185]
	v_mfma_f32_16x16x32_bf16 v[78:81], v[146:149], v[214:217], v[34:37]
	v_mfma_f32_16x16x32_bf16 v[34:37], v[194:197], v[130:133], v[70:73]
	v_mfma_f32_16x16x32_bf16 v[66:69], v[198:201], v[202:205], v[34:37]
	v_mfma_f32_16x16x32_bf16 v[34:37], v[194:197], v[210:213], v[186:189]
	v_mfma_f32_16x16x32_bf16 v[70:73], v[198:201], v[214:217], v[34:37]
	s_barrier
	ds_read_b128 v[144:147], v142 offset:49152
	ds_read_b128 v[158:161], v142 offset:50176
	ds_read_b128 v[164:167], v142 offset:51200
	ds_read_b128 v[182:185], v142 offset:52224
	ds_read_b128 v[186:189], v142 offset:53248
	ds_read_b128 v[194:197], v142 offset:54272
	ds_read_b128 v[198:201], v142 offset:55296
	ds_read_b128 v[218:221], v142 offset:56320
	s_barrier
	s_waitcnt lgkmcnt(0)
	v_mfma_f32_16x16x32_bf16 v[34:37], v[144:147], v[2:5], v[62:65]
	v_mfma_f32_16x16x32_bf16 v[54:57], v[158:161], v[10:13], v[34:37]
	v_mfma_f32_16x16x32_bf16 v[34:37], v[144:147], v[18:21], v[58:61]
	v_mfma_f32_16x16x32_bf16 v[62:65], v[158:161], v[22:25], v[34:37]
	v_mfma_f32_16x16x32_bf16 v[34:37], v[164:167], v[2:5], v[206:209]
	v_mfma_f32_16x16x32_bf16 v[50:53], v[182:185], v[10:13], v[34:37]
	v_mfma_f32_16x16x32_bf16 v[34:37], v[164:167], v[18:21], v[222:225]
	v_mfma_f32_16x16x32_bf16 v[58:61], v[182:185], v[22:25], v[34:37]
	v_mfma_f32_16x16x32_bf16 v[34:37], v[186:189], v[2:5], v[46:49]
	v_mfma_f32_16x16x32_bf16 v[42:45], v[194:197], v[10:13], v[34:37]
	v_mfma_f32_16x16x32_bf16 v[34:37], v[186:189], v[18:21], v[226:229]
	v_mfma_f32_16x16x32_bf16 v[2:5], v[198:201], v[2:5], v[38:41]
	v_mfma_f32_16x16x32_bf16 v[46:49], v[194:197], v[22:25], v[34:37]
	v_mfma_f32_16x16x32_bf16 v[34:37], v[218:221], v[10:13], v[2:5]
	v_mfma_f32_16x16x32_bf16 v[2:5], v[198:201], v[18:21], v[134:137]
	v_mfma_f32_16x16x32_bf16 v[38:41], v[218:221], v[22:25], v[2:5]
	v_mfma_f32_16x16x32_bf16 v[2:5], v[144:147], v[130:133], v[30:33]
	v_mfma_f32_16x16x32_bf16 v[22:25], v[158:161], v[202:205], v[2:5]
	v_mfma_f32_16x16x32_bf16 v[2:5], v[144:147], v[210:213], v[26:29]
	v_mfma_f32_16x16x32_bf16 v[30:33], v[158:161], v[214:217], v[2:5]
	v_mfma_f32_16x16x32_bf16 v[2:5], v[164:167], v[130:133], v[138:141]
	v_mfma_f32_16x16x32_bf16 v[18:21], v[182:185], v[202:205], v[2:5]
	v_mfma_f32_16x16x32_bf16 v[2:5], v[164:167], v[210:213], v[150:153]
	v_mfma_f32_16x16x32_bf16 v[26:29], v[182:185], v[214:217], v[2:5]
	v_mfma_f32_16x16x32_bf16 v[2:5], v[186:189], v[130:133], v[14:17]
	v_mfma_f32_16x16x32_bf16 v[10:13], v[194:197], v[202:205], v[2:5]
	v_mfma_f32_16x16x32_bf16 v[2:5], v[186:189], v[210:213], v[154:157]
	v_mfma_f32_16x16x32_bf16 v[14:17], v[194:197], v[214:217], v[2:5]
	v_mfma_f32_16x16x32_bf16 v[2:5], v[198:201], v[130:133], v[6:9]
	v_mfma_f32_16x16x32_bf16 v[6:9], v[198:201], v[210:213], v[190:193]
	v_mfma_f32_16x16x32_bf16 v[2:5], v[218:221], v[202:205], v[2:5]
	v_mfma_f32_16x16x32_bf16 v[6:9], v[218:221], v[214:217], v[6:9]
	v_cmp_gt_u32_e32 vcc, s67, v0
	s_barrier
	s_and_saveexec_b64 s[20:21], vcc
	s_cbranch_execz .LBB0_69
	s_barrier

; #define G_LDA(dst, b, h)                                                                                                  \
;   _Pragma("unroll") for (int m = 0; m < 4; ++m) _Pragma("unroll") for (int k = 0; k < 2; ++k)                             \
;       dst[m][k] = *(const bf16x8*)((const char*)G_SA(b, h) + ((wr * 4 + m) * 2 + k) * 1024 + rdo)
; #define G_LDB(dst, b, h)                                                                                                  \
;   _Pragma("unroll") for (int n = 0; n < 2; ++n) _Pragma("unroll") for (int k = 0; k < 2; ++k)                             \
;       dst[n][k] = *(const bf16x8*)((const char*)G_SB(b, h) + ((wc * 2 + n) * 2 + k) * 1024 + rdo)
; #define G_WAIT_L(n) asm volatile("s_waitcnt lgkmcnt(" #n ")" ::: "memory")
; #define G_BAR __builtin_amdgcn_s_barrier()
; #define G_SCHED __builtin_amdgcn_sched_barrier(0)
;     ...
;     G_LDB(B0, 0, 0); G_SCHED; G_LDA(At, 0, 0); G_STAGE(G_SA(1, 1), A, oa0, oa1, LDA, 128, KA(tt + 1));
;     G_WAIT_L(8); G_BAR; G_WAIT_L(0); G_MMA(0, 0, At, B0); G_BAR; G_SCHED;
;     G_LDB(B1, 0, 1); G_STAGE(G_SB(0, 0), B, ob0, ob1, LDB, 0, KB(tt + 2));
;     G_BAR; G_WAIT_L(0); G_MMA(0, 1, At, B1); G_BAR;
;     G_LDA(At, 0, 1); G_STAGE(G_SA(0, 0), A, oa0, oa1, LDA, 0, KA(tt + 2));
;     G_BAR; G_WAIT_L(0); G_MMA(1, 0, At, B0); G_BAR; G_SCHED;
.LBB0_96:
	ds_read_b128 v[182:185], v151
	ds_read_b128 v[186:189], v151 offset:1024
	ds_read_b128 v[190:193], v151 offset:2048
	ds_read_b128 v[194:197], v151 offset:3072
	v_add_u32_e32 v162, 0xc000, v147
	v_lshl_add_u64 v[166:167], s[30:31], 0, v[140:141]
	v_readfirstlane_b32 s0, v162
	v_lshl_add_u64 v[164:165], v[166:167], 0, s[78:79]
	s_mov_b32 m0, s0
	ds_read_b128 v[198:201], v143
	ds_read_b128 v[202:205], v143 offset:1024
	ds_read_b128 v[206:209], v143 offset:2048
	ds_read_b128 v[210:213], v143 offset:3072
	ds_read_b128 v[214:217], v143 offset:4096
	ds_read_b128 v[218:221], v143 offset:5120
	ds_read_b128 v[222:225], v143 offset:6144
	ds_read_b128 v[226:229], v143 offset:7168
	global_load_lds_dwordx4 v[164:165], off
	v_add_u32_e32 v164, 0xe000, v147
	v_lshl_add_u64 v[246:247], s[30:31], 0, v[138:139]
	v_readfirstlane_b32 s0, v164
	v_lshl_add_u64 v[230:231], v[246:247], 0, s[78:79]
	s_mov_b32 m0, s0
	s_add_i32 s34, s13, -1
	global_load_lds_dwordx4 v[230:231], off
	s_waitcnt lgkmcnt(8)
	s_barrier
	s_waitcnt lgkmcnt(0)
	v_mfma_f32_16x16x32_bf16 v[126:129], v[198:201], v[182:185], v[126:129]
	v_mfma_f32_16x16x32_bf16 v[122:125], v[198:201], v[190:193], v[122:125]
	v_mfma_f32_16x16x32_bf16 v[118:121], v[206:209], v[182:185], v[118:121]
	v_mfma_f32_16x16x32_bf16 v[114:117], v[206:209], v[190:193], v[114:117]
	v_mfma_f32_16x16x32_bf16 v[110:113], v[214:217], v[182:185], v[110:113]
	v_mfma_f32_16x16x32_bf16 v[106:109], v[214:217], v[190:193], v[106:109]
	v_mfma_f32_16x16x32_bf16 v[102:105], v[222:225], v[182:185], v[102:105]
	v_mfma_f32_16x16x32_bf16 v[98:101], v[222:225], v[190:193], v[98:101]
	v_mfma_f32_16x16x32_bf16 v[126:129], v[202:205], v[186:189], v[126:129]
	v_mfma_f32_16x16x32_bf16 v[122:125], v[202:205], v[194:197], v[122:125]
	v_mfma_f32_16x16x32_bf16 v[118:121], v[210:213], v[186:189], v[118:121]
	v_mfma_f32_16x16x32_bf16 v[114:117], v[210:213], v[194:197], v[114:117]
	v_mfma_f32_16x16x32_bf16 v[110:113], v[218:221], v[186:189], v[110:113]
	v_mfma_f32_16x16x32_bf16 v[106:109], v[218:221], v[194:197], v[106:109]
	v_mfma_f32_16x16x32_bf16 v[102:105], v[226:229], v[186:189], v[102:105]
	v_mfma_f32_16x16x32_bf16 v[98:101], v[226:229], v[194:197], v[98:101]
	s_barrier
	s_add_i32 s0, s25, 0xffff0000
	s_sub_i32 s1, s23, 64
	s_and_b32 s0, s0, 0x1c0000
	s_and_b32 s1, s1, 0x80
	s_or_b32 s0, s0, s1
	s_lshl_b32 s35, s0, 1
	s_add_u32 s0, s26, s35
	s_addc_u32 s1, s27, 0
	v_readfirstlane_b32 s36, v149
	v_lshl_add_u64 v[248:249], s[0:1], 0, v[134:135]
	s_mov_b32 m0, s36
	ds_read_b128 v[230:233], v146
	ds_read_b128 v[234:237], v146 offset:1024
	ds_read_b128 v[238:241], v146 offset:2048
	ds_read_b128 v[242:245], v146 offset:3072
	global_load_lds_dwordx4 v[248:249], off
	v_lshl_add_u64 v[248:249], s[0:1], 0, v[136:137]
	v_readfirstlane_b32 s0, v150
	s_mov_b32 m0, s0
	s_nop 0
	global_load_lds_dwordx4 v[248:249], off
	s_barrier
	s_waitcnt lgkmcnt(0)
	v_mfma_f32_16x16x32_bf16 v[94:97], v[198:201], v[230:233], v[94:97]
	v_mfma_f32_16x16x32_bf16 v[90:93], v[198:201], v[238:241], v[90:93]
	v_mfma_f32_16x16x32_bf16 v[86:89], v[206:209], v[230:233], v[86:89]
	v_mfma_f32_16x16x32_bf16 v[82:85], v[206:209], v[238:241], v[82:85]
	v_mfma_f32_16x16x32_bf16 v[78:81], v[214:217], v[230:233], v[78:81]
	v_mfma_f32_16x16x32_bf16 v[74:77], v[214:217], v[238:241], v[74:77]
	v_mfma_f32_16x16x32_bf16 v[70:73], v[222:225], v[230:233], v[70:73]
	v_mfma_f32_16x16x32_bf16 v[66:69], v[222:225], v[238:241], v[66:69]
	v_mfma_f32_16x16x32_bf16 v[94:97], v[202:205], v[234:237], v[94:97]
	v_mfma_f32_16x16x32_bf16 v[90:93], v[202:205], v[242:245], v[90:93]
	v_mfma_f32_16x16x32_bf16 v[86:89], v[210:213], v[234:237], v[86:89]
	v_mfma_f32_16x16x32_bf16 v[82:85], v[210:213], v[242:245], v[82:85]
	v_mfma_f32_16x16x32_bf16 v[78:81], v[218:221], v[234:237], v[78:81]
	v_mfma_f32_16x16x32_bf16 v[74:77], v[218:221], v[242:245], v[74:77]
	v_mfma_f32_16x16x32_bf16 v[70:73], v[226:229], v[234:237], v[70:73]
	v_mfma_f32_16x16x32_bf16 v[66:69], v[226:229], v[242:245], v[66:69]
	v_readfirstlane_b32 s0, v147
	v_lshl_add_u64 v[248:249], v[166:167], 0, s[82:83]
	s_mov_b32 m0, s0
	v_readfirstlane_b32 s0, v148
	s_barrier
	ds_read_b128 v[198:201], v143 offset:16384
	ds_read_b128 v[202:205], v143 offset:17408
	ds_read_b128 v[206:209], v143 offset:18432
	ds_read_b128 v[210:213], v143 offset:19456
	ds_read_b128 v[214:217], v143 offset:20480
	ds_read_b128 v[218:221], v143 offset:21504
	ds_read_b128 v[222:225], v143 offset:22528
	ds_read_b128 v[226:229], v143 offset:23552
	global_load_lds_dwordx4 v[248:249], off
	s_mov_b32 m0, s0
	v_lshl_add_u64 v[248:249], v[246:247], 0, s[82:83]
	global_load_lds_dwordx4 v[248:249], off
	s_barrier
	s_waitcnt lgkmcnt(0)
	v_mfma_f32_16x16x32_bf16 v[62:65], v[198:201], v[182:185], v[62:65]
	v_mfma_f32_16x16x32_bf16 v[58:61], v[198:201], v[190:193], v[58:61]
	v_mfma_f32_16x16x32_bf16 v[54:57], v[206:209], v[182:185], v[54:57]
	v_mfma_f32_16x16x32_bf16 v[50:53], v[206:209], v[190:193], v[50:53]
	v_mfma_f32_16x16x32_bf16 v[46:49], v[214:217], v[182:185], v[46:49]
	v_mfma_f32_16x16x32_bf16 v[42:45], v[214:217], v[190:193], v[42:45]
	v_mfma_f32_16x16x32_bf16 v[38:41], v[222:225], v[182:185], v[38:41]
	v_mfma_f32_16x16x32_bf16 v[34:37], v[222:225], v[190:193], v[34:37]
	v_mfma_f32_16x16x32_bf16 v[62:65], v[202:205], v[186:189], v[62:65]
	v_mfma_f32_16x16x32_bf16 v[58:61], v[202:205], v[194:197], v[58:61]
	v_mfma_f32_16x16x32_bf16 v[54:57], v[210:213], v[186:189], v[54:57]
	v_mfma_f32_16x16x32_bf16 v[50:53], v[210:213], v[194:197], v[50:53]
	v_mfma_f32_16x16x32_bf16 v[46:49], v[218:221], v[186:189], v[46:49]
	v_mfma_f32_16x16x32_bf16 v[42:45], v[218:221], v[194:197], v[42:45]
	v_mfma_f32_16x16x32_bf16 v[38:41], v[226:229], v[186:189], v[38:41]
	v_mfma_f32_16x16x32_bf16 v[34:37], v[226:229], v[194:197], v[34:37]
	s_barrier
; #define G_LDA(dst, b, h)                                                                                                  \
;   _Pragma("unroll") for (int m = 0; m < 4; ++m) _Pragma("unroll") for (int k = 0; k < 2; ++k)                             \
;       dst[m][k] = *(const bf16x8*)((const char*)G_SA(b, h) + ((wr * 4 + m) * 2 + k) * 1024 + rdo)
; #define G_LDB(dst, b, h)                                                                                                  \
;   _Pragma("unroll") for (int n = 0; n < 2; ++n) _Pragma("unroll") for (int k = 0; k < 2; ++k)                             \
;       dst[n][k] = *(const bf16x8*)((const char*)G_SB(b, h) + ((wc * 2 + n) * 2 + k) * 1024 + rdo)
; #define G_WAIT_V(n) asm volatile("s_waitcnt vmcnt(" #n ")" ::: "memory")
; #define G_WAIT_L(n) asm volatile("s_waitcnt lgkmcnt(" #n ")" ::: "memory")
; #define G_BAR __builtin_amdgcn_s_barrier()
; #define G_SCHED __builtin_amdgcn_sched_barrier(0)
;     ...
;     G_STAGE(G_SB(0, 1), B, ob0, ob1, LDB, 128, KB(tt + 2));
;     G_WAIT_V(6); G_BAR; G_MMA(1, 1, At, B1); G_BAR;
;     G_LDB(B0, 1, 0); G_SCHED; G_LDA(At, 1, 0); G_STAGE(G_SA(0, 1), A, oa0, oa1, LDA, 128, KA(tt + 2));
;     G_WAIT_L(8); G_BAR; G_WAIT_L(0); G_MMA(0, 0, At, B0); G_BAR; G_SCHED;
;     G_LDB(B1, 1, 1); G_STAGE(G_SB(1, 0), B, ob0, ob1, LDB, 0, KB(tt + 3));
;     G_BAR; G_WAIT_L(0); G_MMA(0, 1, At, B1); G_BAR;
;     G_LDA(At, 1, 1); G_STAGE(G_SA(1, 0), A, oa0, oa1, LDA, 0, KA(tt + 3));
	s_add_u32 s0, s28, s35
	s_addc_u32 s1, s29, 0
	v_readfirstlane_b32 s35, v152
	s_mov_b32 m0, s35
	v_lshl_add_u64 v[182:183], s[0:1], 0, v[134:135]
	global_load_lds_dwordx4 v[182:183], off
	v_lshl_add_u64 v[182:183], s[0:1], 0, v[136:137]
	v_readfirstlane_b32 s0, v153
	s_mov_b32 m0, s0
	s_nop 0
	global_load_lds_dwordx4 v[182:183], off
	s_waitcnt vmcnt(6)
	s_barrier
	v_mfma_f32_16x16x32_bf16 v[30:33], v[198:201], v[230:233], v[30:33]
	v_mfma_f32_16x16x32_bf16 v[26:29], v[198:201], v[238:241], v[26:29]
	v_mfma_f32_16x16x32_bf16 v[22:25], v[206:209], v[230:233], v[22:25]
	v_mfma_f32_16x16x32_bf16 v[18:21], v[206:209], v[238:241], v[18:21]
	v_mfma_f32_16x16x32_bf16 v[14:17], v[214:217], v[230:233], v[14:17]
	v_mfma_f32_16x16x32_bf16 v[10:13], v[214:217], v[238:241], v[10:13]
	v_mfma_f32_16x16x32_bf16 v[6:9], v[222:225], v[230:233], v[6:9]
	v_mfma_f32_16x16x32_bf16 v[2:5], v[222:225], v[238:241], v[2:5]
	v_mfma_f32_16x16x32_bf16 v[30:33], v[202:205], v[234:237], v[30:33]
	v_mfma_f32_16x16x32_bf16 v[26:29], v[202:205], v[242:245], v[26:29]
	v_mfma_f32_16x16x32_bf16 v[22:25], v[210:213], v[234:237], v[22:25]
	v_mfma_f32_16x16x32_bf16 v[18:21], v[210:213], v[242:245], v[18:21]
	v_mfma_f32_16x16x32_bf16 v[14:17], v[218:221], v[234:237], v[14:17]
	v_mfma_f32_16x16x32_bf16 v[10:13], v[218:221], v[242:245], v[10:13]
	v_mfma_f32_16x16x32_bf16 v[6:9], v[226:229], v[234:237], v[6:9]
	v_mfma_f32_16x16x32_bf16 v[2:5], v[226:229], v[242:245], v[2:5]
	s_barrier
	ds_read_b128 v[182:185], v145
	ds_read_b128 v[186:189], v145 offset:1024
	ds_read_b128 v[190:193], v145 offset:2048
	ds_read_b128 v[194:197], v145 offset:3072
	v_readfirstlane_b32 s0, v154
	v_lshl_add_u64 v[230:231], v[166:167], 0, s[86:87]
	s_mov_b32 m0, s0
	v_readfirstlane_b32 s0, v155
	ds_read_b128 v[198:201], v143 offset:32768
	ds_read_b128 v[202:205], v143 offset:33792
	ds_read_b128 v[206:209], v143 offset:34816
	ds_read_b128 v[210:213], v143 offset:35840
	ds_read_b128 v[214:217], v143 offset:36864
	ds_read_b128 v[218:221], v143 offset:37888
	ds_read_b128 v[222:225], v143 offset:38912
	ds_read_b128 v[226:229], v143 offset:39936
	global_load_lds_dwordx4 v[230:231], off
	s_mov_b32 m0, s0
	v_lshl_add_u64 v[230:231], v[246:247], 0, s[86:87]
	global_load_lds_dwordx4 v[230:231], off
	s_waitcnt lgkmcnt(8)
	s_barrier
	s_waitcnt lgkmcnt(0)
	v_mfma_f32_16x16x32_bf16 v[126:129], v[198:201], v[182:185], v[126:129]
	v_mfma_f32_16x16x32_bf16 v[122:125], v[198:201], v[190:193], v[122:125]
	v_mfma_f32_16x16x32_bf16 v[118:121], v[206:209], v[182:185], v[118:121]
	v_mfma_f32_16x16x32_bf16 v[114:117], v[206:209], v[190:193], v[114:117]
	v_mfma_f32_16x16x32_bf16 v[110:113], v[214:217], v[182:185], v[110:113]
	v_mfma_f32_16x16x32_bf16 v[106:109], v[214:217], v[190:193], v[106:109]
	v_mfma_f32_16x16x32_bf16 v[102:105], v[222:225], v[182:185], v[102:105]
	v_mfma_f32_16x16x32_bf16 v[98:101], v[222:225], v[190:193], v[98:101]
	v_mfma_f32_16x16x32_bf16 v[126:129], v[202:205], v[186:189], v[126:129]
	v_mfma_f32_16x16x32_bf16 v[122:125], v[202:205], v[194:197], v[122:125]
	v_mfma_f32_16x16x32_bf16 v[118:121], v[210:213], v[186:189], v[118:121]
	v_mfma_f32_16x16x32_bf16 v[114:117], v[210:213], v[194:197], v[114:117]
	v_mfma_f32_16x16x32_bf16 v[110:113], v[218:221], v[186:189], v[110:113]
	v_mfma_f32_16x16x32_bf16 v[106:109], v[218:221], v[194:197], v[106:109]
	v_mfma_f32_16x16x32_bf16 v[102:105], v[226:229], v[186:189], v[102:105]
	v_mfma_f32_16x16x32_bf16 v[98:101], v[226:229], v[194:197], v[98:101]
	s_barrier
	s_and_b32 s0, s25, 0x1c0000
	s_and_b32 s1, s23, 0xc0
	s_or_b32 s0, s0, s1
	s_lshl_b32 s35, s0, 1
	s_add_u32 s0, s26, s35
	s_addc_u32 s1, s27, 0
	v_readfirstlane_b32 s36, v156
	v_lshl_add_u64 v[248:249], s[0:1], 0, v[134:135]
	s_mov_b32 m0, s36
	ds_read_b128 v[230:233], v144
	ds_read_b128 v[234:237], v144 offset:1024
	ds_read_b128 v[238:241], v144 offset:2048
	ds_read_b128 v[242:245], v144 offset:3072
	global_load_lds_dwordx4 v[248:249], off
	v_lshl_add_u64 v[248:249], s[0:1], 0, v[136:137]
	v_readfirstlane_b32 s0, v157
	s_mov_b32 m0, s0
	s_nop 0
	global_load_lds_dwordx4 v[248:249], off
	s_barrier
	s_waitcnt lgkmcnt(0)
	v_mfma_f32_16x16x32_bf16 v[94:97], v[198:201], v[230:233], v[94:97]
	v_mfma_f32_16x16x32_bf16 v[90:93], v[198:201], v[238:241], v[90:93]
	v_mfma_f32_16x16x32_bf16 v[86:89], v[206:209], v[230:233], v[86:89]
	v_mfma_f32_16x16x32_bf16 v[82:85], v[206:209], v[238:241], v[82:85]
	v_mfma_f32_16x16x32_bf16 v[78:81], v[214:217], v[230:233], v[78:81]
	v_mfma_f32_16x16x32_bf16 v[74:77], v[214:217], v[238:241], v[74:77]
	v_mfma_f32_16x16x32_bf16 v[70:73], v[222:225], v[230:233], v[70:73]
	v_mfma_f32_16x16x32_bf16 v[66:69], v[222:225], v[238:241], v[66:69]
	v_mfma_f32_16x16x32_bf16 v[94:97], v[202:205], v[234:237], v[94:97]
	v_mfma_f32_16x16x32_bf16 v[90:93], v[202:205], v[242:245], v[90:93]
	v_mfma_f32_16x16x32_bf16 v[86:89], v[210:213], v[234:237], v[86:89]
	v_mfma_f32_16x16x32_bf16 v[82:85], v[210:213], v[242:245], v[82:85]
	v_mfma_f32_16x16x32_bf16 v[78:81], v[218:221], v[234:237], v[78:81]
	v_mfma_f32_16x16x32_bf16 v[74:77], v[218:221], v[242:245], v[74:77]
	v_mfma_f32_16x16x32_bf16 v[70:73], v[226:229], v[234:237], v[70:73]
	v_mfma_f32_16x16x32_bf16 v[66:69], v[226:229], v[242:245], v[66:69]
	v_readfirstlane_b32 s0, v158
	v_lshl_add_u64 v[166:167], v[166:167], 0, s[90:91]
	s_mov_b32 m0, s0
	v_readfirstlane_b32 s0, v159
	s_barrier
	ds_read_b128 v[198:201], v143 offset:49152
	ds_read_b128 v[202:205], v143 offset:50176
	ds_read_b128 v[206:209], v143 offset:51200
	ds_read_b128 v[210:213], v143 offset:52224
	ds_read_b128 v[214:217], v143 offset:53248
	ds_read_b128 v[218:221], v143 offset:54272
	ds_read_b128 v[222:225], v143 offset:55296
	ds_read_b128 v[226:229], v143 offset:56320
	global_load_lds_dwordx4 v[166:167], off
	s_mov_b32 m0, s0
	v_lshl_add_u64 v[166:167], v[246:247], 0, s[90:91]
	global_load_lds_dwordx4 v[166:167], off
	s_barrier
; #define G_WAIT_V(n) asm volatile("s_waitcnt vmcnt(" #n ")" ::: "memory")
; #define G_WAIT_L(n) asm volatile("s_waitcnt lgkmcnt(" #n ")" ::: "memory")
; #define G_BAR __builtin_amdgcn_s_barrier()
; #define G_SCHED __builtin_amdgcn_sched_barrier(0)
; DI void br_flush(PREF p, f32x4 (&acc)[2][2][4][2], int slot) { br_store(p, acc, slot); zero_acc256(acc); }
;     ...
;     G_BAR; G_WAIT_L(0); G_MMA(1, 0, At, B0); G_BAR; G_SCHED;
;     G_STAGE(G_SB(1, 1), B, ob0, ob1, LDB, 128, KB(tt + 3));
;     G_WAIT_V(6); G_BAR; G_MMA(1, 1, At, B1); G_BAR;
;     if (MODE && ((tt + 1) & 3) == 3) br_flush(p, acc, (tt + 1) >> 2);
	s_waitcnt lgkmcnt(0)
	v_mfma_f32_16x16x32_bf16 v[62:65], v[198:201], v[182:185], v[62:65]
	v_mfma_f32_16x16x32_bf16 v[58:61], v[198:201], v[190:193], v[58:61]
	v_mfma_f32_16x16x32_bf16 v[54:57], v[206:209], v[182:185], v[54:57]
	v_mfma_f32_16x16x32_bf16 v[50:53], v[206:209], v[190:193], v[50:53]
	v_mfma_f32_16x16x32_bf16 v[46:49], v[214:217], v[182:185], v[46:49]
	v_mfma_f32_16x16x32_bf16 v[42:45], v[214:217], v[190:193], v[42:45]
	v_mfma_f32_16x16x32_bf16 v[38:41], v[222:225], v[182:185], v[38:41]
	v_mfma_f32_16x16x32_bf16 v[34:37], v[222:225], v[190:193], v[34:37]
	v_mfma_f32_16x16x32_bf16 v[62:65], v[202:205], v[186:189], v[62:65]
	v_mfma_f32_16x16x32_bf16 v[58:61], v[202:205], v[194:197], v[58:61]
	v_mfma_f32_16x16x32_bf16 v[54:57], v[210:213], v[186:189], v[54:57]
	v_mfma_f32_16x16x32_bf16 v[50:53], v[210:213], v[194:197], v[50:53]
	v_mfma_f32_16x16x32_bf16 v[46:49], v[218:221], v[186:189], v[46:49]
	v_mfma_f32_16x16x32_bf16 v[42:45], v[218:221], v[194:197], v[42:45]
	v_mfma_f32_16x16x32_bf16 v[38:41], v[226:229], v[186:189], v[38:41]
	v_mfma_f32_16x16x32_bf16 v[34:37], v[226:229], v[194:197], v[34:37]
	s_barrier
	s_add_u32 s0, s28, s35
	s_addc_u32 s1, s29, 0
	v_readfirstlane_b32 s35, v160
	s_mov_b32 m0, s35
	v_lshl_add_u64 v[166:167], s[0:1], 0, v[134:135]
	global_load_lds_dwordx4 v[166:167], off
	v_lshl_add_u64 v[166:167], s[0:1], 0, v[136:137]
	v_readfirstlane_b32 s0, v161
	s_mov_b32 m0, s0
	s_nop 0
	global_load_lds_dwordx4 v[166:167], off
	s_waitcnt vmcnt(6)
	s_barrier
	v_mfma_f32_16x16x32_bf16 v[30:33], v[198:201], v[230:233], v[30:33]
	v_mfma_f32_16x16x32_bf16 v[26:29], v[198:201], v[238:241], v[26:29]
	v_mfma_f32_16x16x32_bf16 v[22:25], v[206:209], v[230:233], v[22:25]
	v_mfma_f32_16x16x32_bf16 v[18:21], v[206:209], v[238:241], v[18:21]
	v_mfma_f32_16x16x32_bf16 v[14:17], v[214:217], v[230:233], v[14:17]
	v_mfma_f32_16x16x32_bf16 v[10:13], v[214:217], v[238:241], v[10:13]
	v_mfma_f32_16x16x32_bf16 v[6:9], v[222:225], v[230:233], v[6:9]
	v_mfma_f32_16x16x32_bf16 v[2:5], v[222:225], v[238:241], v[2:5]
	v_mfma_f32_16x16x32_bf16 v[30:33], v[202:205], v[234:237], v[30:33]
	v_mfma_f32_16x16x32_bf16 v[26:29], v[202:205], v[242:245], v[26:29]
	v_mfma_f32_16x16x32_bf16 v[22:25], v[210:213], v[234:237], v[22:25]
	v_mfma_f32_16x16x32_bf16 v[18:21], v[210:213], v[242:245], v[18:21]
	v_mfma_f32_16x16x32_bf16 v[14:17], v[218:221], v[234:237], v[14:17]
	v_mfma_f32_16x16x32_bf16 v[10:13], v[218:221], v[242:245], v[10:13]
	v_mfma_f32_16x16x32_bf16 v[6:9], v[226:229], v[234:237], v[6:9]
	v_mfma_f32_16x16x32_bf16 v[2:5], v[226:229], v[242:245], v[2:5]
	s_and_b32 s0, s34, 3
	s_cmp_eq_u32 s0, 3
	s_barrier
	s_cbranch_scc0 .LBB0_95
; DI unsigned pack2(float a, float b) { unsigned r; asm("v_cvt_pk_bf16_f32 %0, %1, %2\n\ts_nop 1" : "=v"(r) : "v"(a), "v"(b)); return r; }
; DI u32x4* merge_scratch(PREF p, int region) { const int t = tid512(); return (u32x4*)p.fbuf + (size_t)blockIdx.x * 40960 + region * 8192 + (t >> 6) * 1024 + (t & 63); }
; DI void br_store(PREF p, const f32x4 (&acc)[2][2][4][2], int slot) {
;   u32x4* sb = merge_scratch(p, slot);
; #pragma unroll
;   for (int ai = 0; ai < 2; ++ai)
; #pragma unroll
;     for (int bj = 0; bj < 2; ++bj)
; #pragma unroll
;       for (int m = 0; m < 4; ++m) {
;         u32x4 o;
;         o.x = pack2(acc[ai][bj][m][0][0], acc[ai][bj][m][0][1]); o.y = pack2(acc[ai][bj][m][0][2], acc[ai][bj][m][0][3]);
;         o.z = pack2(acc[ai][bj][m][1][0], acc[ai][bj][m][1][1]); o.w = pack2(acc[ai][bj][m][1][2], acc[ai][bj][m][1][3]);
;         sb[((ai * 2 + bj) * 4 + m) * 64] = o;
;       }
; }
; DI void br_flush(PREF p, f32x4 (&acc)[2][2][4][2], int slot) { br_store(p, acc, slot); zero_acc256(acc); }
	v_mov_b32_e32 v0, v168
	s_and_b32 s0, s12, 0x6000
	s_lshl_b32 s0, s0, 4
	v_lshlrev_b32_e32 v165, 4, v0
	s_add_u32 s0, s63, s0
	v_and_b32_e32 v166, 0xfffffc00, v165
	s_addc_u32 s1, s64, 0
	v_ashrrev_i32_e32 v167, 31, v166
	v_and_b32_e32 v0, 63, v0
	v_lshl_add_u64 v[166:167], v[166:167], 4, s[0:1]
	v_lshlrev_b32_e32 v0, 4, v0
	v_lshl_add_u64 v[166:167], v[166:167], 0, v[0:1]
	v_cvt_pk_bf16_f32 v94, v94, v95
	v_cvt_pk_bf16_f32 v95, v96, v97
	v_cvt_pk_bf16_f32 v96, v90, v91
	v_add_co_u32_e32 v90, vcc, s80, v166
	v_cvt_pk_bf16_f32 v97, v92, v93
	s_movk_i32 s0, 0x3000
	s_nop 0
	v_addc_co_u32_e32 v91, vcc, 0, v167, vcc
	v_add_co_u32_e32 v92, vcc, s40, v166
	v_cvt_pk_bf16_f32 v30, v30, v31
	v_cvt_pk_bf16_f32 v31, v32, v33
	v_cvt_pk_bf16_f32 v32, v26, v27
	v_cvt_pk_bf16_f32 v126, v126, v127
	s_nop 1
	v_addc_co_u32_e32 v93, vcc, 0, v167, vcc
	v_add_co_u32_e32 v26, vcc, s0, v166
	v_cvt_pk_bf16_f32 v127, v128, v129
	v_cvt_pk_bf16_f32 v128, v122, v123
	v_cvt_pk_bf16_f32 v129, v124, v125
	v_cvt_pk_bf16_f32 v118, v118, v119
	v_cvt_pk_bf16_f32 v119, v120, v121
	v_cvt_pk_bf16_f32 v120, v114, v115
	v_cvt_pk_bf16_f32 v121, v116, v117
	v_cvt_pk_bf16_f32 v110, v110, v111
	v_cvt_pk_bf16_f32 v111, v112, v113
	v_cvt_pk_bf16_f32 v112, v106, v107
	v_cvt_pk_bf16_f32 v113, v108, v109
	v_cvt_pk_bf16_f32 v102, v102, v103
	v_cvt_pk_bf16_f32 v103, v104, v105
	v_cvt_pk_bf16_f32 v104, v98, v99
	v_cvt_pk_bf16_f32 v105, v100, v101
	v_cvt_pk_bf16_f32 v86, v86, v87
	v_cvt_pk_bf16_f32 v87, v88, v89
	v_cvt_pk_bf16_f32 v88, v82, v83
	v_cvt_pk_bf16_f32 v89, v84, v85
	v_cvt_pk_bf16_f32 v78, v78, v79
	v_cvt_pk_bf16_f32 v79, v80, v81
	v_cvt_pk_bf16_f32 v80, v74, v75
	v_cvt_pk_bf16_f32 v81, v76, v77
	v_cvt_pk_bf16_f32 v70, v70, v71
	v_cvt_pk_bf16_f32 v71, v72, v73
	v_cvt_pk_bf16_f32 v72, v66, v67
	v_cvt_pk_bf16_f32 v73, v68, v69
	v_cvt_pk_bf16_f32 v62, v62, v63
	v_cvt_pk_bf16_f32 v63, v64, v65
	v_cvt_pk_bf16_f32 v64, v58, v59
	v_cvt_pk_bf16_f32 v65, v60, v61
	v_cvt_pk_bf16_f32 v54, v54, v55
	v_cvt_pk_bf16_f32 v55, v56, v57
	v_cvt_pk_bf16_f32 v56, v50, v51
	v_cvt_pk_bf16_f32 v57, v52, v53
	v_cvt_pk_bf16_f32 v46, v46, v47
	v_cvt_pk_bf16_f32 v47, v48, v49
	v_cvt_pk_bf16_f32 v48, v42, v43
	v_cvt_pk_bf16_f32 v49, v44, v45
	v_cvt_pk_bf16_f32 v38, v38, v39
	v_cvt_pk_bf16_f32 v39, v40, v41
	v_cvt_pk_bf16_f32 v40, v34, v35
	v_cvt_pk_bf16_f32 v41, v36, v37
	v_cvt_pk_bf16_f32 v33, v28, v29
	s_nop 1
	v_addc_co_u32_e32 v27, vcc, 0, v167, vcc
	v_cvt_pk_bf16_f32 v22, v22, v23
	v_cvt_pk_bf16_f32 v23, v24, v25
	v_cvt_pk_bf16_f32 v24, v18, v19
	v_cvt_pk_bf16_f32 v25, v20, v21
	v_cvt_pk_bf16_f32 v14, v14, v15
	v_cvt_pk_bf16_f32 v15, v16, v17
	v_cvt_pk_bf16_f32 v16, v10, v11
	v_cvt_pk_bf16_f32 v17, v12, v13
	v_cvt_pk_bf16_f32 v6, v6, v7
	v_cvt_pk_bf16_f32 v7, v8, v9
	v_cvt_pk_bf16_f32 v8, v2, v3
	v_cvt_pk_bf16_f32 v9, v4, v5
	v_mov_b32_e32 v2, 0
	global_store_dwordx4 v[166:167], v[126:129], off
	global_store_dwordx4 v[166:167], v[118:121], off offset:1024
	global_store_dwordx4 v[166:167], v[110:113], off offset:2048
	global_store_dwordx4 v[166:167], v[102:105], off offset:3072
	global_store_dwordx4 v[92:93], v[94:97], off offset:-4096
	global_store_dwordx4 v[90:91], v[86:89], off offset:1024
	global_store_dwordx4 v[90:91], v[78:81], off offset:2048
	global_store_dwordx4 v[90:91], v[70:73], off offset:3072
	global_store_dwordx4 v[92:93], v[62:65], off
	global_store_dwordx4 v[92:93], v[54:57], off offset:1024
	global_store_dwordx4 v[92:93], v[46:49], off offset:2048
	global_store_dwordx4 v[92:93], v[38:41], off offset:3072
	global_store_dwordx4 v[26:27], v[30:33], off
	global_store_dwordx4 v[26:27], v[22:25], off offset:1024
	global_store_dwordx4 v[26:27], v[14:17], off offset:2048
	global_store_dwordx4 v[26:27], v[6:9], off offset:3072
	v_mov_b32_e32 v3, v2
	v_mov_b32_e32 v4, v2
	v_mov_b32_e32 v5, v2
	v_mov_b32_e32 v6, v2
	v_mov_b32_e32 v7, v2
	v_mov_b32_e32 v8, v2
	v_mov_b32_e32 v9, v2
	v_mov_b32_e32 v10, v2
	v_mov_b32_e32 v11, v2
	v_mov_b32_e32 v12, v2
	v_mov_b32_e32 v13, v2
	v_mov_b32_e32 v14, v2
	v_mov_b32_e32 v15, v2
	v_mov_b32_e32 v16, v2
	v_mov_b32_e32 v17, v2
	v_mov_b32_e32 v18, v2
	v_mov_b32_e32 v19, v2
	v_mov_b32_e32 v20, v2
	v_mov_b32_e32 v21, v2
	v_mov_b32_e32 v22, v2
	v_mov_b32_e32 v23, v2
	v_mov_b32_e32 v24, v2
	v_mov_b32_e32 v25, v2
	v_mov_b32_e32 v26, v2
	v_mov_b32_e32 v27, v2
	v_mov_b32_e32 v28, v2
	v_mov_b32_e32 v29, v2
	v_mov_b32_e32 v30, v2
	v_mov_b32_e32 v31, v2
	v_mov_b32_e32 v32, v2
	v_mov_b32_e32 v33, v2
	v_mov_b32_e32 v34, v2
	v_mov_b32_e32 v35, v2
	v_mov_b32_e32 v36, v2
	v_mov_b32_e32 v37, v2
	v_mov_b32_e32 v38, v2
	v_mov_b32_e32 v39, v2
	v_mov_b32_e32 v40, v2
	v_mov_b32_e32 v41, v2
	v_mov_b32_e32 v42, v2
	v_mov_b32_e32 v43, v2
	v_mov_b32_e32 v44, v2
	v_mov_b32_e32 v45, v2
	v_mov_b32_e32 v46, v2
	v_mov_b32_e32 v47, v2
	v_mov_b32_e32 v48, v2
	v_mov_b32_e32 v49, v2
	v_mov_b32_e32 v50, v2
	v_mov_b32_e32 v51, v2
	v_mov_b32_e32 v52, v2
	v_mov_b32_e32 v53, v2
	v_mov_b32_e32 v54, v2
	v_mov_b32_e32 v55, v2
	v_mov_b32_e32 v56, v2
	v_mov_b32_e32 v57, v2
	v_mov_b32_e32 v58, v2
	v_mov_b32_e32 v59, v2
	v_mov_b32_e32 v60, v2
	v_mov_b32_e32 v61, v2
	v_mov_b32_e32 v62, v2
	v_mov_b32_e32 v63, v2
	v_mov_b32_e32 v64, v2
	v_mov_b32_e32 v65, v2
	v_mov_b32_e32 v66, v2
	v_mov_b32_e32 v67, v2
	v_mov_b32_e32 v68, v2
	v_mov_b32_e32 v69, v2
	v_mov_b32_e32 v70, v2
	v_mov_b32_e32 v71, v2
	v_mov_b32_e32 v72, v2
	v_mov_b32_e32 v73, v2
	v_mov_b32_e32 v74, v2
	v_mov_b32_e32 v75, v2
	v_mov_b32_e32 v76, v2
	v_mov_b32_e32 v77, v2
	v_mov_b32_e32 v78, v2
	v_mov_b32_e32 v79, v2
	v_mov_b32_e32 v80, v2
	v_mov_b32_e32 v81, v2
	v_mov_b32_e32 v82, v2
	v_mov_b32_e32 v83, v2
	v_mov_b32_e32 v84, v2
	v_mov_b32_e32 v85, v2
	v_mov_b32_e32 v86, v2
	v_mov_b32_e32 v87, v2
	v_mov_b32_e32 v88, v2
	v_mov_b32_e32 v89, v2
	v_mov_b32_e32 v90, v2
	v_mov_b32_e32 v91, v2
	v_mov_b32_e32 v92, v2
	v_mov_b32_e32 v93, v2
	v_mov_b32_e32 v94, v2
	v_mov_b32_e32 v95, v2
	v_mov_b32_e32 v96, v2
	v_mov_b32_e32 v97, v2
	v_mov_b32_e32 v98, v2
	v_mov_b32_e32 v99, v2
	v_mov_b32_e32 v100, v2
	v_mov_b32_e32 v101, v2
	v_mov_b32_e32 v102, v2
	v_mov_b32_e32 v103, v2
	v_mov_b32_e32 v104, v2
	v_mov_b32_e32 v105, v2
	v_mov_b32_e32 v106, v2
	v_mov_b32_e32 v107, v2
	v_mov_b32_e32 v108, v2
	v_mov_b32_e32 v109, v2
	v_mov_b32_e32 v110, v2
	v_mov_b32_e32 v111, v2
	v_mov_b32_e32 v112, v2
	v_mov_b32_e32 v113, v2
	v_mov_b32_e32 v114, v2
	v_mov_b32_e32 v115, v2
	v_mov_b32_e32 v116, v2
	v_mov_b32_e32 v117, v2
	v_mov_b32_e32 v118, v2
	v_mov_b32_e32 v119, v2
	v_mov_b32_e32 v120, v2
	v_mov_b32_e32 v121, v2
	v_mov_b32_e32 v122, v2
	v_mov_b32_e32 v123, v2
	v_mov_b32_e32 v124, v2
	v_mov_b32_e32 v125, v2
	v_mov_b32_e32 v126, v2
	v_mov_b32_e32 v127, v2
	v_mov_b32_e32 v128, v2
	v_mov_b32_e32 v129, v2
	s_branch .LBB0_95

; #define G_LDA(dst, b, h)                                                                                                  \
;   _Pragma("unroll") for (int m = 0; m < 4; ++m) _Pragma("unroll") for (int k = 0; k < 2; ++k)                             \
;       dst[m][k] = *(const bf16x8*)((const char*)G_SA(b, h) + ((wr * 4 + m) * 2 + k) * 1024 + rdo)
; #define G_LDB(dst, b, h)                                                                                                  \
;   _Pragma("unroll") for (int n = 0; n < 2; ++n) _Pragma("unroll") for (int k = 0; k < 2; ++k)                             \
;       dst[n][k] = *(const bf16x8*)((const char*)G_SB(b, h) + ((wc * 2 + n) * 2 + k) * 1024 + rdo)
; #define G_WAIT_L(n) asm volatile("s_waitcnt lgkmcnt(" #n ")" ::: "memory")
; #define G_BAR __builtin_amdgcn_s_barrier()
; #define G_SCHED __builtin_amdgcn_sched_barrier(0)
;     ...
;     G_LDB(B0, 0, 0); G_SCHED; G_LDA(At, 0, 0); G_STAGE(G_SA(1, 1), A, oa0, oa1, LDA, 128, KA(tt + 1));
;     G_WAIT_L(8); G_BAR; G_WAIT_L(0); G_MMA(0, 0, At, B0); G_BAR; G_SCHED;
;     G_LDB(B1, 0, 1); G_STAGE(G_SB(0, 0), B, ob0, ob1, LDB, 0, KB(tt + 2));
;     G_BAR; G_WAIT_L(0); G_MMA(0, 1, At, B1); G_BAR;
;     G_LDA(At, 0, 1); G_STAGE(G_SA(0, 0), A, oa0, oa1, LDA, 0, KA(tt + 2));
;     G_BAR; G_WAIT_L(0); G_MMA(1, 0, At, B0); G_BAR; G_SCHED;
.LBB0_105:
	ds_read_b128 v[164:167], v160
	ds_read_b128 v[182:185], v160 offset:1024
	ds_read_b128 v[186:189], v160 offset:2048
	ds_read_b128 v[190:193], v160 offset:3072
	v_add_u32_e32 v161, 0xc000, v143
	v_lshl_add_u64 v[242:243], v[136:137], 0, s[8:9]
	v_readfirstlane_b32 s0, v161
	v_add_u32_e32 v162, 0xe000, v143
	v_lshl_add_u64 v[226:227], v[242:243], 0, s[78:79]
	s_mov_b32 m0, s0
	v_lshl_add_u64 v[244:245], v[134:135], 0, s[8:9]
	v_readfirstlane_b32 s0, v162
	ds_read_b128 v[194:197], v142
	ds_read_b128 v[198:201], v142 offset:1024
	ds_read_b128 v[202:205], v142 offset:2048
	ds_read_b128 v[206:209], v142 offset:3072
	ds_read_b128 v[210:213], v142 offset:4096
	ds_read_b128 v[214:217], v142 offset:5120
	ds_read_b128 v[218:221], v142 offset:6144
	ds_read_b128 v[222:225], v142 offset:7168
	global_load_lds_dwordx4 v[226:227], off
	s_mov_b32 m0, s0
	v_lshl_add_u64 v[226:227], v[244:245], 0, s[78:79]
	global_load_lds_dwordx4 v[226:227], off
	s_waitcnt lgkmcnt(8)
	s_barrier
	s_waitcnt lgkmcnt(0)
	v_mfma_f32_16x16x32_bf16 v[126:129], v[194:197], v[164:167], v[126:129]
	v_mfma_f32_16x16x32_bf16 v[122:125], v[194:197], v[186:189], v[122:125]
	v_mfma_f32_16x16x32_bf16 v[118:121], v[202:205], v[164:167], v[118:121]
	v_mfma_f32_16x16x32_bf16 v[114:117], v[202:205], v[186:189], v[114:117]
	v_mfma_f32_16x16x32_bf16 v[110:113], v[210:213], v[164:167], v[110:113]
	v_mfma_f32_16x16x32_bf16 v[106:109], v[210:213], v[186:189], v[106:109]
	v_mfma_f32_16x16x32_bf16 v[102:105], v[218:221], v[164:167], v[102:105]
	v_mfma_f32_16x16x32_bf16 v[98:101], v[218:221], v[186:189], v[98:101]
	v_mfma_f32_16x16x32_bf16 v[126:129], v[198:201], v[182:185], v[126:129]
	v_mfma_f32_16x16x32_bf16 v[122:125], v[198:201], v[190:193], v[122:125]
	v_mfma_f32_16x16x32_bf16 v[118:121], v[206:209], v[182:185], v[118:121]
	v_mfma_f32_16x16x32_bf16 v[114:117], v[206:209], v[190:193], v[114:117]
	v_mfma_f32_16x16x32_bf16 v[110:113], v[214:217], v[182:185], v[110:113]
	v_mfma_f32_16x16x32_bf16 v[106:109], v[214:217], v[190:193], v[106:109]
	v_mfma_f32_16x16x32_bf16 v[102:105], v[222:225], v[182:185], v[102:105]
	v_mfma_f32_16x16x32_bf16 v[98:101], v[222:225], v[190:193], v[98:101]
	s_barrier
	v_lshl_add_u64 v[246:247], v[140:141], 0, s[8:9]
	v_readfirstlane_b32 s0, v146
	v_lshl_add_u64 v[248:249], v[246:247], 0, s[50:51]
	s_mov_b32 m0, s0
	ds_read_b128 v[226:229], v158
	ds_read_b128 v[230:233], v158 offset:1024
	ds_read_b128 v[234:237], v158 offset:2048
	ds_read_b128 v[238:241], v158 offset:3072
	global_load_lds_dwordx4 v[248:249], off
	v_lshl_add_u64 v[248:249], v[138:139], 0, s[8:9]
	v_readfirstlane_b32 s0, v147
	s_mov_b32 m0, s0
	v_lshl_add_u64 v[250:251], v[248:249], 0, s[50:51]
	global_load_lds_dwordx4 v[250:251], off
	s_barrier
	s_waitcnt lgkmcnt(0)
	v_mfma_f32_16x16x32_bf16 v[94:97], v[194:197], v[226:229], v[94:97]
	v_mfma_f32_16x16x32_bf16 v[90:93], v[194:197], v[234:237], v[90:93]
	v_mfma_f32_16x16x32_bf16 v[86:89], v[202:205], v[226:229], v[86:89]
	v_mfma_f32_16x16x32_bf16 v[82:85], v[202:205], v[234:237], v[82:85]
	v_mfma_f32_16x16x32_bf16 v[78:81], v[210:213], v[226:229], v[78:81]
	v_mfma_f32_16x16x32_bf16 v[74:77], v[210:213], v[234:237], v[74:77]
	v_mfma_f32_16x16x32_bf16 v[70:73], v[218:221], v[226:229], v[70:73]
	v_mfma_f32_16x16x32_bf16 v[66:69], v[218:221], v[234:237], v[66:69]
	v_mfma_f32_16x16x32_bf16 v[94:97], v[198:201], v[230:233], v[94:97]
	v_mfma_f32_16x16x32_bf16 v[90:93], v[198:201], v[238:241], v[90:93]
	v_mfma_f32_16x16x32_bf16 v[86:89], v[206:209], v[230:233], v[86:89]
	v_mfma_f32_16x16x32_bf16 v[82:85], v[206:209], v[238:241], v[82:85]
	v_mfma_f32_16x16x32_bf16 v[78:81], v[214:217], v[230:233], v[78:81]
	v_mfma_f32_16x16x32_bf16 v[74:77], v[214:217], v[238:241], v[74:77]
	v_mfma_f32_16x16x32_bf16 v[70:73], v[222:225], v[230:233], v[70:73]
	v_mfma_f32_16x16x32_bf16 v[66:69], v[222:225], v[238:241], v[66:69]
	v_readfirstlane_b32 s0, v143
	v_lshl_add_u64 v[250:251], v[242:243], 0, s[82:83]
	s_mov_b32 m0, s0
	v_readfirstlane_b32 s0, v144
	s_barrier
	ds_read_b128 v[194:197], v142 offset:16384
	ds_read_b128 v[198:201], v142 offset:17408
	ds_read_b128 v[202:205], v142 offset:18432
	ds_read_b128 v[206:209], v142 offset:19456
	ds_read_b128 v[210:213], v142 offset:20480
	ds_read_b128 v[214:217], v142 offset:21504
	ds_read_b128 v[218:221], v142 offset:22528
	ds_read_b128 v[222:225], v142 offset:23552
	global_load_lds_dwordx4 v[250:251], off
	s_mov_b32 m0, s0
	v_lshl_add_u64 v[250:251], v[244:245], 0, s[82:83]
	global_load_lds_dwordx4 v[250:251], off
	s_barrier
	s_waitcnt lgkmcnt(0)
	v_mfma_f32_16x16x32_bf16 v[62:65], v[194:197], v[164:167], v[62:65]
	v_mfma_f32_16x16x32_bf16 v[58:61], v[194:197], v[186:189], v[58:61]
	v_mfma_f32_16x16x32_bf16 v[54:57], v[202:205], v[164:167], v[54:57]
	v_mfma_f32_16x16x32_bf16 v[50:53], v[202:205], v[186:189], v[50:53]
	v_mfma_f32_16x16x32_bf16 v[46:49], v[210:213], v[164:167], v[46:49]
	v_mfma_f32_16x16x32_bf16 v[42:45], v[210:213], v[186:189], v[42:45]
	v_mfma_f32_16x16x32_bf16 v[38:41], v[218:221], v[164:167], v[38:41]
	v_mfma_f32_16x16x32_bf16 v[34:37], v[218:221], v[186:189], v[34:37]
	v_mfma_f32_16x16x32_bf16 v[62:65], v[198:201], v[182:185], v[62:65]
	v_mfma_f32_16x16x32_bf16 v[58:61], v[198:201], v[190:193], v[58:61]
	v_mfma_f32_16x16x32_bf16 v[54:57], v[206:209], v[182:185], v[54:57]
	v_mfma_f32_16x16x32_bf16 v[50:53], v[206:209], v[190:193], v[50:53]
	v_mfma_f32_16x16x32_bf16 v[46:49], v[214:217], v[182:185], v[46:49]
	v_mfma_f32_16x16x32_bf16 v[42:45], v[214:217], v[190:193], v[42:45]
	v_mfma_f32_16x16x32_bf16 v[38:41], v[222:225], v[182:185], v[38:41]
	v_mfma_f32_16x16x32_bf16 v[34:37], v[222:225], v[190:193], v[34:37]
	s_barrier
; #define G_LDA(dst, b, h)                                                                                                  \
;   _Pragma("unroll") for (int m = 0; m < 4; ++m) _Pragma("unroll") for (int k = 0; k < 2; ++k)                             \
;       dst[m][k] = *(const bf16x8*)((const char*)G_SA(b, h) + ((wr * 4 + m) * 2 + k) * 1024 + rdo)
; #define G_LDB(dst, b, h)                                                                                                  \
;   _Pragma("unroll") for (int n = 0; n < 2; ++n) _Pragma("unroll") for (int k = 0; k < 2; ++k)                             \
;       dst[n][k] = *(const bf16x8*)((const char*)G_SB(b, h) + ((wc * 2 + n) * 2 + k) * 1024 + rdo)
; #define G_WAIT_V(n) asm volatile("s_waitcnt vmcnt(" #n ")" ::: "memory")
; #define G_WAIT_L(n) asm volatile("s_waitcnt lgkmcnt(" #n ")" ::: "memory")
; #define G_BAR __builtin_amdgcn_s_barrier()
; #define G_SCHED __builtin_amdgcn_sched_barrier(0)
;     ...
;     G_STAGE(G_SB(0, 1), B, ob0, ob1, LDB, 128, KB(tt + 2));
;     G_WAIT_V(6); G_BAR; G_MMA(1, 1, At, B1); G_BAR;
;     G_LDB(B0, 1, 0); G_SCHED; G_LDA(At, 1, 0); G_STAGE(G_SA(0, 1), A, oa0, oa1, LDA, 128, KA(tt + 2));
;     G_WAIT_L(8); G_BAR; G_WAIT_L(0); G_MMA(0, 0, At, B0); G_BAR; G_SCHED;
;     G_LDB(B1, 1, 1); G_STAGE(G_SB(1, 0), B, ob0, ob1, LDB, 0, KB(tt + 3));
;     G_BAR; G_WAIT_L(0); G_MMA(0, 1, At, B1); G_BAR;
;     G_LDA(At, 1, 1); G_STAGE(G_SA(1, 0), A, oa0, oa1, LDA, 0, KA(tt + 3));
	v_readfirstlane_b32 s0, v149
	v_lshl_add_u64 v[164:165], v[246:247], 0, s[38:39]
	s_mov_b32 m0, s0
	v_readfirstlane_b32 s0, v150
	global_load_lds_dwordx4 v[164:165], off
	s_mov_b32 m0, s0
	v_lshl_add_u64 v[164:165], v[248:249], 0, s[38:39]
	global_load_lds_dwordx4 v[164:165], off
	s_waitcnt vmcnt(6)
	s_barrier
	v_mfma_f32_16x16x32_bf16 v[30:33], v[194:197], v[226:229], v[30:33]
	v_mfma_f32_16x16x32_bf16 v[26:29], v[194:197], v[234:237], v[26:29]
	v_mfma_f32_16x16x32_bf16 v[22:25], v[202:205], v[226:229], v[22:25]
	v_mfma_f32_16x16x32_bf16 v[18:21], v[202:205], v[234:237], v[18:21]
	v_mfma_f32_16x16x32_bf16 v[14:17], v[210:213], v[226:229], v[14:17]
	v_mfma_f32_16x16x32_bf16 v[10:13], v[210:213], v[234:237], v[10:13]
	v_mfma_f32_16x16x32_bf16 v[6:9], v[218:221], v[226:229], v[6:9]
	v_mfma_f32_16x16x32_bf16 v[2:5], v[218:221], v[234:237], v[2:5]
	v_mfma_f32_16x16x32_bf16 v[30:33], v[198:201], v[230:233], v[30:33]
	v_mfma_f32_16x16x32_bf16 v[26:29], v[198:201], v[238:241], v[26:29]
	v_mfma_f32_16x16x32_bf16 v[22:25], v[206:209], v[230:233], v[22:25]
	v_mfma_f32_16x16x32_bf16 v[18:21], v[206:209], v[238:241], v[18:21]
	v_mfma_f32_16x16x32_bf16 v[14:17], v[214:217], v[230:233], v[14:17]
	v_mfma_f32_16x16x32_bf16 v[10:13], v[214:217], v[238:241], v[10:13]
	v_mfma_f32_16x16x32_bf16 v[6:9], v[222:225], v[230:233], v[6:9]
	v_mfma_f32_16x16x32_bf16 v[2:5], v[222:225], v[238:241], v[2:5]
	s_barrier
	ds_read_b128 v[164:167], v148
	ds_read_b128 v[182:185], v148 offset:1024
	ds_read_b128 v[186:189], v148 offset:2048
	ds_read_b128 v[190:193], v148 offset:3072
	v_readfirstlane_b32 s0, v151
	v_lshl_add_u64 v[226:227], v[242:243], 0, s[86:87]
	s_mov_b32 m0, s0
	v_readfirstlane_b32 s0, v152
	ds_read_b128 v[194:197], v142 offset:32768
	ds_read_b128 v[198:201], v142 offset:33792
	ds_read_b128 v[202:205], v142 offset:34816
	ds_read_b128 v[206:209], v142 offset:35840
	ds_read_b128 v[210:213], v142 offset:36864
	ds_read_b128 v[214:217], v142 offset:37888
	ds_read_b128 v[218:221], v142 offset:38912
	ds_read_b128 v[222:225], v142 offset:39936
	global_load_lds_dwordx4 v[226:227], off
	s_mov_b32 m0, s0
	v_lshl_add_u64 v[226:227], v[244:245], 0, s[86:87]
	global_load_lds_dwordx4 v[226:227], off
	s_waitcnt lgkmcnt(8)
	s_barrier
	s_waitcnt lgkmcnt(0)
	v_mfma_f32_16x16x32_bf16 v[126:129], v[194:197], v[164:167], v[126:129]
	v_mfma_f32_16x16x32_bf16 v[122:125], v[194:197], v[186:189], v[122:125]
	v_mfma_f32_16x16x32_bf16 v[118:121], v[202:205], v[164:167], v[118:121]
	v_mfma_f32_16x16x32_bf16 v[114:117], v[202:205], v[186:189], v[114:117]
	v_mfma_f32_16x16x32_bf16 v[110:113], v[210:213], v[164:167], v[110:113]
	v_mfma_f32_16x16x32_bf16 v[106:109], v[210:213], v[186:189], v[106:109]
	v_mfma_f32_16x16x32_bf16 v[102:105], v[218:221], v[164:167], v[102:105]
	v_mfma_f32_16x16x32_bf16 v[98:101], v[218:221], v[186:189], v[98:101]
	v_mfma_f32_16x16x32_bf16 v[126:129], v[198:201], v[182:185], v[126:129]
	v_mfma_f32_16x16x32_bf16 v[122:125], v[198:201], v[190:193], v[122:125]
	v_mfma_f32_16x16x32_bf16 v[118:121], v[206:209], v[182:185], v[118:121]
	v_mfma_f32_16x16x32_bf16 v[114:117], v[206:209], v[190:193], v[114:117]
	v_mfma_f32_16x16x32_bf16 v[110:113], v[214:217], v[182:185], v[110:113]
	v_mfma_f32_16x16x32_bf16 v[106:109], v[214:217], v[190:193], v[106:109]
	v_mfma_f32_16x16x32_bf16 v[102:105], v[222:225], v[182:185], v[102:105]
	v_mfma_f32_16x16x32_bf16 v[98:101], v[222:225], v[190:193], v[98:101]
	s_barrier
	v_readfirstlane_b32 s0, v153
	v_lshl_add_u64 v[250:251], v[246:247], 0, s[4:5]
	s_mov_b32 m0, s0
	v_readfirstlane_b32 s0, v154
	ds_read_b128 v[226:229], v145
	ds_read_b128 v[230:233], v145 offset:1024
	ds_read_b128 v[234:237], v145 offset:2048
	ds_read_b128 v[238:241], v145 offset:3072
	global_load_lds_dwordx4 v[250:251], off
	s_mov_b32 m0, s0
	v_lshl_add_u64 v[250:251], v[248:249], 0, s[4:5]
	global_load_lds_dwordx4 v[250:251], off
	s_barrier
	s_waitcnt lgkmcnt(0)
	v_mfma_f32_16x16x32_bf16 v[94:97], v[194:197], v[226:229], v[94:97]
	v_mfma_f32_16x16x32_bf16 v[90:93], v[194:197], v[234:237], v[90:93]
	v_mfma_f32_16x16x32_bf16 v[86:89], v[202:205], v[226:229], v[86:89]
	v_mfma_f32_16x16x32_bf16 v[82:85], v[202:205], v[234:237], v[82:85]
	v_mfma_f32_16x16x32_bf16 v[78:81], v[210:213], v[226:229], v[78:81]
	v_mfma_f32_16x16x32_bf16 v[74:77], v[210:213], v[234:237], v[74:77]
	v_mfma_f32_16x16x32_bf16 v[70:73], v[218:221], v[226:229], v[70:73]
	v_mfma_f32_16x16x32_bf16 v[66:69], v[218:221], v[234:237], v[66:69]
	v_mfma_f32_16x16x32_bf16 v[94:97], v[198:201], v[230:233], v[94:97]
	v_mfma_f32_16x16x32_bf16 v[90:93], v[198:201], v[238:241], v[90:93]
	v_mfma_f32_16x16x32_bf16 v[86:89], v[206:209], v[230:233], v[86:89]
	v_mfma_f32_16x16x32_bf16 v[82:85], v[206:209], v[238:241], v[82:85]
	v_mfma_f32_16x16x32_bf16 v[78:81], v[214:217], v[230:233], v[78:81]
	v_mfma_f32_16x16x32_bf16 v[74:77], v[214:217], v[238:241], v[74:77]
	v_mfma_f32_16x16x32_bf16 v[70:73], v[222:225], v[230:233], v[70:73]
	v_mfma_f32_16x16x32_bf16 v[66:69], v[222:225], v[238:241], v[66:69]
	v_readfirstlane_b32 s0, v155
	v_lshl_add_u64 v[242:243], v[242:243], 0, s[90:91]
	s_mov_b32 m0, s0
	v_readfirstlane_b32 s0, v156
	s_barrier
	ds_read_b128 v[194:197], v142 offset:49152
	ds_read_b128 v[198:201], v142 offset:50176
	ds_read_b128 v[202:205], v142 offset:51200
	ds_read_b128 v[206:209], v142 offset:52224
	ds_read_b128 v[210:213], v142 offset:53248
	ds_read_b128 v[214:217], v142 offset:54272
	ds_read_b128 v[218:221], v142 offset:55296
	ds_read_b128 v[222:225], v142 offset:56320
	global_load_lds_dwordx4 v[242:243], off
	s_mov_b32 m0, s0
	v_lshl_add_u64 v[242:243], v[244:245], 0, s[90:91]
	global_load_lds_dwordx4 v[242:243], off
	s_barrier
; DI int tid512() { int t = threadIdx.x; asm volatile("" : "+v"(t)); return t; }
; #define G_LDA(dst, b, h)                                                                                                  \
;   _Pragma("unroll") for (int m = 0; m < 4; ++m) _Pragma("unroll") for (int k = 0; k < 2; ++k)                             \
;       dst[m][k] = *(const bf16x8*)((const char*)G_SA(b, h) + ((wr * 4 + m) * 2 + k) * 1024 + rdo)
; #define G_LDB(dst, b, h)                                                                                                  \
;   _Pragma("unroll") for (int n = 0; n < 2; ++n) _Pragma("unroll") for (int k = 0; k < 2; ++k)                             \
;       dst[n][k] = *(const bf16x8*)((const char*)G_SB(b, h) + ((wc * 2 + n) * 2 + k) * 1024 + rdo)
; #define G_WAIT_V(n) asm volatile("s_waitcnt vmcnt(" #n ")" ::: "memory")
; #define G_WAIT_L(n) asm volatile("s_waitcnt lgkmcnt(" #n ")" ::: "memory")
; #define G_BAR __builtin_amdgcn_s_barrier()
; #define G_SCHED __builtin_amdgcn_sched_barrier(0)
; DI u32x4* merge_scratch(PREF p, int region) { const int t = tid512(); return (u32x4*)p.fbuf + (size_t)blockIdx.x * 40960 + region * 8192 + (t >> 6) * 1024 + (t & 63); }
; DI void br_flush(PREF p, f32x4 (&acc)[2][2][4][2], int slot) { br_store(p, acc, slot); zero_acc256(acc); }
;     ...
;     G_BAR; G_WAIT_L(0); G_MMA(1, 0, At, B0); G_BAR; G_SCHED;
;     G_STAGE(G_SB(1, 1), B, ob0, ob1, LDB, 128, KB(tt + 3));
;     G_WAIT_V(6); G_BAR; G_MMA(1, 1, At, B1); G_BAR;
;     if (MODE && ((tt + 1) & 3) == 3) br_flush(p, acc, (tt + 1) >> 2);
;   }
;   {
;     G_LDB(B0, 0, 0); G_LDA(At, 0, 0); G_STAGE(G_SA(1, 1), A, oa0, oa1, LDA, 128, KA(nt - 1));
;     G_BAR; G_WAIT_L(0); G_MMA(0, 0, At, B0); G_BAR;
; DI void gate_reg(PREF p, int l, int n, f32x4 (&acc)[2][2][4][2], int dt) {
;   const u32x4* sbn = merge_scratch(p, n);
;   u32x4* ssum = merge_scratch(p, 4);
;   const int t = tid512(), wid = t >> 6, lane = t & 63, wc = wid & 3, fr = lane & 15;
;   const float* bm = p.b_merge + (size_t)l * 4096 + n * 1024 + dt * 256 + wc * 32 + fr;
;   float bias[2][2];
; #pragma unroll
;   for (int bj = 0; bj < 2; ++bj)
; #pragma unroll
;     for (int nn = 0; nn < 2; ++nn) bias[bj][nn] = bm[bj * 128 + nn * 16];
	s_waitcnt lgkmcnt(0)
	v_mfma_f32_16x16x32_bf16 v[62:65], v[194:197], v[164:167], v[62:65]
	v_mfma_f32_16x16x32_bf16 v[58:61], v[194:197], v[186:189], v[58:61]
	v_mfma_f32_16x16x32_bf16 v[54:57], v[202:205], v[164:167], v[54:57]
	v_mfma_f32_16x16x32_bf16 v[50:53], v[202:205], v[186:189], v[50:53]
	v_mfma_f32_16x16x32_bf16 v[46:49], v[210:213], v[164:167], v[46:49]
	v_mfma_f32_16x16x32_bf16 v[42:45], v[210:213], v[186:189], v[42:45]
	v_mfma_f32_16x16x32_bf16 v[38:41], v[218:221], v[164:167], v[38:41]
	v_mfma_f32_16x16x32_bf16 v[34:37], v[218:221], v[186:189], v[34:37]
	v_mfma_f32_16x16x32_bf16 v[62:65], v[198:201], v[182:185], v[62:65]
	v_mfma_f32_16x16x32_bf16 v[58:61], v[198:201], v[190:193], v[58:61]
	v_mfma_f32_16x16x32_bf16 v[54:57], v[206:209], v[182:185], v[54:57]
	v_mfma_f32_16x16x32_bf16 v[50:53], v[206:209], v[190:193], v[50:53]
	v_mfma_f32_16x16x32_bf16 v[46:49], v[214:217], v[182:185], v[46:49]
	v_mfma_f32_16x16x32_bf16 v[42:45], v[214:217], v[190:193], v[42:45]
	v_mfma_f32_16x16x32_bf16 v[38:41], v[222:225], v[182:185], v[38:41]
	v_mfma_f32_16x16x32_bf16 v[34:37], v[222:225], v[190:193], v[34:37]
	s_barrier
	v_readfirstlane_b32 s0, v157
	v_lshl_add_u64 v[164:165], v[246:247], 0, s[74:75]
	s_mov_b32 m0, s0
	v_readfirstlane_b32 s0, v159
	global_load_lds_dwordx4 v[164:165], off
	s_mov_b32 m0, s0
	v_lshl_add_u64 v[164:165], v[248:249], 0, s[74:75]
	global_load_lds_dwordx4 v[164:165], off
	s_waitcnt vmcnt(6)
	s_barrier
	v_mfma_f32_16x16x32_bf16 v[30:33], v[194:197], v[226:229], v[30:33]
	v_mfma_f32_16x16x32_bf16 v[26:29], v[194:197], v[234:237], v[26:29]
	v_mfma_f32_16x16x32_bf16 v[22:25], v[202:205], v[226:229], v[22:25]
	v_mfma_f32_16x16x32_bf16 v[18:21], v[202:205], v[234:237], v[18:21]
	v_mfma_f32_16x16x32_bf16 v[14:17], v[210:213], v[226:229], v[14:17]
	v_mfma_f32_16x16x32_bf16 v[10:13], v[210:213], v[234:237], v[10:13]
	v_mfma_f32_16x16x32_bf16 v[6:9], v[218:221], v[226:229], v[6:9]
	v_mfma_f32_16x16x32_bf16 v[2:5], v[218:221], v[234:237], v[2:5]
	v_mfma_f32_16x16x32_bf16 v[30:33], v[198:201], v[230:233], v[30:33]
	v_mfma_f32_16x16x32_bf16 v[26:29], v[198:201], v[238:241], v[26:29]
	v_mfma_f32_16x16x32_bf16 v[22:25], v[206:209], v[230:233], v[22:25]
	v_mfma_f32_16x16x32_bf16 v[18:21], v[206:209], v[238:241], v[18:21]
	v_mfma_f32_16x16x32_bf16 v[14:17], v[214:217], v[230:233], v[14:17]
	v_mfma_f32_16x16x32_bf16 v[10:13], v[214:217], v[238:241], v[10:13]
	v_mfma_f32_16x16x32_bf16 v[6:9], v[222:225], v[230:233], v[6:9]
	v_mfma_f32_16x16x32_bf16 v[2:5], v[222:225], v[238:241], v[2:5]
	s_add_i32 s10, s10, 2
	s_add_u32 s8, s8, 0x100
	s_addc_u32 s9, s9, 0
	s_cmp_lt_u32 s10, 12
	s_barrier
	s_cbranch_scc1 .LBB0_105
	v_readfirstlane_b32 s0, v161
	v_lshl_add_u64 v[132:133], v[132:133], 1, s[34:35]
	s_mov_b32 m0, s0
	v_readfirstlane_b32 s0, v162
	ds_read_b128 v[134:137], v160
	ds_read_b128 v[138:141], v160 offset:1024
	ds_read_b128 v[150:153], v160 offset:2048
	ds_read_b128 v[154:157], v160 offset:3072
	ds_read_b128 v[164:167], v142
	ds_read_b128 v[182:185], v142 offset:1024
	ds_read_b128 v[186:189], v142 offset:2048
	ds_read_b128 v[190:193], v142 offset:3072
	ds_read_b128 v[194:197], v142 offset:4096
	ds_read_b128 v[198:201], v142 offset:5120
	ds_read_b128 v[202:205], v142 offset:6144
	ds_read_b128 v[206:209], v142 offset:7168
	global_load_lds_dwordx4 v[132:133], off
	s_mov_b32 m0, s0
	v_lshl_add_u64 v[130:131], v[130:131], 1, s[34:35]
	global_load_lds_dwordx4 v[130:131], off
	s_lshl_b32 s1, s23, 8
	s_add_u32 s98, s25, s1
	s_addc_u32 s99, s48, 0
	v_bfe_u32 v251, v168, 6, 2
	v_lshlrev_b32_e32 v248, 6, v251
	v_and_b32_e32 v250, 15, v168
	v_lshl_or_b32 v248, v250, 2, v248
	global_load_dword v170, v248, s[98:99]
	s_add_u32 s98, s98, 0x1000
	s_addc_u32 s99, s99, 0
	global_load_dword v252, v248, s[98:99]
	s_add_u32 s98, s98, 0x1000
	s_addc_u32 s99, s99, 0
	global_load_dword v253, v248, s[98:99]
	s_add_u32 s98, s98, 0x1000
	s_addc_u32 s99, s99, 0
	global_load_dword v162, v248, s[98:99]
	s_lshl_b32 s1, s23, 1
	v_lshrrev_b32_e32 v249, 1, v251
	v_add_u32_e32 v249, s1, v249
	v_and_b32_e32 v249, 3, v249
	v_lshrrev_b32_e32 v250, 8, v168
	v_lshl_add_u32 v249, v250, 2, v249
	v_lshlrev_b32_e32 v249, 14, v249
	v_and_b32_e32 v250, 63, v168
	v_lshl_or_b32 v249, v250, 4, v249
	v_and_b32_e32 v250, 1, v251
	v_lshl_or_b32 v249, v250, 3, v249
	s_lshr_b32 s1, s23, 1
	s_lshl_b32 s1, s1, 12
	s_add_u32 s20, s63, s1
	s_addc_u32 s21, s64, 0
	global_load_dwordx2 v[230:231], v249, s[20:21] offset:0
	global_load_dwordx2 v[238:239], v249, s[20:21] offset:1024
	s_add_u32 s20, s20, 0x20000
	s_addc_u32 s21, s21, 0
	global_load_dwordx2 v[232:233], v249, s[20:21] offset:0
	global_load_dwordx2 v[240:241], v249, s[20:21] offset:1024
	s_add_u32 s20, s20, 0x20000
	s_addc_u32 s21, s21, 0
	global_load_dwordx2 v[234:235], v249, s[20:21] offset:0
	global_load_dwordx2 v[242:243], v249, s[20:21] offset:1024
	s_add_u32 s20, s20, 0x20000
	s_addc_u32 s21, s21, 0
	global_load_dwordx2 v[236:237], v249, s[20:21] offset:0
	global_load_dwordx2 v[244:245], v249, s[20:21] offset:1024
	s_barrier
	s_waitcnt lgkmcnt(0)
	v_mfma_f32_16x16x32_bf16 v[126:129], v[164:167], v[134:137], v[126:129]
	v_mfma_f32_16x16x32_bf16 v[122:125], v[164:167], v[150:153], v[122:125]
	v_mfma_f32_16x16x32_bf16 v[114:117], v[186:189], v[150:153], v[114:117]
	v_mfma_f32_16x16x32_bf16 v[110:113], v[194:197], v[134:137], v[110:113]
	v_mfma_f32_16x16x32_bf16 v[106:109], v[194:197], v[150:153], v[106:109]
	v_mfma_f32_16x16x32_bf16 v[102:105], v[202:205], v[134:137], v[102:105]
	v_mfma_f32_16x16x32_bf16 v[98:101], v[202:205], v[150:153], v[98:101]
	v_mfma_f32_16x16x32_bf16 v[126:129], v[182:185], v[138:141], v[126:129]
	v_mfma_f32_16x16x32_bf16 v[122:125], v[182:185], v[154:157], v[122:125]
	v_mfma_f32_16x16x32_bf16 v[118:121], v[186:189], v[134:137], v[118:121]
	v_mfma_f32_16x16x32_bf16 v[114:117], v[190:193], v[154:157], v[114:117]
	v_mfma_f32_16x16x32_bf16 v[110:113], v[198:201], v[138:141], v[110:113]
	v_mfma_f32_16x16x32_bf16 v[106:109], v[198:201], v[154:157], v[106:109]
	v_mfma_f32_16x16x32_bf16 v[102:105], v[206:209], v[138:141], v[102:105]
	v_mfma_f32_16x16x32_bf16 v[98:101], v[206:209], v[154:157], v[98:101]
	v_mfma_f32_16x16x32_bf16 v[118:121], v[190:193], v[138:141], v[118:121]
	s_barrier
; #define G_LDA(dst, b, h)                                                                                                  \
;   _Pragma("unroll") for (int m = 0; m < 4; ++m) _Pragma("unroll") for (int k = 0; k < 2; ++k)                             \
;       dst[m][k] = *(const bf16x8*)((const char*)G_SA(b, h) + ((wr * 4 + m) * 2 + k) * 1024 + rdo)
; #define G_LDB(dst, b, h)                                                                                                  \
;   _Pragma("unroll") for (int n = 0; n < 2; ++n) _Pragma("unroll") for (int k = 0; k < 2; ++k)                             \
;       dst[n][k] = *(const bf16x8*)((const char*)G_SB(b, h) + ((wc * 2 + n) * 2 + k) * 1024 + rdo)
; #define G_WAIT_V(n) asm volatile("s_waitcnt vmcnt(" #n ")" ::: "memory")
; #define G_WAIT_L(n) asm volatile("s_waitcnt lgkmcnt(" #n ")" ::: "memory")
; #define G_BAR __builtin_amdgcn_s_barrier()
;     ...
;     G_LDB(B1, 0, 1); G_BAR; G_WAIT_L(0); G_MMA(0, 1, At, B1); G_BAR;
;     G_LDA(At, 0, 1); G_WAIT_V(4); G_BAR; G_WAIT_L(0); G_MMA(1, 0, At, B0); G_MMA(1, 1, At, B1); G_BAR;
;   }
;   {
;     G_LDB(B0, 1, 0); G_LDA(At, 1, 0); G_WAIT_V(2); G_BAR; G_WAIT_L(0); G_MMA(0, 0, At, B0); G_BAR;
;     G_LDB(B1, 1, 1); G_WAIT_V(0); G_BAR; G_WAIT_L(0); G_MMA(0, 1, At, B1); G_BAR;
	ds_read_b128 v[130:133], v158
	ds_read_b128 v[210:213], v158 offset:1024
	ds_read_b128 v[214:217], v158 offset:2048
	ds_read_b128 v[158:161], v158 offset:3072
	s_barrier
	s_waitcnt lgkmcnt(0)
	v_mfma_f32_16x16x32_bf16 v[94:97], v[164:167], v[130:133], v[94:97]
	v_mfma_f32_16x16x32_bf16 v[90:93], v[164:167], v[214:217], v[90:93]
	v_mfma_f32_16x16x32_bf16 v[86:89], v[186:189], v[130:133], v[86:89]
	v_mfma_f32_16x16x32_bf16 v[82:85], v[186:189], v[214:217], v[82:85]
	v_mfma_f32_16x16x32_bf16 v[78:81], v[194:197], v[130:133], v[78:81]
	v_mfma_f32_16x16x32_bf16 v[74:77], v[194:197], v[214:217], v[74:77]
	v_mfma_f32_16x16x32_bf16 v[70:73], v[202:205], v[130:133], v[70:73]
	v_mfma_f32_16x16x32_bf16 v[66:69], v[202:205], v[214:217], v[66:69]
	v_mfma_f32_16x16x32_bf16 v[94:97], v[182:185], v[210:213], v[94:97]
	v_mfma_f32_16x16x32_bf16 v[90:93], v[182:185], v[158:161], v[90:93]
	v_mfma_f32_16x16x32_bf16 v[86:89], v[190:193], v[210:213], v[86:89]
	v_mfma_f32_16x16x32_bf16 v[82:85], v[190:193], v[158:161], v[82:85]
	v_mfma_f32_16x16x32_bf16 v[78:81], v[198:201], v[210:213], v[78:81]
	v_mfma_f32_16x16x32_bf16 v[74:77], v[198:201], v[158:161], v[74:77]
	v_mfma_f32_16x16x32_bf16 v[70:73], v[206:209], v[210:213], v[70:73]
	v_mfma_f32_16x16x32_bf16 v[66:69], v[206:209], v[158:161], v[66:69]
	s_barrier
	ds_read_b128 v[164:167], v142 offset:16384
	ds_read_b128 v[182:185], v142 offset:17408
	ds_read_b128 v[186:189], v142 offset:18432
	ds_read_b128 v[190:193], v142 offset:19456
	ds_read_b128 v[194:197], v142 offset:20480
	ds_read_b128 v[198:201], v142 offset:21504
	ds_read_b128 v[202:205], v142 offset:22528
	ds_read_b128 v[206:209], v142 offset:23552
	s_waitcnt vmcnt(16)
	s_barrier
	s_waitcnt lgkmcnt(0)
	v_mfma_f32_16x16x32_bf16 v[62:65], v[164:167], v[134:137], v[62:65]
	v_mfma_f32_16x16x32_bf16 v[58:61], v[164:167], v[150:153], v[58:61]
	v_mfma_f32_16x16x32_bf16 v[54:57], v[186:189], v[134:137], v[54:57]
	v_mfma_f32_16x16x32_bf16 v[50:53], v[186:189], v[150:153], v[50:53]
	v_mfma_f32_16x16x32_bf16 v[46:49], v[194:197], v[134:137], v[46:49]
	v_mfma_f32_16x16x32_bf16 v[38:41], v[202:205], v[134:137], v[38:41]
	v_mfma_f32_16x16x32_bf16 v[34:37], v[202:205], v[150:153], v[34:37]
	v_mfma_f32_16x16x32_bf16 v[62:65], v[182:185], v[138:141], v[62:65]
	v_mfma_f32_16x16x32_bf16 v[58:61], v[182:185], v[154:157], v[58:61]
	v_mfma_f32_16x16x32_bf16 v[54:57], v[190:193], v[138:141], v[54:57]
	v_mfma_f32_16x16x32_bf16 v[50:53], v[190:193], v[154:157], v[50:53]
	v_mfma_f32_16x16x32_bf16 v[46:49], v[198:201], v[138:141], v[46:49]
	v_mfma_f32_16x16x32_bf16 v[42:45], v[194:197], v[150:153], v[42:45]
	v_mfma_f32_16x16x32_bf16 v[38:41], v[206:209], v[138:141], v[38:41]
	v_mfma_f32_16x16x32_bf16 v[34:37], v[206:209], v[154:157], v[34:37]
	v_mfma_f32_16x16x32_bf16 v[42:45], v[198:201], v[154:157], v[42:45]
	v_mfma_f32_16x16x32_bf16 v[26:29], v[164:167], v[214:217], v[26:29]
	v_mfma_f32_16x16x32_bf16 v[22:25], v[186:189], v[130:133], v[22:25]
	v_mfma_f32_16x16x32_bf16 v[14:17], v[194:197], v[130:133], v[14:17]
	v_mfma_f32_16x16x32_bf16 v[10:13], v[194:197], v[214:217], v[10:13]
	v_mfma_f32_16x16x32_bf16 v[2:5], v[202:205], v[214:217], v[2:5]
	v_mfma_f32_16x16x32_bf16 v[30:33], v[164:167], v[130:133], v[30:33]
	v_mfma_f32_16x16x32_bf16 v[26:29], v[182:185], v[158:161], v[26:29]
	v_mfma_f32_16x16x32_bf16 v[22:25], v[190:193], v[210:213], v[22:25]
	v_mfma_f32_16x16x32_bf16 v[18:21], v[186:189], v[214:217], v[18:21]
	v_mfma_f32_16x16x32_bf16 v[14:17], v[198:201], v[210:213], v[14:17]
	v_mfma_f32_16x16x32_bf16 v[10:13], v[198:201], v[158:161], v[10:13]
	v_mfma_f32_16x16x32_bf16 v[6:9], v[202:205], v[130:133], v[6:9]
	v_mfma_f32_16x16x32_bf16 v[2:5], v[206:209], v[158:161], v[2:5]
	v_mfma_f32_16x16x32_bf16 v[30:33], v[182:185], v[210:213], v[30:33]
	v_mfma_f32_16x16x32_bf16 v[18:21], v[190:193], v[158:161], v[18:21]
	v_mfma_f32_16x16x32_bf16 v[6:9], v[206:209], v[210:213], v[6:9]
	s_barrier
	ds_read_b128 v[130:133], v148
	ds_read_b128 v[154:157], v148 offset:1024
	ds_read_b128 v[164:167], v148 offset:2048
	ds_read_b128 v[182:185], v148 offset:3072
	ds_read_b128 v[186:189], v142 offset:32768
	ds_read_b128 v[190:193], v142 offset:33792
	ds_read_b128 v[194:197], v142 offset:34816
	ds_read_b128 v[198:201], v142 offset:35840
	ds_read_b128 v[202:205], v142 offset:36864
	ds_read_b128 v[206:209], v142 offset:37888
	ds_read_b128 v[210:213], v142 offset:38912
	ds_read_b128 v[214:217], v142 offset:39936
	s_waitcnt vmcnt(14)
	s_barrier
; #define G_LDA(dst, b, h)                                                                                                  \
;   _Pragma("unroll") for (int m = 0; m < 4; ++m) _Pragma("unroll") for (int k = 0; k < 2; ++k)                             \
;       dst[m][k] = *(const bf16x8*)((const char*)G_SA(b, h) + ((wr * 4 + m) * 2 + k) * 1024 + rdo)
; #define G_LDB(dst, b, h)                                                                                                  \
;   _Pragma("unroll") for (int n = 0; n < 2; ++n) _Pragma("unroll") for (int k = 0; k < 2; ++k)                             \
;       dst[n][k] = *(const bf16x8*)((const char*)G_SB(b, h) + ((wc * 2 + n) * 2 + k) * 1024 + rdo)
; #define G_WAIT_V(n) asm volatile("s_waitcnt vmcnt(" #n ")" ::: "memory")
; #define G_WAIT_L(n) asm volatile("s_waitcnt lgkmcnt(" #n ")" ::: "memory")
; #define G_BAR __builtin_amdgcn_s_barrier()
;     ...
;     G_LDB(B1, 1, 1); G_WAIT_V(0); G_BAR; G_WAIT_L(0); G_MMA(0, 1, At, B1); G_BAR;
;     G_LDA(At, 1, 1); G_BAR; G_WAIT_L(0); G_MMA(1, 0, At, B0); G_MMA(1, 1, At, B1); G_BAR;
;   }
;   if (wr == 0) G_BAR;
	s_waitcnt lgkmcnt(0)
	v_mfma_f32_16x16x32_bf16 v[126:129], v[186:189], v[130:133], v[126:129]
	v_mfma_f32_16x16x32_bf16 v[122:125], v[186:189], v[164:167], v[122:125]
	v_mfma_f32_16x16x32_bf16 v[118:121], v[194:197], v[130:133], v[118:121]
	v_mfma_f32_16x16x32_bf16 v[114:117], v[194:197], v[164:167], v[114:117]
	v_mfma_f32_16x16x32_bf16 v[110:113], v[202:205], v[130:133], v[110:113]
	v_mfma_f32_16x16x32_bf16 v[106:109], v[202:205], v[164:167], v[106:109]
	v_mfma_f32_16x16x32_bf16 v[102:105], v[210:213], v[130:133], v[102:105]
	v_mfma_f32_16x16x32_bf16 v[98:101], v[210:213], v[164:167], v[98:101]
	v_mfma_f32_16x16x32_bf16 v[158:161], v[190:193], v[154:157], v[126:129]
	v_mfma_f32_16x16x32_bf16 v[150:153], v[190:193], v[182:185], v[122:125]
	v_mfma_f32_16x16x32_bf16 v[146:149], v[198:201], v[154:157], v[118:121]
	v_mfma_f32_16x16x32_bf16 v[138:141], v[198:201], v[182:185], v[114:117]
	v_mfma_f32_16x16x32_bf16 v[134:137], v[206:209], v[154:157], v[110:113]
	v_mfma_f32_16x16x32_bf16 v[126:129], v[206:209], v[182:185], v[106:109]
	v_mfma_f32_16x16x32_bf16 v[122:125], v[214:217], v[154:157], v[102:105]
	v_mfma_f32_16x16x32_bf16 v[114:117], v[214:217], v[182:185], v[98:101]
	s_barrier
	ds_read_b128 v[118:121], v145
	ds_read_b128 v[218:221], v145 offset:1024
	ds_read_b128 v[222:225], v145 offset:2048
	ds_read_b128 v[226:229], v145 offset:3072
	s_waitcnt vmcnt(12)
	s_barrier
	s_waitcnt lgkmcnt(0)
	v_mfma_f32_16x16x32_bf16 v[94:97], v[186:189], v[118:121], v[94:97]
	v_mfma_f32_16x16x32_bf16 v[90:93], v[186:189], v[222:225], v[90:93]
	v_mfma_f32_16x16x32_bf16 v[86:89], v[194:197], v[118:121], v[86:89]
	v_mfma_f32_16x16x32_bf16 v[82:85], v[194:197], v[222:225], v[82:85]
	v_mfma_f32_16x16x32_bf16 v[78:81], v[202:205], v[118:121], v[78:81]
	v_mfma_f32_16x16x32_bf16 v[74:77], v[202:205], v[222:225], v[74:77]
	v_mfma_f32_16x16x32_bf16 v[70:73], v[210:213], v[118:121], v[70:73]
	v_mfma_f32_16x16x32_bf16 v[66:69], v[210:213], v[222:225], v[66:69]
	v_mfma_f32_16x16x32_bf16 v[110:113], v[190:193], v[218:221], v[94:97]
	v_mfma_f32_16x16x32_bf16 v[106:109], v[190:193], v[226:229], v[90:93]
	v_mfma_f32_16x16x32_bf16 v[102:105], v[198:201], v[218:221], v[86:89]
	v_mfma_f32_16x16x32_bf16 v[98:101], v[198:201], v[226:229], v[82:85]
	v_mfma_f32_16x16x32_bf16 v[94:97], v[206:209], v[218:221], v[78:81]
	v_mfma_f32_16x16x32_bf16 v[90:93], v[206:209], v[226:229], v[74:77]
	v_mfma_f32_16x16x32_bf16 v[86:89], v[214:217], v[218:221], v[70:73]
	v_mfma_f32_16x16x32_bf16 v[82:85], v[214:217], v[226:229], v[66:69]
	s_barrier
	ds_read_b128 v[186:189], v142 offset:49152
	ds_read_b128 v[190:193], v142 offset:50176
	ds_read_b128 v[194:197], v142 offset:51200
	ds_read_b128 v[198:201], v142 offset:52224
	ds_read_b128 v[202:205], v142 offset:53248
	ds_read_b128 v[206:209], v142 offset:54272
	ds_read_b128 v[210:213], v142 offset:55296
	ds_read_b128 v[142:145], v142 offset:56320
	s_barrier
	s_waitcnt lgkmcnt(0)
	v_mfma_f32_16x16x32_bf16 v[62:65], v[186:189], v[130:133], v[62:65]
	v_mfma_f32_16x16x32_bf16 v[58:61], v[186:189], v[164:167], v[58:61]
	v_mfma_f32_16x16x32_bf16 v[54:57], v[194:197], v[130:133], v[54:57]
	v_mfma_f32_16x16x32_bf16 v[50:53], v[194:197], v[164:167], v[50:53]
	v_mfma_f32_16x16x32_bf16 v[46:49], v[202:205], v[130:133], v[46:49]
	v_mfma_f32_16x16x32_bf16 v[42:45], v[202:205], v[164:167], v[42:45]
	v_mfma_f32_16x16x32_bf16 v[38:41], v[210:213], v[130:133], v[38:41]
	v_mfma_f32_16x16x32_bf16 v[34:37], v[210:213], v[164:167], v[34:37]
	v_mfma_f32_16x16x32_bf16 v[78:81], v[190:193], v[154:157], v[62:65]
	v_mfma_f32_16x16x32_bf16 v[74:77], v[190:193], v[182:185], v[58:61]
	v_mfma_f32_16x16x32_bf16 v[70:73], v[198:201], v[154:157], v[54:57]
	v_mfma_f32_16x16x32_bf16 v[66:69], v[198:201], v[182:185], v[50:53]
	v_mfma_f32_16x16x32_bf16 v[62:65], v[206:209], v[154:157], v[46:49]
	v_mfma_f32_16x16x32_bf16 v[58:61], v[206:209], v[182:185], v[42:45]
	v_mfma_f32_16x16x32_bf16 v[54:57], v[142:145], v[154:157], v[38:41]
	v_mfma_f32_16x16x32_bf16 v[50:53], v[142:145], v[182:185], v[34:37]
	v_mfma_f32_16x16x32_bf16 v[30:33], v[186:189], v[118:121], v[30:33]
	v_mfma_f32_16x16x32_bf16 v[26:29], v[186:189], v[222:225], v[26:29]
	v_mfma_f32_16x16x32_bf16 v[22:25], v[194:197], v[118:121], v[22:25]
	v_mfma_f32_16x16x32_bf16 v[18:21], v[194:197], v[222:225], v[18:21]
	v_mfma_f32_16x16x32_bf16 v[14:17], v[202:205], v[118:121], v[14:17]
	v_mfma_f32_16x16x32_bf16 v[10:13], v[202:205], v[222:225], v[10:13]
	v_mfma_f32_16x16x32_bf16 v[6:9], v[210:213], v[118:121], v[6:9]
	v_mfma_f32_16x16x32_bf16 v[2:5], v[210:213], v[222:225], v[2:5]
	v_mfma_f32_16x16x32_bf16 v[46:49], v[190:193], v[218:221], v[30:33]
	v_mfma_f32_16x16x32_bf16 v[38:41], v[190:193], v[226:229], v[26:29]
	v_mfma_f32_16x16x32_bf16 v[34:37], v[198:201], v[218:221], v[22:25]
	v_mfma_f32_16x16x32_bf16 v[26:29], v[198:201], v[226:229], v[18:21]
	v_mfma_f32_16x16x32_bf16 v[22:25], v[206:209], v[218:221], v[14:17]
	v_mfma_f32_16x16x32_bf16 v[14:17], v[206:209], v[226:229], v[10:13]
	v_mfma_f32_16x16x32_bf16 v[10:13], v[142:145], v[218:221], v[6:9]
	v_mfma_f32_16x16x32_bf16 v[2:5], v[142:145], v[226:229], v[2:5]
	v_cmp_gt_u32_e32 vcc, s67, v0
	s_barrier
	s_and_saveexec_b64 s[8:9], vcc
	s_cbranch_execz .LBB0_108
	s_barrier

; #define G_LDA(dst, b, h)                                                                                                  \
;   _Pragma("unroll") for (int m = 0; m < 4; ++m) _Pragma("unroll") for (int k = 0; k < 2; ++k)                             \
;       dst[m][k] = *(const bf16x8*)((const char*)G_SA(b, h) + ((wr * 4 + m) * 2 + k) * 1024 + rdo)
; #define G_LDB(dst, b, h)                                                                                                  \
;   _Pragma("unroll") for (int n = 0; n < 2; ++n) _Pragma("unroll") for (int k = 0; k < 2; ++k)                             \
;       dst[n][k] = *(const bf16x8*)((const char*)G_SB(b, h) + ((wc * 2 + n) * 2 + k) * 1024 + rdo)
; #define G_WAIT_V(n) asm volatile("s_waitcnt vmcnt(" #n ")" ::: "memory")
; #define G_WAIT_L(n) asm volatile("s_waitcnt lgkmcnt(" #n ")" ::: "memory")
; #define G_BAR __builtin_amdgcn_s_barrier()
; #define G_SCHED __builtin_amdgcn_sched_barrier(0)
;     ...
;   if (wr == 1) G_BAR;
;   G_WAIT_V(4); G_BAR;
;   G_STAGE(G_SB(1, 0), B, ob0, ob1, LDB, 0, KB(1)); G_STAGE(G_SA(1, 0), A, oa0, oa1, LDA, 0, KA(1)); G_STAGE(G_SB(1, 1), B, ob0, ob1, LDB, 128, KB(1));
;   G_WAIT_V(6); G_BAR;
;   for (int tt = 0; tt < nt - 2; tt += 2) {
;     G_LDB(B0, 0, 0); G_SCHED; G_LDA(At, 0, 0); G_STAGE(G_SA(1, 1), A, oa0, oa1, LDA, 128, KA(tt + 1));
;     G_WAIT_L(8); G_BAR; G_WAIT_L(0); G_MMA(0, 0, At, B0); G_BAR; G_SCHED;
;     G_LDB(B1, 0, 1); G_STAGE(G_SB(0, 0), B, ob0, ob1, LDB, 0, KB(tt + 2));
;     G_BAR; G_WAIT_L(0); G_MMA(0, 1, At, B1); G_BAR;
.LBB0_217:
	s_or_b64 exec, exec, s[20:21]
	v_add_u32_e32 v13, 0x18000, v18
	v_lshl_add_u64 v[24:25], v[6:7], 0, s[76:77]
	v_readfirstlane_b32 s27, v13
	v_add_u32_e32 v13, 0x1a000, v18
	s_mov_b32 m0, s27
	v_readfirstlane_b32 s28, v13
	v_add_u32_e32 v13, 0x8000, v18
	s_waitcnt vmcnt(4)
	s_barrier
	global_load_lds_dwordx4 v[24:25], off
	v_lshl_add_u64 v[24:25], v[8:9], 0, s[76:77]
	s_mov_b32 m0, s28
	v_readfirstlane_b32 s21, v13
	v_add_u32_e32 v13, 0xa000, v18
	global_load_lds_dwordx4 v[24:25], off
	v_lshl_add_u64 v[24:25], v[10:11], 0, s[76:77]
	s_mov_b32 m0, s21
	v_readfirstlane_b32 s26, v13
	s_add_u32 s0, s18, 0x10080
	v_add_u32_e32 v13, 0x1c000, v18
	global_load_lds_dwordx4 v[24:25], off
	v_lshl_add_u64 v[24:25], v[14:15], 0, s[76:77]
	s_mov_b32 m0, s26
	s_addc_u32 s1, s19, 0
	v_readfirstlane_b32 s15, v13
	v_add_u32_e32 v13, 0x1e000, v18
	global_load_lds_dwordx4 v[24:25], off
	v_lshl_add_u64 v[24:25], s[0:1], 0, v[2:3]
	s_mov_b32 m0, s15
	v_readfirstlane_b32 s20, v13
	global_load_lds_dwordx4 v[24:25], off
	v_lshl_add_u64 v[24:25], s[0:1], 0, v[4:5]
	s_mov_b32 m0, s20
	v_lshlrev_b32_e32 v26, 2, v0
	global_load_lds_dwordx4 v[24:25], off
	v_lshlrev_b32_e32 v24, 6, v0
	v_and_b32_e32 v13, 48, v0
	v_and_b32_e32 v25, 0x3c0, v24
	v_and_b32_e32 v41, 32, v26
	v_or_b32_e32 v40, v25, v13
	v_bitop3_b32 v13, v25, v41, v13 bitop3:0x36
	s_movk_i32 s0, 0x3000
	v_and_or_b32 v162, v24, s0, v13
	s_add_u32 s0, s16, 0x10080
	s_addc_u32 s1, s17, 0
	v_lshl_add_u64 v[72:73], s[0:1], 0, v[2:3]
	v_lshl_add_u64 v[74:75], s[0:1], 0, v[4:5]
	s_add_u32 s0, s18, 0x10100
	s_addc_u32 s1, s19, 0
	v_or_b32_e32 v230, 0x10000, v162
	v_or_b32_e32 v232, 0x10800, v162
	s_waitcnt vmcnt(6)
	s_barrier
	v_lshl_add_u64 v[160:161], s[0:1], 0, v[2:3]
	v_lshl_add_u64 v[194:195], s[0:1], 0, v[4:5]
	s_add_u32 s0, s16, 0x10100
	v_or_b32_e32 v231, 0x10400, v162
	ds_read_b128 v[24:27], v230
	ds_read_b128 v[28:31], v231
	v_or_b32_e32 v233, 0x10c00, v162
	ds_read_b128 v[32:35], v232
	ds_read_b128 v[36:39], v233
	s_addc_u32 s1, s17, 0
	v_lshl_add_u64 v[214:215], s[0:1], 0, v[2:3]
	v_lshl_add_u64 v[216:217], s[0:1], 0, v[4:5]
	s_add_u32 s0, s18, 0x10180
	s_addc_u32 s1, s19, 0
	v_lshlrev_b32_e32 v42, 13, v12
	v_lshl_add_u64 v[120:121], v[6:7], 0, s[82:83]
	v_lshl_add_u64 v[122:123], v[8:9], 0, s[82:83]
	v_lshl_add_u64 v[152:153], v[10:11], 0, s[82:83]
	v_lshl_add_u64 v[226:227], v[6:7], 0, s[90:91]
	v_lshl_add_u64 v[228:229], v[8:9], 0, s[90:91]
	v_lshl_add_u64 v[12:13], v[10:11], 0, s[90:91]
	v_lshl_add_u64 v[10:11], v[14:15], 0, s[90:91]
	v_lshl_add_u64 v[8:9], s[0:1], 0, v[2:3]
	v_lshl_add_u64 v[6:7], s[0:1], 0, v[4:5]
	v_lshl_add_u64 v[154:155], v[14:15], 0, s[82:83]
	v_add_u32_e32 v14, 0xc000, v18
	v_bitop3_b32 v242, v40, v42, v41 bitop3:0xde
	v_readfirstlane_b32 s19, v14
	v_add_u32_e32 v14, 0xe000, v18
	s_mov_b32 m0, s19
	v_readfirstlane_b32 s18, v14
	ds_read_b128 v[40:43], v242
	ds_read_b128 v[44:47], v242 offset:1024
	ds_read_b128 v[48:51], v242 offset:2048
	ds_read_b128 v[52:55], v242 offset:3072
	ds_read_b128 v[56:59], v242 offset:4096
	ds_read_b128 v[60:63], v242 offset:5120
	ds_read_b128 v[64:67], v242 offset:6144
	ds_read_b128 v[68:71], v242 offset:7168
	global_load_lds_dwordx4 v[72:73], off
	s_mov_b32 m0, s18
	s_nop 0
	global_load_lds_dwordx4 v[74:75], off
	s_waitcnt lgkmcnt(8)
	s_barrier
	s_waitcnt lgkmcnt(0)
	v_mfma_f32_16x16x32_bf16 v[72:75], v[40:43], v[24:27], 0
	v_mfma_f32_16x16x32_bf16 v[76:79], v[40:43], v[32:35], 0
	v_mfma_f32_16x16x32_bf16 v[80:83], v[48:51], v[24:27], 0
	v_mfma_f32_16x16x32_bf16 v[84:87], v[48:51], v[32:35], 0
	v_mfma_f32_16x16x32_bf16 v[88:91], v[56:59], v[24:27], 0
	v_mfma_f32_16x16x32_bf16 v[92:95], v[56:59], v[32:35], 0
	v_mfma_f32_16x16x32_bf16 v[96:99], v[64:67], v[24:27], 0
	v_mfma_f32_16x16x32_bf16 v[100:103], v[64:67], v[32:35], 0
	v_mfma_f32_16x16x32_bf16 v[72:75], v[44:47], v[28:31], v[72:75]
	v_mfma_f32_16x16x32_bf16 v[76:79], v[44:47], v[36:39], v[76:79]
	v_mfma_f32_16x16x32_bf16 v[80:83], v[52:55], v[28:31], v[80:83]
	v_mfma_f32_16x16x32_bf16 v[84:87], v[52:55], v[36:39], v[84:87]
	v_mfma_f32_16x16x32_bf16 v[88:91], v[60:63], v[28:31], v[88:91]
	v_mfma_f32_16x16x32_bf16 v[92:95], v[60:63], v[36:39], v[92:95]
	v_mfma_f32_16x16x32_bf16 v[96:99], v[68:71], v[28:31], v[96:99]
	v_mfma_f32_16x16x32_bf16 v[100:103], v[68:71], v[36:39], v[100:103]
	s_barrier
	v_readfirstlane_b32 s0, v22
	v_or_b32_e32 v234, 0x14000, v162
	v_or_b32_e32 v236, 0x14800, v162
	s_mov_b32 m0, s0
	v_readfirstlane_b32 s0, v23
	v_or_b32_e32 v235, 0x14400, v162
	ds_read_b128 v[104:107], v234
	ds_read_b128 v[108:111], v235
	v_or_b32_e32 v237, 0x14c00, v162
	ds_read_b128 v[112:115], v236
	ds_read_b128 v[116:119], v237
	global_load_lds_dwordx4 v[120:121], off
	s_mov_b32 m0, s0
	s_nop 0
	global_load_lds_dwordx4 v[122:123], off
	s_barrier
	s_waitcnt lgkmcnt(0)
	v_mfma_f32_16x16x32_bf16 v[120:123], v[40:43], v[104:107], 0
	v_mfma_f32_16x16x32_bf16 v[40:43], v[40:43], v[112:115], 0
	v_mfma_f32_16x16x32_bf16 v[120:123], v[44:47], v[108:111], v[120:123]
	v_mfma_f32_16x16x32_bf16 v[40:43], v[44:47], v[116:119], v[40:43]
	v_mfma_f32_16x16x32_bf16 v[44:47], v[48:51], v[104:107], 0
	v_mfma_f32_16x16x32_bf16 v[48:51], v[48:51], v[112:115], 0
	v_mfma_f32_16x16x32_bf16 v[44:47], v[52:55], v[108:111], v[44:47]
	v_mfma_f32_16x16x32_bf16 v[48:51], v[52:55], v[116:119], v[48:51]
	v_mfma_f32_16x16x32_bf16 v[52:55], v[56:59], v[104:107], 0
	v_mfma_f32_16x16x32_bf16 v[56:59], v[56:59], v[112:115], 0
	v_mfma_f32_16x16x32_bf16 v[52:55], v[60:63], v[108:111], v[52:55]
	v_mfma_f32_16x16x32_bf16 v[56:59], v[60:63], v[116:119], v[56:59]
	v_mfma_f32_16x16x32_bf16 v[60:63], v[64:67], v[104:107], 0
	v_mfma_f32_16x16x32_bf16 v[64:67], v[64:67], v[112:115], 0
	v_mfma_f32_16x16x32_bf16 v[60:63], v[68:71], v[108:111], v[60:63]
	v_mfma_f32_16x16x32_bf16 v[64:67], v[68:71], v[116:119], v[64:67]
	v_readfirstlane_b32 s0, v18
	s_mov_b32 m0, s0
	v_readfirstlane_b32 s0, v19
	s_barrier
; #define G_LDA(dst, b, h)                                                                                                  \
;   _Pragma("unroll") for (int m = 0; m < 4; ++m) _Pragma("unroll") for (int k = 0; k < 2; ++k)                             \
;       dst[m][k] = *(const bf16x8*)((const char*)G_SA(b, h) + ((wr * 4 + m) * 2 + k) * 1024 + rdo)
; #define G_LDB(dst, b, h)                                                                                                  \
;   _Pragma("unroll") for (int n = 0; n < 2; ++n) _Pragma("unroll") for (int k = 0; k < 2; ++k)                             \
;       dst[n][k] = *(const bf16x8*)((const char*)G_SB(b, h) + ((wc * 2 + n) * 2 + k) * 1024 + rdo)
; #define G_WAIT_V(n) asm volatile("s_waitcnt vmcnt(" #n ")" ::: "memory")
; #define G_WAIT_L(n) asm volatile("s_waitcnt lgkmcnt(" #n ")" ::: "memory")
; #define G_BAR __builtin_amdgcn_s_barrier()
; #define G_SCHED __builtin_amdgcn_sched_barrier(0)
;     ...
;     G_BAR; G_WAIT_L(0); G_MMA(0, 1, At, B1); G_BAR;
;     G_LDA(At, 0, 1); G_STAGE(G_SA(0, 0), A, oa0, oa1, LDA, 0, KA(tt + 2));
;     G_BAR; G_WAIT_L(0); G_MMA(1, 0, At, B0); G_BAR; G_SCHED;
;     G_STAGE(G_SB(0, 1), B, ob0, ob1, LDB, 128, KB(tt + 2));
;     G_WAIT_V(6); G_BAR; G_MMA(1, 1, At, B1); G_BAR;
;     G_LDB(B0, 1, 0); G_SCHED; G_LDA(At, 1, 0); G_STAGE(G_SA(0, 1), A, oa0, oa1, LDA, 128, KA(tt + 2));
;     G_WAIT_L(8); G_BAR; G_WAIT_L(0); G_MMA(0, 0, At, B0); G_BAR; G_SCHED;
;     G_LDB(B1, 1, 1); G_STAGE(G_SB(1, 0), B, ob0, ob1, LDB, 0, KB(tt + 3));
;     G_BAR; G_WAIT_L(0); G_MMA(0, 1, At, B1); G_BAR;
;     G_LDA(At, 1, 1); G_STAGE(G_SA(1, 0), A, oa0, oa1, LDA, 0, KA(tt + 3));
	ds_read_b128 v[68:71], v242 offset:16384
	ds_read_b128 v[124:127], v242 offset:17408
	ds_read_b128 v[128:131], v242 offset:18432
	ds_read_b128 v[132:135], v242 offset:19456
	ds_read_b128 v[136:139], v242 offset:20480
	ds_read_b128 v[140:143], v242 offset:21504
	ds_read_b128 v[144:147], v242 offset:22528
	ds_read_b128 v[148:151], v242 offset:23552
	global_load_lds_dwordx4 v[152:153], off
	s_mov_b32 m0, s0
	s_nop 0
	global_load_lds_dwordx4 v[154:155], off
	s_barrier
	s_waitcnt lgkmcnt(0)
	v_mfma_f32_16x16x32_bf16 v[152:155], v[68:71], v[24:27], 0
	v_mfma_f32_16x16x32_bf16 v[164:167], v[128:131], v[24:27], 0
	v_mfma_f32_16x16x32_bf16 v[186:189], v[136:139], v[24:27], 0
	v_mfma_f32_16x16x32_bf16 v[22:25], v[144:147], v[24:27], 0
	v_mfma_f32_16x16x32_bf16 v[152:155], v[124:127], v[28:31], v[152:155]
	v_mfma_f32_16x16x32_bf16 v[164:167], v[132:135], v[28:31], v[164:167]
	v_mfma_f32_16x16x32_bf16 v[186:189], v[140:143], v[28:31], v[186:189]
	v_mfma_f32_16x16x32_bf16 v[22:25], v[148:151], v[28:31], v[22:25]
	v_mfma_f32_16x16x32_bf16 v[26:29], v[144:147], v[32:35], 0
	v_mfma_f32_16x16x32_bf16 v[156:159], v[68:71], v[32:35], 0
	v_mfma_f32_16x16x32_bf16 v[182:185], v[128:131], v[32:35], 0
	v_mfma_f32_16x16x32_bf16 v[190:193], v[136:139], v[32:35], 0
	v_mfma_f32_16x16x32_bf16 v[26:29], v[148:151], v[36:39], v[26:29]
	v_mfma_f32_16x16x32_bf16 v[156:159], v[124:127], v[36:39], v[156:159]
	v_mfma_f32_16x16x32_bf16 v[182:185], v[132:135], v[36:39], v[182:185]
	v_mfma_f32_16x16x32_bf16 v[190:193], v[140:143], v[36:39], v[190:193]
	s_barrier
	v_readfirstlane_b32 s0, v20
	s_mov_b32 m0, s0
	v_readfirstlane_b32 s0, v21
	global_load_lds_dwordx4 v[160:161], off
	s_mov_b32 m0, s0
	s_nop 0
	global_load_lds_dwordx4 v[194:195], off
	s_waitcnt vmcnt(6)
	s_barrier
	v_mfma_f32_16x16x32_bf16 v[18:21], v[68:71], v[104:107], 0
	v_mfma_f32_16x16x32_bf16 v[30:33], v[68:71], v[112:115], 0
	v_mfma_f32_16x16x32_bf16 v[18:21], v[124:127], v[108:111], v[18:21]
	v_mfma_f32_16x16x32_bf16 v[30:33], v[124:127], v[116:119], v[30:33]
	v_mfma_f32_16x16x32_bf16 v[34:37], v[128:131], v[104:107], 0
	v_mfma_f32_16x16x32_bf16 v[124:127], v[136:139], v[104:107], 0
	v_mfma_f32_16x16x32_bf16 v[104:107], v[144:147], v[104:107], 0
	v_mfma_f32_16x16x32_bf16 v[34:37], v[132:135], v[108:111], v[34:37]
	v_mfma_f32_16x16x32_bf16 v[68:71], v[128:131], v[112:115], 0
	v_mfma_f32_16x16x32_bf16 v[124:127], v[140:143], v[108:111], v[124:127]
	v_mfma_f32_16x16x32_bf16 v[128:131], v[136:139], v[112:115], 0
	v_mfma_f32_16x16x32_bf16 v[104:107], v[148:151], v[108:111], v[104:107]
	v_mfma_f32_16x16x32_bf16 v[108:111], v[144:147], v[112:115], 0
	v_mfma_f32_16x16x32_bf16 v[68:71], v[132:135], v[116:119], v[68:71]
	v_mfma_f32_16x16x32_bf16 v[128:131], v[140:143], v[116:119], v[128:131]
	v_mfma_f32_16x16x32_bf16 v[108:111], v[148:151], v[116:119], v[108:111]
	v_or_b32_e32 v160, 0x18000, v162
	v_or_b32_e32 v238, 0x18800, v162
	s_barrier
	v_or_b32_e32 v161, 0x18400, v162
	ds_read_b128 v[112:115], v160
	ds_read_b128 v[116:119], v161
	v_or_b32_e32 v239, 0x18c00, v162
	ds_read_b128 v[132:135], v238
	ds_read_b128 v[136:139], v239
	v_readfirstlane_b32 s0, v16
	s_mov_b32 m0, s0
	v_readfirstlane_b32 s0, v17
	ds_read_b128 v[140:143], v242 offset:32768
	ds_read_b128 v[144:147], v242 offset:33792
	ds_read_b128 v[148:151], v242 offset:34816
	ds_read_b128 v[194:197], v242 offset:35840
	ds_read_b128 v[198:201], v242 offset:36864
	ds_read_b128 v[202:205], v242 offset:37888
	ds_read_b128 v[206:209], v242 offset:38912
	ds_read_b128 v[210:213], v242 offset:39936
	global_load_lds_dwordx4 v[214:215], off
	s_mov_b32 m0, s0
	s_nop 0
	global_load_lds_dwordx4 v[216:217], off
	s_waitcnt lgkmcnt(8)
	s_barrier
	s_waitcnt lgkmcnt(0)
	v_mfma_f32_16x16x32_bf16 v[14:17], v[140:143], v[112:115], v[72:75]
	v_mfma_f32_16x16x32_bf16 v[72:75], v[140:143], v[132:135], v[76:79]
	v_mfma_f32_16x16x32_bf16 v[76:79], v[148:151], v[112:115], v[80:83]
	v_mfma_f32_16x16x32_bf16 v[80:83], v[148:151], v[132:135], v[84:87]
	v_mfma_f32_16x16x32_bf16 v[84:87], v[198:201], v[112:115], v[88:91]
	v_mfma_f32_16x16x32_bf16 v[88:91], v[198:201], v[132:135], v[92:95]
	v_mfma_f32_16x16x32_bf16 v[92:95], v[206:209], v[112:115], v[96:99]
	v_mfma_f32_16x16x32_bf16 v[96:99], v[206:209], v[132:135], v[100:103]
	v_mfma_f32_16x16x32_bf16 v[14:17], v[144:147], v[116:119], v[14:17]
	v_mfma_f32_16x16x32_bf16 v[72:75], v[144:147], v[136:139], v[72:75]
	v_mfma_f32_16x16x32_bf16 v[76:79], v[194:197], v[116:119], v[76:79]
	v_mfma_f32_16x16x32_bf16 v[80:83], v[194:197], v[136:139], v[80:83]
	v_mfma_f32_16x16x32_bf16 v[84:87], v[202:205], v[116:119], v[84:87]
	v_mfma_f32_16x16x32_bf16 v[88:91], v[202:205], v[136:139], v[88:91]
	v_mfma_f32_16x16x32_bf16 v[92:95], v[210:213], v[116:119], v[92:95]
	v_mfma_f32_16x16x32_bf16 v[96:99], v[210:213], v[136:139], v[96:99]
	s_barrier
	v_or_b32_e32 v240, 0x1c000, v162
	v_or_b32_e32 v243, 0x1c800, v162
	s_mov_b32 m0, s27
	v_or_b32_e32 v241, 0x1c400, v162
	ds_read_b128 v[100:103], v240
	ds_read_b128 v[214:217], v241
	v_or_b32_e32 v162, 0x1cc00, v162
	ds_read_b128 v[218:221], v243
	ds_read_b128 v[222:225], v162
	global_load_lds_dwordx4 v[226:227], off
	s_mov_b32 m0, s28
	s_nop 0
	global_load_lds_dwordx4 v[228:229], off
	s_barrier
; #define G_LDA(dst, b, h)                                                                                                  \
;   _Pragma("unroll") for (int m = 0; m < 4; ++m) _Pragma("unroll") for (int k = 0; k < 2; ++k)                             \
;       dst[m][k] = *(const bf16x8*)((const char*)G_SA(b, h) + ((wr * 4 + m) * 2 + k) * 1024 + rdo)
; #define G_LDB(dst, b, h)                                                                                                  \
;   _Pragma("unroll") for (int n = 0; n < 2; ++n) _Pragma("unroll") for (int k = 0; k < 2; ++k)                             \
;       dst[n][k] = *(const bf16x8*)((const char*)G_SB(b, h) + ((wc * 2 + n) * 2 + k) * 1024 + rdo)
; #define G_WAIT_V(n) asm volatile("s_waitcnt vmcnt(" #n ")" ::: "memory")
; #define G_WAIT_L(n) asm volatile("s_waitcnt lgkmcnt(" #n ")" ::: "memory")
; #define G_BAR __builtin_amdgcn_s_barrier()
; #define G_SCHED __builtin_amdgcn_sched_barrier(0)
; DI void br_flush(PREF p, f32x4 (&acc)[2][2][4][2], int slot) { br_store(p, acc, slot); zero_acc256(acc); }
;     ...
;     G_LDA(At, 1, 1); G_STAGE(G_SA(1, 0), A, oa0, oa1, LDA, 0, KA(tt + 3));
;     G_BAR; G_WAIT_L(0); G_MMA(1, 0, At, B0); G_BAR; G_SCHED;
;     G_STAGE(G_SB(1, 1), B, ob0, ob1, LDB, 128, KB(tt + 3));
;     G_WAIT_V(6); G_BAR; G_MMA(1, 1, At, B1); G_BAR;
;     if (MODE && ((tt + 1) & 3) == 3) br_flush(p, acc, (tt + 1) >> 2);
;   }
;   {
;     G_LDB(B0, 0, 0); G_LDA(At, 0, 0); G_STAGE(G_SA(1, 1), A, oa0, oa1, LDA, 128, KA(nt - 1));
;     G_BAR; G_WAIT_L(0); G_MMA(0, 0, At, B0); G_BAR;
	s_waitcnt lgkmcnt(0)
	v_mfma_f32_16x16x32_bf16 v[120:123], v[140:143], v[100:103], v[120:123]
	v_mfma_f32_16x16x32_bf16 v[38:41], v[140:143], v[218:221], v[40:43]
	v_mfma_f32_16x16x32_bf16 v[42:45], v[148:151], v[100:103], v[44:47]
	v_mfma_f32_16x16x32_bf16 v[46:49], v[148:151], v[218:221], v[48:51]
	v_mfma_f32_16x16x32_bf16 v[50:53], v[198:201], v[100:103], v[52:55]
	v_mfma_f32_16x16x32_bf16 v[54:57], v[198:201], v[218:221], v[56:59]
	v_mfma_f32_16x16x32_bf16 v[58:61], v[206:209], v[100:103], v[60:63]
	v_mfma_f32_16x16x32_bf16 v[62:65], v[206:209], v[218:221], v[64:67]
	v_mfma_f32_16x16x32_bf16 v[120:123], v[144:147], v[214:217], v[120:123]
	v_mfma_f32_16x16x32_bf16 v[38:41], v[144:147], v[222:225], v[38:41]
	v_mfma_f32_16x16x32_bf16 v[42:45], v[194:197], v[214:217], v[42:45]
	v_mfma_f32_16x16x32_bf16 v[46:49], v[194:197], v[222:225], v[46:49]
	v_mfma_f32_16x16x32_bf16 v[50:53], v[202:205], v[214:217], v[50:53]
	v_mfma_f32_16x16x32_bf16 v[54:57], v[202:205], v[222:225], v[54:57]
	v_mfma_f32_16x16x32_bf16 v[58:61], v[210:213], v[214:217], v[58:61]
	v_mfma_f32_16x16x32_bf16 v[62:65], v[210:213], v[222:225], v[62:65]
	s_mov_b32 m0, s21
	s_barrier
	ds_read_b128 v[140:143], v242 offset:49152
	ds_read_b128 v[144:147], v242 offset:50176
	ds_read_b128 v[148:151], v242 offset:51200
	ds_read_b128 v[194:197], v242 offset:52224
	ds_read_b128 v[198:201], v242 offset:53248
	ds_read_b128 v[202:205], v242 offset:54272
	ds_read_b128 v[206:209], v242 offset:55296
	ds_read_b128 v[210:213], v242 offset:56320
	global_load_lds_dwordx4 v[12:13], off
	s_mov_b32 m0, s26
	s_nop 0
	global_load_lds_dwordx4 v[10:11], off
	s_barrier
	s_waitcnt lgkmcnt(0)
	v_mfma_f32_16x16x32_bf16 v[10:13], v[140:143], v[112:115], v[152:155]
	v_mfma_f32_16x16x32_bf16 v[22:25], v[206:209], v[112:115], v[22:25]
	v_mfma_f32_16x16x32_bf16 v[26:29], v[206:209], v[132:135], v[26:29]
	v_mfma_f32_16x16x32_bf16 v[10:13], v[144:147], v[116:119], v[10:13]
	v_mfma_f32_16x16x32_bf16 v[152:155], v[140:143], v[132:135], v[156:159]
	v_mfma_f32_16x16x32_bf16 v[156:159], v[148:151], v[112:115], v[164:167]
	v_mfma_f32_16x16x32_bf16 v[164:167], v[148:151], v[132:135], v[182:185]
	v_mfma_f32_16x16x32_bf16 v[182:185], v[198:201], v[112:115], v[186:189]
	v_mfma_f32_16x16x32_bf16 v[186:189], v[198:201], v[132:135], v[190:193]
	v_mfma_f32_16x16x32_bf16 v[22:25], v[210:213], v[116:119], v[22:25]
	v_mfma_f32_16x16x32_bf16 v[26:29], v[210:213], v[136:139], v[26:29]
	v_mfma_f32_16x16x32_bf16 v[152:155], v[144:147], v[136:139], v[152:155]
	v_mfma_f32_16x16x32_bf16 v[156:159], v[194:197], v[116:119], v[156:159]
	v_mfma_f32_16x16x32_bf16 v[164:167], v[194:197], v[136:139], v[164:167]
	v_mfma_f32_16x16x32_bf16 v[182:185], v[202:205], v[116:119], v[182:185]
	v_mfma_f32_16x16x32_bf16 v[186:189], v[202:205], v[136:139], v[186:189]
	s_barrier
	s_mov_b32 m0, s15
	s_nop 0
	global_load_lds_dwordx4 v[8:9], off
	s_mov_b32 m0, s20
	s_nop 0
	global_load_lds_dwordx4 v[6:7], off
	s_waitcnt vmcnt(6)
	s_barrier
	v_mfma_f32_16x16x32_bf16 v[6:9], v[140:143], v[100:103], v[18:21]
	v_mfma_f32_16x16x32_bf16 v[18:21], v[140:143], v[218:221], v[30:33]
	v_mfma_f32_16x16x32_bf16 v[30:33], v[148:151], v[100:103], v[34:37]
	v_mfma_f32_16x16x32_bf16 v[34:37], v[148:151], v[218:221], v[68:71]
	v_mfma_f32_16x16x32_bf16 v[66:69], v[198:201], v[100:103], v[124:127]
	v_mfma_f32_16x16x32_bf16 v[112:115], v[198:201], v[218:221], v[128:131]
	v_mfma_f32_16x16x32_bf16 v[100:103], v[206:209], v[100:103], v[104:107]
	v_mfma_f32_16x16x32_bf16 v[104:107], v[206:209], v[218:221], v[108:111]
	v_mfma_f32_16x16x32_bf16 v[6:9], v[144:147], v[214:217], v[6:9]
	v_mfma_f32_16x16x32_bf16 v[18:21], v[144:147], v[222:225], v[18:21]
	v_mfma_f32_16x16x32_bf16 v[30:33], v[194:197], v[214:217], v[30:33]
	v_mfma_f32_16x16x32_bf16 v[34:37], v[194:197], v[222:225], v[34:37]
	v_mfma_f32_16x16x32_bf16 v[66:69], v[202:205], v[214:217], v[66:69]
	v_mfma_f32_16x16x32_bf16 v[112:115], v[202:205], v[222:225], v[112:115]
	v_mfma_f32_16x16x32_bf16 v[100:103], v[210:213], v[214:217], v[100:103]
	v_mfma_f32_16x16x32_bf16 v[104:107], v[210:213], v[222:225], v[104:107]
	s_add_u32 s0, s16, 0x10180
	s_addc_u32 s1, s17, 0
	s_mov_b32 m0, s19
	v_lshl_add_u64 v[2:3], s[0:1], 0, v[2:3]
	s_barrier
	ds_read_b128 v[108:111], v230
	ds_read_b128 v[116:119], v231
	ds_read_b128 v[124:127], v232
	ds_read_b128 v[128:131], v233
	ds_read_b128 v[132:135], v242
	ds_read_b128 v[136:139], v242 offset:1024
	ds_read_b128 v[140:143], v242 offset:2048
	ds_read_b128 v[144:147], v242 offset:3072
	ds_read_b128 v[148:151], v242 offset:4096
	ds_read_b128 v[190:193], v242 offset:5120
	ds_read_b128 v[194:197], v242 offset:6144
	ds_read_b128 v[198:201], v242 offset:7168
	global_load_lds_dwordx4 v[2:3], off
	s_mov_b32 m0, s18
	v_lshl_add_u64 v[2:3], s[0:1], 0, v[4:5]
	global_load_lds_dwordx4 v[2:3], off
	s_barrier
	s_waitcnt lgkmcnt(0)
	v_mfma_f32_16x16x32_bf16 v[2:5], v[132:135], v[108:111], v[14:17]
	v_mfma_f32_16x16x32_bf16 v[14:17], v[132:135], v[124:127], v[72:75]
	v_mfma_f32_16x16x32_bf16 v[70:73], v[140:143], v[108:111], v[76:79]
	v_mfma_f32_16x16x32_bf16 v[74:77], v[140:143], v[124:127], v[80:83]
	v_mfma_f32_16x16x32_bf16 v[78:81], v[148:151], v[108:111], v[84:87]
	v_mfma_f32_16x16x32_bf16 v[82:85], v[148:151], v[124:127], v[88:91]
	v_mfma_f32_16x16x32_bf16 v[86:89], v[194:197], v[108:111], v[92:95]
	v_mfma_f32_16x16x32_bf16 v[90:93], v[194:197], v[124:127], v[96:99]
	v_mfma_f32_16x16x32_bf16 v[2:5], v[136:139], v[116:119], v[2:5]
	v_mfma_f32_16x16x32_bf16 v[14:17], v[136:139], v[128:131], v[14:17]
	v_mfma_f32_16x16x32_bf16 v[70:73], v[144:147], v[116:119], v[70:73]
	v_mfma_f32_16x16x32_bf16 v[74:77], v[144:147], v[128:131], v[74:77]
	v_mfma_f32_16x16x32_bf16 v[78:81], v[190:193], v[116:119], v[78:81]
	v_mfma_f32_16x16x32_bf16 v[82:85], v[190:193], v[128:131], v[82:85]
	v_mfma_f32_16x16x32_bf16 v[86:89], v[198:201], v[116:119], v[86:89]
	v_mfma_f32_16x16x32_bf16 v[90:93], v[198:201], v[128:131], v[90:93]
	s_barrier
; #define G_LDA(dst, b, h)                                                                                                  \
;   _Pragma("unroll") for (int m = 0; m < 4; ++m) _Pragma("unroll") for (int k = 0; k < 2; ++k)                             \
;       dst[m][k] = *(const bf16x8*)((const char*)G_SA(b, h) + ((wr * 4 + m) * 2 + k) * 1024 + rdo)
; #define G_LDB(dst, b, h)                                                                                                  \
;   _Pragma("unroll") for (int n = 0; n < 2; ++n) _Pragma("unroll") for (int k = 0; k < 2; ++k)                             \
;       dst[n][k] = *(const bf16x8*)((const char*)G_SB(b, h) + ((wc * 2 + n) * 2 + k) * 1024 + rdo)
; #define G_WAIT_V(n) asm volatile("s_waitcnt vmcnt(" #n ")" ::: "memory")
; #define G_WAIT_L(n) asm volatile("s_waitcnt lgkmcnt(" #n ")" ::: "memory")
; #define G_BAR __builtin_amdgcn_s_barrier()
;     ...
;     G_LDB(B1, 0, 1); G_BAR; G_WAIT_L(0); G_MMA(0, 1, At, B1); G_BAR;
;     G_LDA(At, 0, 1); G_WAIT_V(4); G_BAR; G_WAIT_L(0); G_MMA(1, 0, At, B0); G_MMA(1, 1, At, B1); G_BAR;
;   }
;   {
;     G_LDB(B0, 1, 0); G_LDA(At, 1, 0); G_WAIT_V(2); G_BAR; G_WAIT_L(0); G_MMA(0, 0, At, B0); G_BAR;
	ds_read_b128 v[94:97], v234
	ds_read_b128 v[202:205], v235
	ds_read_b128 v[206:209], v236
	ds_read_b128 v[210:213], v237
	s_barrier
	s_waitcnt lgkmcnt(0)
	v_mfma_f32_16x16x32_bf16 v[38:41], v[132:135], v[206:209], v[38:41]
	v_mfma_f32_16x16x32_bf16 v[42:45], v[140:143], v[94:97], v[42:45]
	v_mfma_f32_16x16x32_bf16 v[46:49], v[140:143], v[206:209], v[46:49]
	v_mfma_f32_16x16x32_bf16 v[50:53], v[148:151], v[94:97], v[50:53]
	v_mfma_f32_16x16x32_bf16 v[54:57], v[148:151], v[206:209], v[54:57]
	v_mfma_f32_16x16x32_bf16 v[58:61], v[194:197], v[94:97], v[58:61]
	v_mfma_f32_16x16x32_bf16 v[62:65], v[194:197], v[206:209], v[62:65]
	v_mfma_f32_16x16x32_bf16 v[120:123], v[132:135], v[94:97], v[120:123]
	v_mfma_f32_16x16x32_bf16 v[38:41], v[136:139], v[210:213], v[38:41]
	v_mfma_f32_16x16x32_bf16 v[42:45], v[144:147], v[202:205], v[42:45]
	v_mfma_f32_16x16x32_bf16 v[46:49], v[144:147], v[210:213], v[46:49]
	v_mfma_f32_16x16x32_bf16 v[50:53], v[190:193], v[202:205], v[50:53]
	v_mfma_f32_16x16x32_bf16 v[54:57], v[190:193], v[210:213], v[54:57]
	v_mfma_f32_16x16x32_bf16 v[58:61], v[198:201], v[202:205], v[58:61]
	v_mfma_f32_16x16x32_bf16 v[62:65], v[198:201], v[210:213], v[62:65]
	v_mfma_f32_16x16x32_bf16 v[214:217], v[136:139], v[202:205], v[120:123]
	s_barrier
	s_nop 0
	ds_read_b128 v[120:123], v242 offset:16384
	ds_read_b128 v[132:135], v242 offset:17408
	ds_read_b128 v[136:139], v242 offset:18432
	ds_read_b128 v[140:143], v242 offset:19456
	ds_read_b128 v[144:147], v242 offset:20480
	ds_read_b128 v[148:151], v242 offset:21504
	ds_read_b128 v[190:193], v242 offset:22528
	ds_read_b128 v[194:197], v242 offset:23552
	s_waitcnt vmcnt(4)
	s_barrier
	s_waitcnt lgkmcnt(0)
	v_mfma_f32_16x16x32_bf16 v[10:13], v[120:123], v[108:111], v[10:13]
	v_mfma_f32_16x16x32_bf16 v[22:25], v[190:193], v[108:111], v[22:25]
	v_mfma_f32_16x16x32_bf16 v[26:29], v[190:193], v[124:127], v[26:29]
	v_mfma_f32_16x16x32_bf16 v[10:13], v[132:135], v[116:119], v[10:13]
	v_mfma_f32_16x16x32_bf16 v[152:155], v[120:123], v[124:127], v[152:155]
	v_mfma_f32_16x16x32_bf16 v[156:159], v[136:139], v[108:111], v[156:159]
	v_mfma_f32_16x16x32_bf16 v[164:167], v[136:139], v[124:127], v[164:167]
	v_mfma_f32_16x16x32_bf16 v[182:185], v[144:147], v[108:111], v[182:185]
	v_mfma_f32_16x16x32_bf16 v[186:189], v[144:147], v[124:127], v[186:189]
	v_mfma_f32_16x16x32_bf16 v[22:25], v[194:197], v[116:119], v[22:25]
	v_mfma_f32_16x16x32_bf16 v[26:29], v[194:197], v[128:131], v[26:29]
	v_mfma_f32_16x16x32_bf16 v[152:155], v[132:135], v[128:131], v[152:155]
	v_mfma_f32_16x16x32_bf16 v[156:159], v[140:143], v[116:119], v[156:159]
	v_mfma_f32_16x16x32_bf16 v[164:167], v[140:143], v[128:131], v[164:167]
	v_mfma_f32_16x16x32_bf16 v[182:185], v[148:151], v[116:119], v[182:185]
	v_mfma_f32_16x16x32_bf16 v[186:189], v[148:151], v[128:131], v[186:189]
	v_mfma_f32_16x16x32_bf16 v[30:33], v[136:139], v[94:97], v[30:33]
	v_mfma_f32_16x16x32_bf16 v[6:9], v[120:123], v[94:97], v[6:9]
	v_mfma_f32_16x16x32_bf16 v[18:21], v[120:123], v[206:209], v[18:21]
	v_mfma_f32_16x16x32_bf16 v[118:121], v[140:143], v[202:205], v[30:33]
	v_mfma_f32_16x16x32_bf16 v[30:33], v[136:139], v[206:209], v[34:37]
	v_mfma_f32_16x16x32_bf16 v[138:141], v[140:143], v[210:213], v[30:33]
	v_mfma_f32_16x16x32_bf16 v[30:33], v[144:147], v[94:97], v[66:69]
	v_mfma_f32_16x16x32_bf16 v[198:201], v[148:151], v[202:205], v[30:33]
	v_mfma_f32_16x16x32_bf16 v[30:33], v[144:147], v[206:209], v[112:115]
	v_mfma_f32_16x16x32_bf16 v[142:145], v[148:151], v[210:213], v[30:33]
	v_mfma_f32_16x16x32_bf16 v[30:33], v[190:193], v[94:97], v[100:103]
	v_mfma_f32_16x16x32_bf16 v[6:9], v[132:135], v[202:205], v[6:9]
	v_mfma_f32_16x16x32_bf16 v[18:21], v[132:135], v[210:213], v[18:21]
	v_mfma_f32_16x16x32_bf16 v[98:101], v[194:197], v[202:205], v[30:33]
	v_mfma_f32_16x16x32_bf16 v[30:33], v[190:193], v[206:209], v[104:107]
	v_mfma_f32_16x16x32_bf16 v[146:149], v[194:197], v[210:213], v[30:33]
	s_barrier
	s_nop 4
	s_nop 0
	ds_read_b128 v[30:33], v160
	ds_read_b128 v[34:37], v161
	ds_read_b128 v[190:193], v238
	ds_read_b128 v[194:197], v239
	ds_read_b128 v[66:69], v242 offset:32768
	ds_read_b128 v[94:97], v242 offset:33792
	ds_read_b128 v[202:205], v242 offset:34816
	ds_read_b128 v[206:209], v242 offset:35840
	ds_read_b128 v[210:213], v242 offset:36864
	ds_read_b128 v[218:221], v242 offset:37888
	ds_read_b128 v[222:225], v242 offset:38912
	ds_read_b128 v[226:229], v242 offset:39936
	s_waitcnt vmcnt(2)
	s_barrier
; #define G_LDA(dst, b, h)                                                                                                  \
;   _Pragma("unroll") for (int m = 0; m < 4; ++m) _Pragma("unroll") for (int k = 0; k < 2; ++k)                             \
;       dst[m][k] = *(const bf16x8*)((const char*)G_SA(b, h) + ((wr * 4 + m) * 2 + k) * 1024 + rdo)
; #define G_LDB(dst, b, h)                                                                                                  \
;   _Pragma("unroll") for (int n = 0; n < 2; ++n) _Pragma("unroll") for (int k = 0; k < 2; ++k)                             \
;       dst[n][k] = *(const bf16x8*)((const char*)G_SB(b, h) + ((wc * 2 + n) * 2 + k) * 1024 + rdo)
; #define G_WAIT_V(n) asm volatile("s_waitcnt vmcnt(" #n ")" ::: "memory")
; #define G_WAIT_L(n) asm volatile("s_waitcnt lgkmcnt(" #n ")" ::: "memory")
; #define G_BAR __builtin_amdgcn_s_barrier()
;     ...
;     G_LDB(B0, 1, 0); G_LDA(At, 1, 0); G_WAIT_V(2); G_BAR; G_WAIT_L(0); G_MMA(0, 0, At, B0); G_BAR;
;     G_LDB(B1, 1, 1); G_WAIT_V(0); G_BAR; G_WAIT_L(0); G_MMA(0, 1, At, B1); G_BAR;
;     G_LDA(At, 1, 1); G_BAR; G_WAIT_L(0); G_MMA(1, 0, At, B0); G_MMA(1, 1, At, B1); G_BAR;
;   }
;   if (wr == 0) G_BAR;
	s_waitcnt lgkmcnt(0)
	v_mfma_f32_16x16x32_bf16 v[2:5], v[66:69], v[30:33], v[2:5]
	v_mfma_f32_16x16x32_bf16 v[126:129], v[94:97], v[34:37], v[2:5]
	v_mfma_f32_16x16x32_bf16 v[2:5], v[66:69], v[190:193], v[14:17]
	v_mfma_f32_16x16x32_bf16 v[134:137], v[94:97], v[194:197], v[2:5]
	v_mfma_f32_16x16x32_bf16 v[2:5], v[202:205], v[30:33], v[70:73]
	v_mfma_f32_16x16x32_bf16 v[122:125], v[206:209], v[34:37], v[2:5]
	v_mfma_f32_16x16x32_bf16 v[2:5], v[202:205], v[190:193], v[74:77]
	v_mfma_f32_16x16x32_bf16 v[130:133], v[206:209], v[194:197], v[2:5]
	v_mfma_f32_16x16x32_bf16 v[2:5], v[210:213], v[30:33], v[78:81]
	v_mfma_f32_16x16x32_bf16 v[110:113], v[218:221], v[34:37], v[2:5]
	v_mfma_f32_16x16x32_bf16 v[2:5], v[210:213], v[190:193], v[82:85]
	v_mfma_f32_16x16x32_bf16 v[114:117], v[218:221], v[194:197], v[2:5]
	v_mfma_f32_16x16x32_bf16 v[2:5], v[222:225], v[30:33], v[86:89]
	v_mfma_f32_16x16x32_bf16 v[102:105], v[226:229], v[34:37], v[2:5]
	v_mfma_f32_16x16x32_bf16 v[2:5], v[222:225], v[190:193], v[90:93]
	v_mfma_f32_16x16x32_bf16 v[106:109], v[226:229], v[194:197], v[2:5]
	s_barrier
	s_nop 4
	s_nop 0
	ds_read_b128 v[2:5], v240
	ds_read_b128 v[230:233], v241
	ds_read_b128 v[234:237], v243
	ds_read_b128 v[238:241], v162
	s_waitcnt vmcnt(0)
	s_barrier
	s_waitcnt lgkmcnt(0)
	v_mfma_f32_16x16x32_bf16 v[14:17], v[66:69], v[2:5], v[214:217]
	v_mfma_f32_16x16x32_bf16 v[86:89], v[94:97], v[230:233], v[14:17]
	v_mfma_f32_16x16x32_bf16 v[14:17], v[66:69], v[234:237], v[38:41]
	v_mfma_f32_16x16x32_bf16 v[94:97], v[94:97], v[238:241], v[14:17]
	v_mfma_f32_16x16x32_bf16 v[14:17], v[202:205], v[2:5], v[42:45]
	v_mfma_f32_16x16x32_bf16 v[82:85], v[206:209], v[230:233], v[14:17]
	v_mfma_f32_16x16x32_bf16 v[14:17], v[202:205], v[234:237], v[46:49]
	v_mfma_f32_16x16x32_bf16 v[90:93], v[206:209], v[238:241], v[14:17]
	v_mfma_f32_16x16x32_bf16 v[14:17], v[210:213], v[2:5], v[50:53]
	v_mfma_f32_16x16x32_bf16 v[74:77], v[218:221], v[230:233], v[14:17]
	v_mfma_f32_16x16x32_bf16 v[14:17], v[210:213], v[234:237], v[54:57]
	v_mfma_f32_16x16x32_bf16 v[78:81], v[218:221], v[238:241], v[14:17]
	v_mfma_f32_16x16x32_bf16 v[14:17], v[222:225], v[2:5], v[58:61]
	v_mfma_f32_16x16x32_bf16 v[66:69], v[226:229], v[230:233], v[14:17]
	v_mfma_f32_16x16x32_bf16 v[14:17], v[222:225], v[234:237], v[62:65]
	v_mfma_f32_16x16x32_bf16 v[70:73], v[226:229], v[238:241], v[14:17]
	s_barrier
	s_nop 4
	s_nop 0
	ds_read_b128 v[14:17], v242 offset:49152
	ds_read_b128 v[202:205], v242 offset:50176
	ds_read_b128 v[206:209], v242 offset:51200
	ds_read_b128 v[210:213], v242 offset:52224
	ds_read_b128 v[214:217], v242 offset:53248
	ds_read_b128 v[218:221], v242 offset:54272
	ds_read_b128 v[222:225], v242 offset:55296
	ds_read_b128 v[226:229], v242 offset:56320
	s_barrier
	s_waitcnt lgkmcnt(0)
	v_mfma_f32_16x16x32_bf16 v[10:13], v[14:17], v[30:33], v[10:13]
	v_mfma_f32_16x16x32_bf16 v[54:57], v[202:205], v[34:37], v[10:13]
	v_mfma_f32_16x16x32_bf16 v[10:13], v[14:17], v[190:193], v[152:155]
	v_mfma_f32_16x16x32_bf16 v[62:65], v[202:205], v[194:197], v[10:13]
	v_mfma_f32_16x16x32_bf16 v[10:13], v[206:209], v[30:33], v[156:159]
	v_mfma_f32_16x16x32_bf16 v[50:53], v[210:213], v[34:37], v[10:13]
	v_mfma_f32_16x16x32_bf16 v[10:13], v[206:209], v[190:193], v[164:167]
	v_mfma_f32_16x16x32_bf16 v[58:61], v[210:213], v[194:197], v[10:13]
	v_mfma_f32_16x16x32_bf16 v[10:13], v[214:217], v[30:33], v[182:185]
	v_mfma_f32_16x16x32_bf16 v[42:45], v[218:221], v[34:37], v[10:13]
	v_mfma_f32_16x16x32_bf16 v[10:13], v[214:217], v[190:193], v[186:189]
	v_mfma_f32_16x16x32_bf16 v[46:49], v[218:221], v[194:197], v[10:13]
	v_mfma_f32_16x16x32_bf16 v[10:13], v[222:225], v[30:33], v[22:25]
	v_mfma_f32_16x16x32_bf16 v[34:37], v[226:229], v[34:37], v[10:13]
	v_mfma_f32_16x16x32_bf16 v[10:13], v[222:225], v[190:193], v[26:29]
	v_mfma_f32_16x16x32_bf16 v[38:41], v[226:229], v[194:197], v[10:13]
	v_mfma_f32_16x16x32_bf16 v[6:9], v[14:17], v[2:5], v[6:9]
	v_mfma_f32_16x16x32_bf16 v[22:25], v[202:205], v[230:233], v[6:9]
	v_mfma_f32_16x16x32_bf16 v[6:9], v[14:17], v[234:237], v[18:21]
	v_mfma_f32_16x16x32_bf16 v[30:33], v[202:205], v[238:241], v[6:9]
	v_mfma_f32_16x16x32_bf16 v[6:9], v[206:209], v[2:5], v[118:121]
	v_mfma_f32_16x16x32_bf16 v[18:21], v[210:213], v[230:233], v[6:9]
	v_mfma_f32_16x16x32_bf16 v[6:9], v[206:209], v[234:237], v[138:141]
	v_mfma_f32_16x16x32_bf16 v[26:29], v[210:213], v[238:241], v[6:9]
	v_mfma_f32_16x16x32_bf16 v[6:9], v[214:217], v[2:5], v[198:201]
	v_mfma_f32_16x16x32_bf16 v[10:13], v[218:221], v[230:233], v[6:9]
	v_mfma_f32_16x16x32_bf16 v[6:9], v[214:217], v[234:237], v[142:145]
	v_mfma_f32_16x16x32_bf16 v[14:17], v[218:221], v[238:241], v[6:9]
	v_mfma_f32_16x16x32_bf16 v[2:5], v[222:225], v[2:5], v[98:101]
	v_mfma_f32_16x16x32_bf16 v[6:9], v[222:225], v[234:237], v[146:149]
	v_mfma_f32_16x16x32_bf16 v[2:5], v[226:229], v[230:233], v[2:5]
	v_mfma_f32_16x16x32_bf16 v[6:9], v[226:229], v[238:241], v[6:9]
	v_cmp_gt_u32_e32 vcc, s67, v0
	s_barrier
	s_and_saveexec_b64 s[16:17], vcc
	s_cbranch_execz .LBB0_214
	s_barrier
	s_branch .LBB0_214

; #define G_LDA(dst, b, h)                                                                                                  \
;   _Pragma("unroll") for (int m = 0; m < 4; ++m) _Pragma("unroll") for (int k = 0; k < 2; ++k)                             \
;       dst[m][k] = *(const bf16x8*)((const char*)G_SA(b, h) + ((wr * 4 + m) * 2 + k) * 1024 + rdo)
; #define G_LDB(dst, b, h)                                                                                                  \
;   _Pragma("unroll") for (int n = 0; n < 2; ++n) _Pragma("unroll") for (int k = 0; k < 2; ++k)                             \
;       dst[n][k] = *(const bf16x8*)((const char*)G_SB(b, h) + ((wc * 2 + n) * 2 + k) * 1024 + rdo)
; #define G_WAIT_L(n) asm volatile("s_waitcnt lgkmcnt(" #n ")" ::: "memory")
; #define G_BAR __builtin_amdgcn_s_barrier()
; #define G_SCHED __builtin_amdgcn_sched_barrier(0)
;     ...
;   for (int tt = 0; tt < nt - 2; tt += 2) {
;     G_LDB(B0, 0, 0); G_SCHED; G_LDA(At, 0, 0); G_STAGE(G_SA(1, 1), A, oa0, oa1, LDA, 128, KA(tt + 1));
;     G_WAIT_L(8); G_BAR; G_WAIT_L(0); G_MMA(0, 0, At, B0); G_BAR; G_SCHED;
;     G_LDB(B1, 0, 1); G_STAGE(G_SB(0, 0), B, ob0, ob1, LDB, 0, KB(tt + 2));
;     G_BAR; G_WAIT_L(0); G_MMA(0, 1, At, B1); G_BAR;
;     G_LDA(At, 0, 1); G_STAGE(G_SA(0, 0), A, oa0, oa1, LDA, 0, KA(tt + 2));
;     G_BAR; G_WAIT_L(0); G_MMA(1, 0, At, B0); G_BAR; G_SCHED;
.LBB0_453:
	ds_read_b128 v[182:185], v161
	ds_read_b128 v[186:189], v161 offset:1024
	ds_read_b128 v[190:193], v161 offset:2048
	ds_read_b128 v[194:197], v161 offset:3072
	v_add_u32_e32 v162, 0xc000, v144
	v_lshl_add_u64 v[166:167], v[136:137], 0, s[20:21]
	v_readfirstlane_b32 s0, v162
	v_lshl_add_u64 v[164:165], v[166:167], 0, s[78:79]
	s_mov_b32 m0, s0
	ds_read_b128 v[198:201], v143
	ds_read_b128 v[202:205], v143 offset:1024
	ds_read_b128 v[206:209], v143 offset:2048
	ds_read_b128 v[210:213], v143 offset:3072
	ds_read_b128 v[214:217], v143 offset:4096
	ds_read_b128 v[218:221], v143 offset:5120
	ds_read_b128 v[222:225], v143 offset:6144
	ds_read_b128 v[226:229], v143 offset:7168
	global_load_lds_dwordx4 v[164:165], off
	v_add_u32_e32 v164, 0xe000, v144
	v_lshl_add_u64 v[246:247], v[134:135], 0, s[20:21]
	v_readfirstlane_b32 s0, v164
	s_mov_b32 m0, s0
	v_lshl_add_u64 v[230:231], v[246:247], 0, s[78:79]
	global_load_lds_dwordx4 v[230:231], off
	s_waitcnt lgkmcnt(8)
	s_barrier
	s_waitcnt lgkmcnt(0)
	v_mfma_f32_16x16x32_bf16 v[126:129], v[198:201], v[182:185], v[126:129]
	v_mfma_f32_16x16x32_bf16 v[122:125], v[198:201], v[190:193], v[122:125]
	v_mfma_f32_16x16x32_bf16 v[118:121], v[206:209], v[182:185], v[118:121]
	v_mfma_f32_16x16x32_bf16 v[114:117], v[206:209], v[190:193], v[114:117]
	v_mfma_f32_16x16x32_bf16 v[110:113], v[214:217], v[182:185], v[110:113]
	v_mfma_f32_16x16x32_bf16 v[106:109], v[214:217], v[190:193], v[106:109]
	v_mfma_f32_16x16x32_bf16 v[102:105], v[222:225], v[182:185], v[102:105]
	v_mfma_f32_16x16x32_bf16 v[98:101], v[222:225], v[190:193], v[98:101]
	v_mfma_f32_16x16x32_bf16 v[126:129], v[202:205], v[186:189], v[126:129]
	v_mfma_f32_16x16x32_bf16 v[122:125], v[202:205], v[194:197], v[122:125]
	v_mfma_f32_16x16x32_bf16 v[118:121], v[210:213], v[186:189], v[118:121]
	v_mfma_f32_16x16x32_bf16 v[114:117], v[210:213], v[194:197], v[114:117]
	v_mfma_f32_16x16x32_bf16 v[110:113], v[218:221], v[186:189], v[110:113]
	v_mfma_f32_16x16x32_bf16 v[106:109], v[218:221], v[194:197], v[106:109]
	v_mfma_f32_16x16x32_bf16 v[102:105], v[226:229], v[186:189], v[102:105]
	v_mfma_f32_16x16x32_bf16 v[98:101], v[226:229], v[194:197], v[98:101]
	s_barrier
	v_lshl_add_u64 v[248:249], v[140:141], 0, s[20:21]
	v_readfirstlane_b32 s0, v147
	v_lshl_add_u64 v[250:251], v[248:249], 0, s[82:83]
	s_mov_b32 m0, s0
	ds_read_b128 v[230:233], v159
	ds_read_b128 v[234:237], v159 offset:1024
	ds_read_b128 v[238:241], v159 offset:2048
	ds_read_b128 v[242:245], v159 offset:3072
	global_load_lds_dwordx4 v[250:251], off
	v_lshl_add_u64 v[250:251], v[138:139], 0, s[20:21]
	v_readfirstlane_b32 s0, v148
	s_mov_b32 m0, s0
	v_lshl_add_u64 v[252:253], v[250:251], 0, s[82:83]
	global_load_lds_dwordx4 v[252:253], off
	s_barrier
	s_waitcnt lgkmcnt(0)
	v_mfma_f32_16x16x32_bf16 v[94:97], v[198:201], v[230:233], v[94:97]
	v_mfma_f32_16x16x32_bf16 v[86:89], v[198:201], v[238:241], v[86:89]
	v_mfma_f32_16x16x32_bf16 v[70:73], v[206:209], v[230:233], v[70:73]
	v_mfma_f32_16x16x32_bf16 v[58:61], v[206:209], v[238:241], v[58:61]
	v_mfma_f32_16x16x32_bf16 v[54:57], v[214:217], v[230:233], v[54:57]
	v_mfma_f32_16x16x32_bf16 v[50:53], v[214:217], v[238:241], v[50:53]
	v_mfma_f32_16x16x32_bf16 v[46:49], v[222:225], v[230:233], v[46:49]
	v_mfma_f32_16x16x32_bf16 v[42:45], v[222:225], v[238:241], v[42:45]
	v_mfma_f32_16x16x32_bf16 v[94:97], v[202:205], v[234:237], v[94:97]
	v_mfma_f32_16x16x32_bf16 v[86:89], v[202:205], v[242:245], v[86:89]
	v_mfma_f32_16x16x32_bf16 v[70:73], v[210:213], v[234:237], v[70:73]
	v_mfma_f32_16x16x32_bf16 v[58:61], v[210:213], v[242:245], v[58:61]
	v_mfma_f32_16x16x32_bf16 v[54:57], v[218:221], v[234:237], v[54:57]
	v_mfma_f32_16x16x32_bf16 v[50:53], v[218:221], v[242:245], v[50:53]
	v_mfma_f32_16x16x32_bf16 v[46:49], v[226:229], v[234:237], v[46:49]
	v_mfma_f32_16x16x32_bf16 v[42:45], v[226:229], v[242:245], v[42:45]
	v_readfirstlane_b32 s0, v144
	v_lshl_add_u64 v[252:253], v[166:167], 0, s[82:83]
	s_mov_b32 m0, s0
	v_readfirstlane_b32 s0, v145
	s_barrier
	ds_read_b128 v[198:201], v143 offset:16384
	ds_read_b128 v[202:205], v143 offset:17408
	ds_read_b128 v[206:209], v143 offset:18432
	ds_read_b128 v[210:213], v143 offset:19456
	ds_read_b128 v[214:217], v143 offset:20480
	ds_read_b128 v[218:221], v143 offset:21504
	ds_read_b128 v[222:225], v143 offset:22528
	ds_read_b128 v[226:229], v143 offset:23552
	global_load_lds_dwordx4 v[252:253], off
	s_mov_b32 m0, s0
	v_lshl_add_u64 v[252:253], v[246:247], 0, s[82:83]
	global_load_lds_dwordx4 v[252:253], off
	s_barrier
	s_waitcnt lgkmcnt(0)
	v_mfma_f32_16x16x32_bf16 v[38:41], v[198:201], v[182:185], v[38:41]
	v_mfma_f32_16x16x32_bf16 v[34:37], v[198:201], v[190:193], v[34:37]
	v_mfma_f32_16x16x32_bf16 v[30:33], v[206:209], v[182:185], v[30:33]
	v_mfma_f32_16x16x32_bf16 v[26:29], v[206:209], v[190:193], v[26:29]
	v_mfma_f32_16x16x32_bf16 v[22:25], v[214:217], v[182:185], v[22:25]
	v_mfma_f32_16x16x32_bf16 v[18:21], v[214:217], v[190:193], v[18:21]
	v_mfma_f32_16x16x32_bf16 v[14:17], v[222:225], v[182:185], v[14:17]
	v_mfma_f32_16x16x32_bf16 v[10:13], v[222:225], v[190:193], v[10:13]
	v_mfma_f32_16x16x32_bf16 v[38:41], v[202:205], v[186:189], v[38:41]
	v_mfma_f32_16x16x32_bf16 v[34:37], v[202:205], v[194:197], v[34:37]
	v_mfma_f32_16x16x32_bf16 v[30:33], v[210:213], v[186:189], v[30:33]
	v_mfma_f32_16x16x32_bf16 v[26:29], v[210:213], v[194:197], v[26:29]
	v_mfma_f32_16x16x32_bf16 v[22:25], v[218:221], v[186:189], v[22:25]
	v_mfma_f32_16x16x32_bf16 v[18:21], v[218:221], v[194:197], v[18:21]
	v_mfma_f32_16x16x32_bf16 v[14:17], v[226:229], v[186:189], v[14:17]
	v_mfma_f32_16x16x32_bf16 v[10:13], v[226:229], v[194:197], v[10:13]
	s_barrier
; #define G_LDA(dst, b, h)                                                                                                  \
;   _Pragma("unroll") for (int m = 0; m < 4; ++m) _Pragma("unroll") for (int k = 0; k < 2; ++k)                             \
;       dst[m][k] = *(const bf16x8*)((const char*)G_SA(b, h) + ((wr * 4 + m) * 2 + k) * 1024 + rdo)
; #define G_LDB(dst, b, h)                                                                                                  \
;   _Pragma("unroll") for (int n = 0; n < 2; ++n) _Pragma("unroll") for (int k = 0; k < 2; ++k)                             \
;       dst[n][k] = *(const bf16x8*)((const char*)G_SB(b, h) + ((wc * 2 + n) * 2 + k) * 1024 + rdo)
; #define G_WAIT_V(n) asm volatile("s_waitcnt vmcnt(" #n ")" ::: "memory")
; #define G_WAIT_L(n) asm volatile("s_waitcnt lgkmcnt(" #n ")" ::: "memory")
; #define G_BAR __builtin_amdgcn_s_barrier()
; #define G_SCHED __builtin_amdgcn_sched_barrier(0)
;     ...
;     G_STAGE(G_SB(0, 1), B, ob0, ob1, LDB, 128, KB(tt + 2));
;     G_WAIT_V(6); G_BAR; G_MMA(1, 1, At, B1); G_BAR;
;     G_LDB(B0, 1, 0); G_SCHED; G_LDA(At, 1, 0); G_STAGE(G_SA(0, 1), A, oa0, oa1, LDA, 128, KA(tt + 2));
;     G_WAIT_L(8); G_BAR; G_WAIT_L(0); G_MMA(0, 0, At, B0); G_BAR; G_SCHED;
;     G_LDB(B1, 1, 1); G_STAGE(G_SB(1, 0), B, ob0, ob1, LDB, 0, KB(tt + 3));
;     G_BAR; G_WAIT_L(0); G_MMA(0, 1, At, B1); G_BAR;
;     G_LDA(At, 1, 1); G_STAGE(G_SA(1, 0), A, oa0, oa1, LDA, 0, KA(tt + 3));
	v_readfirstlane_b32 s0, v149
	v_lshl_add_u64 v[182:183], v[248:249], 0, s[86:87]
	s_mov_b32 m0, s0
	v_readfirstlane_b32 s0, v151
	global_load_lds_dwordx4 v[182:183], off
	s_mov_b32 m0, s0
	v_lshl_add_u64 v[182:183], v[250:251], 0, s[86:87]
	global_load_lds_dwordx4 v[182:183], off
	s_waitcnt vmcnt(6)
	s_barrier
	v_mfma_f32_16x16x32_bf16 v[6:9], v[198:201], v[230:233], v[6:9]
	v_mfma_f32_16x16x32_bf16 v[2:5], v[198:201], v[238:241], v[2:5]
	v_mfma_f32_16x16x32_bf16 v[62:65], v[206:209], v[230:233], v[62:65]
	v_mfma_f32_16x16x32_bf16 v[66:69], v[206:209], v[238:241], v[66:69]
	v_mfma_f32_16x16x32_bf16 v[74:77], v[214:217], v[230:233], v[74:77]
	v_mfma_f32_16x16x32_bf16 v[78:81], v[214:217], v[238:241], v[78:81]
	v_mfma_f32_16x16x32_bf16 v[82:85], v[222:225], v[230:233], v[82:85]
	v_mfma_f32_16x16x32_bf16 v[90:93], v[222:225], v[238:241], v[90:93]
	v_mfma_f32_16x16x32_bf16 v[6:9], v[202:205], v[234:237], v[6:9]
	v_mfma_f32_16x16x32_bf16 v[2:5], v[202:205], v[242:245], v[2:5]
	v_mfma_f32_16x16x32_bf16 v[62:65], v[210:213], v[234:237], v[62:65]
	v_mfma_f32_16x16x32_bf16 v[66:69], v[210:213], v[242:245], v[66:69]
	v_mfma_f32_16x16x32_bf16 v[74:77], v[218:221], v[234:237], v[74:77]
	v_mfma_f32_16x16x32_bf16 v[78:81], v[218:221], v[242:245], v[78:81]
	v_mfma_f32_16x16x32_bf16 v[82:85], v[226:229], v[234:237], v[82:85]
	v_mfma_f32_16x16x32_bf16 v[90:93], v[226:229], v[242:245], v[90:93]
	s_barrier
	ds_read_b128 v[182:185], v150
	ds_read_b128 v[186:189], v150 offset:1024
	ds_read_b128 v[190:193], v150 offset:2048
	ds_read_b128 v[194:197], v150 offset:3072
	v_readfirstlane_b32 s0, v152
	v_lshl_add_u64 v[230:231], v[166:167], 0, s[86:87]
	s_mov_b32 m0, s0
	v_readfirstlane_b32 s0, v153
	ds_read_b128 v[198:201], v143 offset:32768
	ds_read_b128 v[202:205], v143 offset:33792
	ds_read_b128 v[206:209], v143 offset:34816
	ds_read_b128 v[210:213], v143 offset:35840
	ds_read_b128 v[214:217], v143 offset:36864
	ds_read_b128 v[218:221], v143 offset:37888
	ds_read_b128 v[222:225], v143 offset:38912
	ds_read_b128 v[226:229], v143 offset:39936
	global_load_lds_dwordx4 v[230:231], off
	s_mov_b32 m0, s0
	v_lshl_add_u64 v[230:231], v[246:247], 0, s[86:87]
	global_load_lds_dwordx4 v[230:231], off
	s_waitcnt lgkmcnt(8)
	s_barrier
	s_waitcnt lgkmcnt(0)
	v_mfma_f32_16x16x32_bf16 v[126:129], v[198:201], v[182:185], v[126:129]
	v_mfma_f32_16x16x32_bf16 v[122:125], v[198:201], v[190:193], v[122:125]
	v_mfma_f32_16x16x32_bf16 v[118:121], v[206:209], v[182:185], v[118:121]
	v_mfma_f32_16x16x32_bf16 v[114:117], v[206:209], v[190:193], v[114:117]
	v_mfma_f32_16x16x32_bf16 v[110:113], v[214:217], v[182:185], v[110:113]
	v_mfma_f32_16x16x32_bf16 v[106:109], v[214:217], v[190:193], v[106:109]
	v_mfma_f32_16x16x32_bf16 v[102:105], v[222:225], v[182:185], v[102:105]
	v_mfma_f32_16x16x32_bf16 v[98:101], v[222:225], v[190:193], v[98:101]
	v_mfma_f32_16x16x32_bf16 v[126:129], v[202:205], v[186:189], v[126:129]
	v_mfma_f32_16x16x32_bf16 v[122:125], v[202:205], v[194:197], v[122:125]
	v_mfma_f32_16x16x32_bf16 v[118:121], v[210:213], v[186:189], v[118:121]
	v_mfma_f32_16x16x32_bf16 v[114:117], v[210:213], v[194:197], v[114:117]
	v_mfma_f32_16x16x32_bf16 v[110:113], v[218:221], v[186:189], v[110:113]
	v_mfma_f32_16x16x32_bf16 v[106:109], v[218:221], v[194:197], v[106:109]
	v_mfma_f32_16x16x32_bf16 v[102:105], v[226:229], v[186:189], v[102:105]
	v_mfma_f32_16x16x32_bf16 v[98:101], v[226:229], v[194:197], v[98:101]
	s_barrier
	v_readfirstlane_b32 s0, v154
	v_lshl_add_u64 v[252:253], v[248:249], 0, s[90:91]
	s_mov_b32 m0, s0
	v_readfirstlane_b32 s0, v155
	ds_read_b128 v[230:233], v146
	ds_read_b128 v[234:237], v146 offset:1024
	ds_read_b128 v[238:241], v146 offset:2048
	ds_read_b128 v[242:245], v146 offset:3072
	global_load_lds_dwordx4 v[252:253], off
	s_mov_b32 m0, s0
	v_lshl_add_u64 v[252:253], v[250:251], 0, s[90:91]
	global_load_lds_dwordx4 v[252:253], off
	s_barrier
	s_waitcnt lgkmcnt(0)
	v_mfma_f32_16x16x32_bf16 v[94:97], v[198:201], v[230:233], v[94:97]
	v_mfma_f32_16x16x32_bf16 v[86:89], v[198:201], v[238:241], v[86:89]
	v_mfma_f32_16x16x32_bf16 v[70:73], v[206:209], v[230:233], v[70:73]
	v_mfma_f32_16x16x32_bf16 v[58:61], v[206:209], v[238:241], v[58:61]
	v_mfma_f32_16x16x32_bf16 v[54:57], v[214:217], v[230:233], v[54:57]
	v_mfma_f32_16x16x32_bf16 v[50:53], v[214:217], v[238:241], v[50:53]
	v_mfma_f32_16x16x32_bf16 v[46:49], v[222:225], v[230:233], v[46:49]
	v_mfma_f32_16x16x32_bf16 v[42:45], v[222:225], v[238:241], v[42:45]
	v_mfma_f32_16x16x32_bf16 v[94:97], v[202:205], v[234:237], v[94:97]
	v_mfma_f32_16x16x32_bf16 v[86:89], v[202:205], v[242:245], v[86:89]
	v_mfma_f32_16x16x32_bf16 v[70:73], v[210:213], v[234:237], v[70:73]
	v_mfma_f32_16x16x32_bf16 v[58:61], v[210:213], v[242:245], v[58:61]
	v_mfma_f32_16x16x32_bf16 v[54:57], v[218:221], v[234:237], v[54:57]
	v_mfma_f32_16x16x32_bf16 v[50:53], v[218:221], v[242:245], v[50:53]
	v_mfma_f32_16x16x32_bf16 v[46:49], v[226:229], v[234:237], v[46:49]
	v_mfma_f32_16x16x32_bf16 v[42:45], v[226:229], v[242:245], v[42:45]
	v_readfirstlane_b32 s0, v156
	v_lshl_add_u64 v[166:167], v[166:167], 0, s[90:91]
	s_mov_b32 m0, s0
	v_readfirstlane_b32 s0, v157
	s_barrier
	ds_read_b128 v[198:201], v143 offset:49152
	ds_read_b128 v[202:205], v143 offset:50176
	ds_read_b128 v[206:209], v143 offset:51200
	ds_read_b128 v[210:213], v143 offset:52224
	ds_read_b128 v[214:217], v143 offset:53248
	ds_read_b128 v[218:221], v143 offset:54272
	ds_read_b128 v[222:225], v143 offset:55296
	ds_read_b128 v[226:229], v143 offset:56320
	global_load_lds_dwordx4 v[166:167], off
	s_mov_b32 m0, s0
	v_lshl_add_u64 v[166:167], v[246:247], 0, s[90:91]
	global_load_lds_dwordx4 v[166:167], off
	s_barrier
; #define G_LDA(dst, b, h)                                                                                                  \
;   _Pragma("unroll") for (int m = 0; m < 4; ++m) _Pragma("unroll") for (int k = 0; k < 2; ++k)                             \
;       dst[m][k] = *(const bf16x8*)((const char*)G_SA(b, h) + ((wr * 4 + m) * 2 + k) * 1024 + rdo)
; #define G_LDB(dst, b, h)                                                                                                  \
;   _Pragma("unroll") for (int n = 0; n < 2; ++n) _Pragma("unroll") for (int k = 0; k < 2; ++k)                             \
;       dst[n][k] = *(const bf16x8*)((const char*)G_SB(b, h) + ((wc * 2 + n) * 2 + k) * 1024 + rdo)
; #define G_WAIT_V(n) asm volatile("s_waitcnt vmcnt(" #n ")" ::: "memory")
; #define G_WAIT_L(n) asm volatile("s_waitcnt lgkmcnt(" #n ")" ::: "memory")
; #define G_BAR __builtin_amdgcn_s_barrier()
; #define G_SCHED __builtin_amdgcn_sched_barrier(0)
; DI void br_flush(PREF p, f32x4 (&acc)[2][2][4][2], int slot) { br_store(p, acc, slot); zero_acc256(acc); }
;     ...
;     G_LDA(At, 1, 1); G_STAGE(G_SA(1, 0), A, oa0, oa1, LDA, 0, KA(tt + 3));
;     G_BAR; G_WAIT_L(0); G_MMA(1, 0, At, B0); G_BAR; G_SCHED;
;     G_STAGE(G_SB(1, 1), B, ob0, ob1, LDB, 128, KB(tt + 3));
;     G_WAIT_V(6); G_BAR; G_MMA(1, 1, At, B1); G_BAR;
;     if (MODE && ((tt + 1) & 3) == 3) br_flush(p, acc, (tt + 1) >> 2);
;   }
;   {
;     G_LDB(B0, 0, 0); G_LDA(At, 0, 0); G_STAGE(G_SA(1, 1), A, oa0, oa1, LDA, 128, KA(nt - 1));
;     G_BAR; G_WAIT_L(0); G_MMA(0, 0, At, B0); G_BAR;
;     G_LDB(B1, 0, 1); G_BAR; G_WAIT_L(0); G_MMA(0, 1, At, B1); G_BAR;
;     G_LDA(At, 0, 1); G_WAIT_V(4); G_BAR; G_WAIT_L(0); G_MMA(1, 0, At, B0); G_MMA(1, 1, At, B1); G_BAR;
	s_waitcnt lgkmcnt(0)
	v_mfma_f32_16x16x32_bf16 v[38:41], v[198:201], v[182:185], v[38:41]
	v_mfma_f32_16x16x32_bf16 v[34:37], v[198:201], v[190:193], v[34:37]
	v_mfma_f32_16x16x32_bf16 v[30:33], v[206:209], v[182:185], v[30:33]
	v_mfma_f32_16x16x32_bf16 v[26:29], v[206:209], v[190:193], v[26:29]
	v_mfma_f32_16x16x32_bf16 v[22:25], v[214:217], v[182:185], v[22:25]
	v_mfma_f32_16x16x32_bf16 v[18:21], v[214:217], v[190:193], v[18:21]
	v_mfma_f32_16x16x32_bf16 v[14:17], v[222:225], v[182:185], v[14:17]
	v_mfma_f32_16x16x32_bf16 v[10:13], v[222:225], v[190:193], v[10:13]
	v_mfma_f32_16x16x32_bf16 v[38:41], v[202:205], v[186:189], v[38:41]
	v_mfma_f32_16x16x32_bf16 v[34:37], v[202:205], v[194:197], v[34:37]
	v_mfma_f32_16x16x32_bf16 v[30:33], v[210:213], v[186:189], v[30:33]
	v_mfma_f32_16x16x32_bf16 v[26:29], v[210:213], v[194:197], v[26:29]
	v_mfma_f32_16x16x32_bf16 v[22:25], v[218:221], v[186:189], v[22:25]
	v_mfma_f32_16x16x32_bf16 v[18:21], v[218:221], v[194:197], v[18:21]
	v_mfma_f32_16x16x32_bf16 v[14:17], v[226:229], v[186:189], v[14:17]
	v_mfma_f32_16x16x32_bf16 v[10:13], v[226:229], v[194:197], v[10:13]
	s_barrier
	v_readfirstlane_b32 s0, v158
	v_lshl_add_u64 v[166:167], v[248:249], 0, s[6:7]
	s_mov_b32 m0, s0
	v_readfirstlane_b32 s0, v160
	global_load_lds_dwordx4 v[166:167], off
	s_mov_b32 m0, s0
	v_lshl_add_u64 v[166:167], v[250:251], 0, s[6:7]
	global_load_lds_dwordx4 v[166:167], off
	s_waitcnt vmcnt(6)
	s_barrier
	v_mfma_f32_16x16x32_bf16 v[6:9], v[198:201], v[230:233], v[6:9]
	v_mfma_f32_16x16x32_bf16 v[2:5], v[198:201], v[238:241], v[2:5]
	v_mfma_f32_16x16x32_bf16 v[62:65], v[206:209], v[230:233], v[62:65]
	v_mfma_f32_16x16x32_bf16 v[66:69], v[206:209], v[238:241], v[66:69]
	v_mfma_f32_16x16x32_bf16 v[74:77], v[214:217], v[230:233], v[74:77]
	v_mfma_f32_16x16x32_bf16 v[78:81], v[214:217], v[238:241], v[78:81]
	v_mfma_f32_16x16x32_bf16 v[82:85], v[222:225], v[230:233], v[82:85]
	v_mfma_f32_16x16x32_bf16 v[90:93], v[222:225], v[238:241], v[90:93]
	v_mfma_f32_16x16x32_bf16 v[6:9], v[202:205], v[234:237], v[6:9]
	v_mfma_f32_16x16x32_bf16 v[2:5], v[202:205], v[242:245], v[2:5]
	v_mfma_f32_16x16x32_bf16 v[62:65], v[210:213], v[234:237], v[62:65]
	v_mfma_f32_16x16x32_bf16 v[66:69], v[210:213], v[242:245], v[66:69]
	v_mfma_f32_16x16x32_bf16 v[74:77], v[218:221], v[234:237], v[74:77]
	v_mfma_f32_16x16x32_bf16 v[78:81], v[218:221], v[242:245], v[78:81]
	v_mfma_f32_16x16x32_bf16 v[82:85], v[226:229], v[234:237], v[82:85]
	v_mfma_f32_16x16x32_bf16 v[90:93], v[226:229], v[242:245], v[90:93]
	s_add_i32 s15, s15, 2
	s_add_u32 s20, s20, 0x100
	s_addc_u32 s21, s21, 0
	s_cmp_lt_u32 s15, 12
	s_barrier
	s_cbranch_scc1 .LBB0_453
	s_add_u32 s0, s18, 0x40780
	s_addc_u32 s1, s19, 0
	v_readfirstlane_b32 s15, v162
	v_lshl_add_u64 v[132:133], v[132:133], 1, s[0:1]
	s_mov_b32 m0, s15
	v_lshl_add_u64 v[130:131], v[130:131], 1, s[0:1]
	v_readfirstlane_b32 s0, v164
	ds_read_b128 v[134:137], v161
	ds_read_b128 v[138:141], v161 offset:1024
	ds_read_b128 v[152:155], v161 offset:2048
	ds_read_b128 v[182:185], v161 offset:3072
	ds_read_b128 v[186:189], v143
	ds_read_b128 v[190:193], v143 offset:1024
	ds_read_b128 v[194:197], v143 offset:2048
	ds_read_b128 v[198:201], v143 offset:3072
	ds_read_b128 v[202:205], v143 offset:4096
	ds_read_b128 v[206:209], v143 offset:5120
	ds_read_b128 v[210:213], v143 offset:6144
	ds_read_b128 v[214:217], v143 offset:7168
	global_load_lds_dwordx4 v[132:133], off
	s_mov_b32 m0, s0
	s_nop 0
	global_load_lds_dwordx4 v[130:131], off
	s_barrier
	s_waitcnt lgkmcnt(0)
	v_mfma_f32_16x16x32_bf16 v[126:129], v[186:189], v[134:137], v[126:129]
	v_mfma_f32_16x16x32_bf16 v[122:125], v[186:189], v[152:155], v[122:125]
	v_mfma_f32_16x16x32_bf16 v[110:113], v[202:205], v[134:137], v[110:113]
	v_mfma_f32_16x16x32_bf16 v[102:105], v[210:213], v[134:137], v[102:105]
	v_mfma_f32_16x16x32_bf16 v[126:129], v[190:193], v[138:141], v[126:129]
	v_mfma_f32_16x16x32_bf16 v[122:125], v[190:193], v[182:185], v[122:125]
	v_mfma_f32_16x16x32_bf16 v[118:121], v[194:197], v[134:137], v[118:121]
	v_mfma_f32_16x16x32_bf16 v[114:117], v[194:197], v[152:155], v[114:117]
	v_mfma_f32_16x16x32_bf16 v[110:113], v[206:209], v[138:141], v[110:113]
	v_mfma_f32_16x16x32_bf16 v[106:109], v[202:205], v[152:155], v[106:109]
	v_mfma_f32_16x16x32_bf16 v[102:105], v[214:217], v[138:141], v[102:105]
	v_mfma_f32_16x16x32_bf16 v[98:101], v[210:213], v[152:155], v[98:101]
	v_mfma_f32_16x16x32_bf16 v[130:133], v[198:201], v[138:141], v[118:121]
	v_mfma_f32_16x16x32_bf16 v[164:167], v[198:201], v[182:185], v[114:117]
	v_mfma_f32_16x16x32_bf16 v[218:221], v[206:209], v[182:185], v[106:109]
	v_mfma_f32_16x16x32_bf16 v[222:225], v[214:217], v[182:185], v[98:101]
	s_barrier
	s_nop 1
	s_nop 0
	ds_read_b128 v[98:101], v159
	ds_read_b128 v[106:109], v159 offset:1024
	ds_read_b128 v[114:117], v159 offset:2048
	ds_read_b128 v[118:121], v159 offset:3072
	s_barrier
	s_waitcnt lgkmcnt(0)
	v_mfma_f32_16x16x32_bf16 v[94:97], v[186:189], v[98:101], v[94:97]
	v_mfma_f32_16x16x32_bf16 v[70:73], v[194:197], v[98:101], v[70:73]
	v_mfma_f32_16x16x32_bf16 v[58:61], v[194:197], v[114:117], v[58:61]
	v_mfma_f32_16x16x32_bf16 v[54:57], v[202:205], v[98:101], v[54:57]
	v_mfma_f32_16x16x32_bf16 v[50:53], v[202:205], v[114:117], v[50:53]
	v_mfma_f32_16x16x32_bf16 v[46:49], v[210:213], v[98:101], v[46:49]
	v_mfma_f32_16x16x32_bf16 v[42:45], v[210:213], v[114:117], v[42:45]
	v_mfma_f32_16x16x32_bf16 v[94:97], v[190:193], v[106:109], v[94:97]
	v_mfma_f32_16x16x32_bf16 v[86:89], v[186:189], v[114:117], v[86:89]
	v_mfma_f32_16x16x32_bf16 v[70:73], v[198:201], v[106:109], v[70:73]
	v_mfma_f32_16x16x32_bf16 v[58:61], v[198:201], v[118:121], v[58:61]
	v_mfma_f32_16x16x32_bf16 v[54:57], v[206:209], v[106:109], v[54:57]
	v_mfma_f32_16x16x32_bf16 v[50:53], v[206:209], v[118:121], v[50:53]
	v_mfma_f32_16x16x32_bf16 v[46:49], v[214:217], v[106:109], v[46:49]
	v_mfma_f32_16x16x32_bf16 v[42:45], v[214:217], v[118:121], v[42:45]
	v_mfma_f32_16x16x32_bf16 v[156:159], v[190:193], v[118:121], v[86:89]
	s_barrier
; #define G_LDA(dst, b, h)                                                                                                  \
;   _Pragma("unroll") for (int m = 0; m < 4; ++m) _Pragma("unroll") for (int k = 0; k < 2; ++k)                             \
;       dst[m][k] = *(const bf16x8*)((const char*)G_SA(b, h) + ((wr * 4 + m) * 2 + k) * 1024 + rdo)
; #define G_LDB(dst, b, h)                                                                                                  \
;   _Pragma("unroll") for (int n = 0; n < 2; ++n) _Pragma("unroll") for (int k = 0; k < 2; ++k)                             \
;       dst[n][k] = *(const bf16x8*)((const char*)G_SB(b, h) + ((wc * 2 + n) * 2 + k) * 1024 + rdo)
; #define G_WAIT_V(n) asm volatile("s_waitcnt vmcnt(" #n ")" ::: "memory")
; #define G_WAIT_L(n) asm volatile("s_waitcnt lgkmcnt(" #n ")" ::: "memory")
; #define G_BAR __builtin_amdgcn_s_barrier()
;     ...
;     G_LDA(At, 0, 1); G_WAIT_V(4); G_BAR; G_WAIT_L(0); G_MMA(1, 0, At, B0); G_MMA(1, 1, At, B1); G_BAR;
;   }
;   {
;     G_LDB(B0, 1, 0); G_LDA(At, 1, 0); G_WAIT_V(2); G_BAR; G_WAIT_L(0); G_MMA(0, 0, At, B0); G_BAR;
	s_nop 0
	ds_read_b128 v[86:89], v143 offset:16384
	ds_read_b128 v[186:189], v143 offset:17408
	ds_read_b128 v[190:193], v143 offset:18432
	ds_read_b128 v[194:197], v143 offset:19456
	ds_read_b128 v[198:201], v143 offset:20480
	ds_read_b128 v[202:205], v143 offset:21504
	ds_read_b128 v[206:209], v143 offset:22528
	ds_read_b128 v[210:213], v143 offset:23552
	s_waitcnt vmcnt(4)
	s_barrier
	s_waitcnt lgkmcnt(0)
	v_mfma_f32_16x16x32_bf16 v[38:41], v[86:89], v[134:137], v[38:41]
	v_mfma_f32_16x16x32_bf16 v[34:37], v[86:89], v[152:155], v[34:37]
	v_mfma_f32_16x16x32_bf16 v[30:33], v[190:193], v[134:137], v[30:33]
	v_mfma_f32_16x16x32_bf16 v[26:29], v[190:193], v[152:155], v[26:29]
	v_mfma_f32_16x16x32_bf16 v[22:25], v[198:201], v[134:137], v[22:25]
	v_mfma_f32_16x16x32_bf16 v[18:21], v[198:201], v[152:155], v[18:21]
	v_mfma_f32_16x16x32_bf16 v[14:17], v[206:209], v[134:137], v[14:17]
	v_mfma_f32_16x16x32_bf16 v[10:13], v[206:209], v[152:155], v[10:13]
	v_mfma_f32_16x16x32_bf16 v[38:41], v[186:189], v[138:141], v[38:41]
	v_mfma_f32_16x16x32_bf16 v[34:37], v[186:189], v[182:185], v[34:37]
	v_mfma_f32_16x16x32_bf16 v[30:33], v[194:197], v[138:141], v[30:33]
	v_mfma_f32_16x16x32_bf16 v[26:29], v[194:197], v[182:185], v[26:29]
	v_mfma_f32_16x16x32_bf16 v[22:25], v[202:205], v[138:141], v[22:25]
	v_mfma_f32_16x16x32_bf16 v[18:21], v[202:205], v[182:185], v[18:21]
	v_mfma_f32_16x16x32_bf16 v[14:17], v[210:213], v[138:141], v[14:17]
	v_mfma_f32_16x16x32_bf16 v[10:13], v[210:213], v[182:185], v[10:13]
	v_mfma_f32_16x16x32_bf16 v[62:65], v[190:193], v[98:101], v[62:65]
	v_mfma_f32_16x16x32_bf16 v[134:137], v[194:197], v[106:109], v[62:65]
	v_mfma_f32_16x16x32_bf16 v[62:65], v[190:193], v[114:117], v[66:69]
	v_mfma_f32_16x16x32_bf16 v[138:141], v[194:197], v[118:121], v[62:65]
	v_mfma_f32_16x16x32_bf16 v[62:65], v[198:201], v[98:101], v[74:77]
	v_mfma_f32_16x16x32_bf16 v[152:155], v[202:205], v[106:109], v[62:65]
	v_mfma_f32_16x16x32_bf16 v[62:65], v[198:201], v[114:117], v[78:81]
	v_mfma_f32_16x16x32_bf16 v[6:9], v[86:89], v[98:101], v[6:9]
	v_mfma_f32_16x16x32_bf16 v[2:5], v[86:89], v[114:117], v[2:5]
	v_mfma_f32_16x16x32_bf16 v[182:185], v[202:205], v[118:121], v[62:65]
	v_mfma_f32_16x16x32_bf16 v[62:65], v[206:209], v[98:101], v[82:85]
	v_mfma_f32_16x16x32_bf16 v[6:9], v[186:189], v[106:109], v[6:9]
	v_mfma_f32_16x16x32_bf16 v[2:5], v[186:189], v[118:121], v[2:5]
	v_mfma_f32_16x16x32_bf16 v[186:189], v[210:213], v[106:109], v[62:65]
	v_mfma_f32_16x16x32_bf16 v[62:65], v[206:209], v[114:117], v[90:93]
	v_mfma_f32_16x16x32_bf16 v[190:193], v[210:213], v[118:121], v[62:65]
	s_barrier
	ds_read_b128 v[194:197], v150
	ds_read_b128 v[198:201], v150 offset:1024
	ds_read_b128 v[202:205], v150 offset:2048
	ds_read_b128 v[148:151], v150 offset:3072
	s_nop 0
	s_nop 0
	ds_read_b128 v[62:65], v143 offset:32768
	ds_read_b128 v[66:69], v143 offset:33792
	ds_read_b128 v[74:77], v143 offset:34816
	ds_read_b128 v[78:81], v143 offset:35840
	ds_read_b128 v[206:209], v143 offset:36864
	ds_read_b128 v[210:213], v143 offset:37888
	ds_read_b128 v[214:217], v143 offset:38912
	ds_read_b128 v[226:229], v143 offset:39936
	s_waitcnt vmcnt(2)
	s_barrier
	s_waitcnt lgkmcnt(0)
	v_mfma_f32_16x16x32_bf16 v[82:85], v[62:65], v[194:197], v[126:129]
	v_mfma_f32_16x16x32_bf16 v[118:121], v[66:69], v[198:201], v[82:85]
	v_mfma_f32_16x16x32_bf16 v[82:85], v[62:65], v[202:205], v[122:125]
	v_mfma_f32_16x16x32_bf16 v[126:129], v[66:69], v[148:151], v[82:85]
	v_mfma_f32_16x16x32_bf16 v[82:85], v[74:77], v[194:197], v[130:133]
	v_mfma_f32_16x16x32_bf16 v[114:117], v[78:81], v[198:201], v[82:85]
	v_mfma_f32_16x16x32_bf16 v[82:85], v[74:77], v[202:205], v[164:167]
	v_mfma_f32_16x16x32_bf16 v[122:125], v[78:81], v[148:151], v[82:85]
	v_mfma_f32_16x16x32_bf16 v[82:85], v[206:209], v[194:197], v[110:113]
	v_mfma_f32_16x16x32_bf16 v[106:109], v[210:213], v[198:201], v[82:85]
	v_mfma_f32_16x16x32_bf16 v[82:85], v[206:209], v[202:205], v[218:221]
	v_mfma_f32_16x16x32_bf16 v[110:113], v[210:213], v[148:151], v[82:85]
	v_mfma_f32_16x16x32_bf16 v[82:85], v[214:217], v[194:197], v[102:105]
	v_mfma_f32_16x16x32_bf16 v[98:101], v[226:229], v[198:201], v[82:85]
	v_mfma_f32_16x16x32_bf16 v[82:85], v[214:217], v[202:205], v[222:225]
	v_mfma_f32_16x16x32_bf16 v[102:105], v[226:229], v[148:151], v[82:85]
	s_barrier
; #define G_LDA(dst, b, h)                                                                                                  \
;   _Pragma("unroll") for (int m = 0; m < 4; ++m) _Pragma("unroll") for (int k = 0; k < 2; ++k)                             \
;       dst[m][k] = *(const bf16x8*)((const char*)G_SA(b, h) + ((wr * 4 + m) * 2 + k) * 1024 + rdo)
; #define G_LDB(dst, b, h)                                                                                                  \
;   _Pragma("unroll") for (int n = 0; n < 2; ++n) _Pragma("unroll") for (int k = 0; k < 2; ++k)                             \
;       dst[n][k] = *(const bf16x8*)((const char*)G_SB(b, h) + ((wc * 2 + n) * 2 + k) * 1024 + rdo)
; #define G_WAIT_V(n) asm volatile("s_waitcnt vmcnt(" #n ")" ::: "memory")
; #define G_WAIT_L(n) asm volatile("s_waitcnt lgkmcnt(" #n ")" ::: "memory")
; #define G_BAR __builtin_amdgcn_s_barrier()
;     ...
;     G_LDB(B1, 1, 1); G_WAIT_V(0); G_BAR; G_WAIT_L(0); G_MMA(0, 1, At, B1); G_BAR;
;     G_LDA(At, 1, 1); G_BAR; G_WAIT_L(0); G_MMA(1, 0, At, B0); G_MMA(1, 1, At, B1); G_BAR;
;   }
;   if (wr == 0) G_BAR;
	ds_read_b128 v[130:133], v146
	ds_read_b128 v[164:167], v146 offset:1024
	ds_read_b128 v[218:221], v146 offset:2048
	ds_read_b128 v[144:147], v146 offset:3072
	s_waitcnt vmcnt(0)
	s_barrier
	s_waitcnt lgkmcnt(0)
	v_mfma_f32_16x16x32_bf16 v[82:85], v[62:65], v[130:133], v[94:97]
	v_mfma_f32_16x16x32_bf16 v[62:65], v[62:65], v[218:221], v[156:159]
	v_mfma_f32_16x16x32_bf16 v[94:97], v[66:69], v[144:147], v[62:65]
	v_mfma_f32_16x16x32_bf16 v[62:65], v[74:77], v[130:133], v[70:73]
	v_mfma_f32_16x16x32_bf16 v[58:61], v[74:77], v[218:221], v[58:61]
	v_mfma_f32_16x16x32_bf16 v[54:57], v[206:209], v[130:133], v[54:57]
	v_mfma_f32_16x16x32_bf16 v[50:53], v[206:209], v[218:221], v[50:53]
	v_mfma_f32_16x16x32_bf16 v[46:49], v[214:217], v[130:133], v[46:49]
	v_mfma_f32_16x16x32_bf16 v[42:45], v[214:217], v[218:221], v[42:45]
	v_mfma_f32_16x16x32_bf16 v[86:89], v[66:69], v[164:167], v[82:85]
	v_mfma_f32_16x16x32_bf16 v[82:85], v[78:81], v[164:167], v[62:65]
	v_mfma_f32_16x16x32_bf16 v[90:93], v[78:81], v[144:147], v[58:61]
	v_mfma_f32_16x16x32_bf16 v[74:77], v[210:213], v[164:167], v[54:57]
	v_mfma_f32_16x16x32_bf16 v[78:81], v[210:213], v[144:147], v[50:53]
	v_mfma_f32_16x16x32_bf16 v[66:69], v[226:229], v[164:167], v[46:49]
	v_mfma_f32_16x16x32_bf16 v[70:73], v[226:229], v[144:147], v[42:45]
	s_barrier
	ds_read_b128 v[156:159], v143 offset:49152
	ds_read_b128 v[206:209], v143 offset:50176
	ds_read_b128 v[210:213], v143 offset:51200
	ds_read_b128 v[214:217], v143 offset:52224
	ds_read_b128 v[222:225], v143 offset:53248
	ds_read_b128 v[226:229], v143 offset:54272
	ds_read_b128 v[230:233], v143 offset:55296
	ds_read_b128 v[234:237], v143 offset:56320
	s_barrier
	s_waitcnt lgkmcnt(0)
	v_mfma_f32_16x16x32_bf16 v[38:41], v[156:159], v[194:197], v[38:41]
	v_mfma_f32_16x16x32_bf16 v[34:37], v[156:159], v[202:205], v[34:37]
	v_mfma_f32_16x16x32_bf16 v[30:33], v[210:213], v[194:197], v[30:33]
	v_mfma_f32_16x16x32_bf16 v[26:29], v[210:213], v[202:205], v[26:29]
	v_mfma_f32_16x16x32_bf16 v[22:25], v[222:225], v[194:197], v[22:25]
	v_mfma_f32_16x16x32_bf16 v[18:21], v[222:225], v[202:205], v[18:21]
	v_mfma_f32_16x16x32_bf16 v[14:17], v[230:233], v[194:197], v[14:17]
	v_mfma_f32_16x16x32_bf16 v[10:13], v[230:233], v[202:205], v[10:13]
	v_mfma_f32_16x16x32_bf16 v[54:57], v[206:209], v[198:201], v[38:41]
	v_mfma_f32_16x16x32_bf16 v[62:65], v[206:209], v[148:151], v[34:37]
	v_mfma_f32_16x16x32_bf16 v[50:53], v[214:217], v[198:201], v[30:33]
	v_mfma_f32_16x16x32_bf16 v[58:61], v[214:217], v[148:151], v[26:29]
	v_mfma_f32_16x16x32_bf16 v[42:45], v[226:229], v[198:201], v[22:25]
	v_mfma_f32_16x16x32_bf16 v[46:49], v[226:229], v[148:151], v[18:21]
	v_mfma_f32_16x16x32_bf16 v[34:37], v[234:237], v[198:201], v[14:17]
	v_mfma_f32_16x16x32_bf16 v[38:41], v[234:237], v[148:151], v[10:13]
	v_mfma_f32_16x16x32_bf16 v[2:5], v[156:159], v[218:221], v[2:5]
	v_mfma_f32_16x16x32_bf16 v[30:33], v[206:209], v[144:147], v[2:5]
	v_mfma_f32_16x16x32_bf16 v[2:5], v[210:213], v[130:133], v[134:137]
	v_mfma_f32_16x16x32_bf16 v[18:21], v[214:217], v[164:167], v[2:5]
	v_mfma_f32_16x16x32_bf16 v[2:5], v[210:213], v[218:221], v[138:141]
	v_mfma_f32_16x16x32_bf16 v[26:29], v[214:217], v[144:147], v[2:5]
	v_mfma_f32_16x16x32_bf16 v[2:5], v[222:225], v[130:133], v[152:155]
	v_mfma_f32_16x16x32_bf16 v[6:9], v[156:159], v[130:133], v[6:9]
	v_mfma_f32_16x16x32_bf16 v[10:13], v[226:229], v[164:167], v[2:5]
	v_mfma_f32_16x16x32_bf16 v[2:5], v[222:225], v[218:221], v[182:185]
	v_mfma_f32_16x16x32_bf16 v[22:25], v[206:209], v[164:167], v[6:9]
	v_mfma_f32_16x16x32_bf16 v[14:17], v[226:229], v[144:147], v[2:5]
	v_mfma_f32_16x16x32_bf16 v[2:5], v[230:233], v[130:133], v[186:189]
	v_mfma_f32_16x16x32_bf16 v[6:9], v[230:233], v[218:221], v[190:193]
	v_mfma_f32_16x16x32_bf16 v[2:5], v[234:237], v[164:167], v[2:5]
	v_mfma_f32_16x16x32_bf16 v[6:9], v[234:237], v[144:147], v[6:9]
	v_cmp_gt_u32_e32 vcc, s67, v0
	s_barrier
	s_and_saveexec_b64 s[18:19], vcc
	s_cbranch_execz .LBB0_456
	s_barrier
